# stack5 + static s_setprio 1 for waves 4-7 in the prompt attention loop + back-to-back s_setprio 0/1 pairs deleted from the GEMM K-loops
# speedup vs baseline: 1.0088x; 1.0088x over previous
; #define PG8_STAGE(bufoff, gbase, voff) do { _Pragma("unroll") for (int _i = 0; _i < 2; ++_i) \
;         __builtin_amdgcn_global_load_lds((const unsigned*)((const char*)(gbase) + (voff)[_i]), (PG8_LAS unsigned*)(lds + (bufoff) + ldsw + _i * 8192), 16, 0, 0); } while (0)
; #define PG8_LDA(dst, b, h) do { _Pragma("unroll") for (int m = 0; m < 4; ++m) _Pragma("unroll") for (int k = 0; k < 2; ++k) dst[m][k] = *(const PG8_LAS bf16x8*)(lds + PG8_SA(b, h) + aoff + m * 2048 + k * 1024); } while (0)
; #define PG8_LDB(dst, b, h) do { _Pragma("unroll") for (int n = 0; n < 2; ++n) _Pragma("unroll") for (int k = 0; k < 2; ++k) dst[n][k] = *(const PG8_LAS bf16x8*)(lds + PG8_SB(b, h) + boff + n * 2048 + k * 1024); } while (0)
; #define PG8_MMA(ai, bj, At, Bt) do { __builtin_amdgcn_s_setprio(1); _Pragma("unroll") for (int m = 0; m < 4; ++m) _Pragma("unroll") for (int n = 0; n < 2; ++n) _Pragma("unroll") for (int k = 0; k < 2; ++k) \
;         acc[ai][bj][m][n] = __builtin_amdgcn_mfma_f32_16x16x32_bf16(Bt[n][k], At[m][k], acc[ai][bj][m][n], 0, 0, 0); __builtin_amdgcn_s_setprio(0); } while (0)
; #define PG8_WAIT_V(n) asm volatile("s_waitcnt vmcnt(" #n ")" ::: "memory")
; template <class Epi, class Sched, bool ALIGN_EPI = false, bool SP2 = false>
; __device__ __forceinline__ void gemm_phase(PG8_LAS unsigned char* lds, const Gemm g, const Sched& S, const Epi& E) {
;     ...
;             PG8_LDB(B0, 0, 0); PG8_LDB(B1, 0, 1); PG8_SCHED; PG8_LDA(At, 0, 0); PG8_STAGE(PG8_SA(1, 1), a1 + ahstep, voffA);
;             PG8_WAIT_V(8); PG8_WAIT_L(0); PG8_BAR; PG8_MMA(0, 0, At, B0); PG8_MMA(0, 1, At, B1); PG8_BAR; PG8_SCHED;
;             PG8_LDA(At, 0, 1); PG8_STAGE(PG8_SB(0, 0), b2, voffB); PG8_STAGE(PG8_SB(0, 1), b2 + hstep, voffB); PG8_STAGE(PG8_SA(0, 0), a2, voffA);
;             PG8_WAIT_V(8); PG8_WAIT_L(0); PG8_BAR; PG8_MMA(1, 0, At, B0); PG8_MMA(1, 1, At, B1); PG8_BAR; PG8_SCHED;
;             PG8_LDB(B0, 1, 0); PG8_LDB(B1, 1, 1); PG8_SCHED; PG8_LDA(At, 1, 0); PG8_STAGE(PG8_SA(0, 1), a2 + ahstep, voffA);
;             PG8_WAIT_V(8); PG8_WAIT_L(0); PG8_BAR; PG8_MMA(0, 0, At, B0); PG8_MMA(0, 1, At, B1); PG8_BAR; PG8_SCHED;
;             PG8_LDA(At, 1, 1); PG8_STAGE(PG8_SB(1, 0), b3, voffB); PG8_STAGE(PG8_SB(1, 1), b3 + hstep, voffB); PG8_STAGE(PG8_SA(1, 0), a3, voffA);
;             PG8_WAIT_V(8); PG8_WAIT_L(0); PG8_BAR; PG8_MMA(1, 0, At, B0); PG8_MMA(1, 1, At, B1); PG8_BAR; PG8_SCHED;
.LBB0_206:
	ds_read_b128 v[130:133], v193
	ds_read_b128 v[134:137], v193 offset:1024
	ds_read_b128 v[138:141], v193 offset:2048
	ds_read_b128 v[142:145], v193 offset:3072
	ds_read_b128 v[166:169], v194
	ds_read_b128 v[170:173], v194 offset:1024
	ds_read_b128 v[174:177], v194 offset:2048
	ds_read_b128 v[178:181], v194 offset:3072
	s_add_u32 s4, s0, 0xfffc0080
	s_addc_u32 s5, s1, -1
	s_cmp_eq_u32 s85, 12
	s_cselect_b32 s29, s49, s5
	s_cselect_b32 s28, s60, s4
	s_cselect_b32 s5, s47, s84
	s_cselect_b32 s4, s65, s73
	v_lshl_add_u64 v[186:187], s[0:1], 0, v[158:159]
	s_add_i32 m0, s45, 0xc000
	ds_read_b128 v[182:185], v195
	ds_read_b128 v[202:205], v195 offset:1024
	ds_read_b128 v[206:209], v195 offset:2048
	ds_read_b128 v[212:215], v195 offset:3072
	ds_read_b128 v[216:219], v195 offset:4096
	ds_read_b128 v[220:223], v195 offset:5120
	ds_read_b128 v[224:227], v195 offset:6144
	ds_read_b128 v[228:231], v195 offset:7168
	global_load_lds_dwordx4 v[186:187], off
	v_lshl_add_u64 v[186:187], s[0:1], 0, v[160:161]
	s_add_i32 m0, s45, 0xe000
	s_nop 0
	global_load_lds_dwordx4 v[186:187], off
	s_waitcnt vmcnt(8)
	s_waitcnt lgkmcnt(0)
	s_barrier
	s_setprio 1
	s_waitcnt lgkmcnt(0)
	v_mfma_f32_16x16x32_bf16 v[126:129], v[130:133], v[182:185], v[126:129]
	v_mfma_f32_16x16x32_bf16 v[122:125], v[138:141], v[182:185], v[122:125]
	v_mfma_f32_16x16x32_bf16 v[118:121], v[130:133], v[206:209], v[118:121]
	v_mfma_f32_16x16x32_bf16 v[114:117], v[138:141], v[206:209], v[114:117]
	v_mfma_f32_16x16x32_bf16 v[102:105], v[130:133], v[216:219], v[102:105]
	v_mfma_f32_16x16x32_bf16 v[98:101], v[138:141], v[216:219], v[98:101]
	v_mfma_f32_16x16x32_bf16 v[86:89], v[130:133], v[224:227], v[86:89]
	v_mfma_f32_16x16x32_bf16 v[82:85], v[138:141], v[224:227], v[82:85]
	v_mfma_f32_16x16x32_bf16 v[126:129], v[134:137], v[202:205], v[126:129]
	v_mfma_f32_16x16x32_bf16 v[122:125], v[142:145], v[202:205], v[122:125]
	v_mfma_f32_16x16x32_bf16 v[118:121], v[134:137], v[212:215], v[118:121]
	v_mfma_f32_16x16x32_bf16 v[114:117], v[142:145], v[212:215], v[114:117]
	v_mfma_f32_16x16x32_bf16 v[102:105], v[134:137], v[220:223], v[102:105]
	v_mfma_f32_16x16x32_bf16 v[98:101], v[142:145], v[220:223], v[98:101]
	v_mfma_f32_16x16x32_bf16 v[86:89], v[134:137], v[228:231], v[86:89]
	v_mfma_f32_16x16x32_bf16 v[82:85], v[142:145], v[228:231], v[82:85]
	v_mfma_f32_16x16x32_bf16 v[110:113], v[166:169], v[182:185], v[110:113]
	v_mfma_f32_16x16x32_bf16 v[106:109], v[174:177], v[182:185], v[106:109]
	v_mfma_f32_16x16x32_bf16 v[94:97], v[166:169], v[206:209], v[94:97]
	v_mfma_f32_16x16x32_bf16 v[90:93], v[174:177], v[206:209], v[90:93]
	v_mfma_f32_16x16x32_bf16 v[78:81], v[166:169], v[216:219], v[78:81]
	v_mfma_f32_16x16x32_bf16 v[74:77], v[174:177], v[216:219], v[74:77]
	v_mfma_f32_16x16x32_bf16 v[70:73], v[166:169], v[224:227], v[70:73]
	v_mfma_f32_16x16x32_bf16 v[66:69], v[174:177], v[224:227], v[66:69]
	v_mfma_f32_16x16x32_bf16 v[110:113], v[170:173], v[202:205], v[110:113]
	v_mfma_f32_16x16x32_bf16 v[106:109], v[178:181], v[202:205], v[106:109]
	v_mfma_f32_16x16x32_bf16 v[94:97], v[170:173], v[212:215], v[94:97]
	v_mfma_f32_16x16x32_bf16 v[90:93], v[178:181], v[212:215], v[90:93]
	v_mfma_f32_16x16x32_bf16 v[78:81], v[170:173], v[220:223], v[78:81]
	v_mfma_f32_16x16x32_bf16 v[74:77], v[178:181], v[220:223], v[74:77]
	v_mfma_f32_16x16x32_bf16 v[70:73], v[170:173], v[228:231], v[70:73]
	v_mfma_f32_16x16x32_bf16 v[66:69], v[178:181], v[228:231], v[66:69]
	s_setprio 0
	s_barrier
	s_add_i32 s68, s61, s35
	v_lshl_add_u64 v[186:187], s[4:5], 0, v[148:149]
	s_mov_b32 m0, s68
	ds_read_b128 v[182:185], v195 offset:16384
	ds_read_b128 v[202:205], v195 offset:17408
	ds_read_b128 v[206:209], v195 offset:18432
	ds_read_b128 v[212:215], v195 offset:19456
	ds_read_b128 v[216:219], v195 offset:20480
	ds_read_b128 v[220:223], v195 offset:21504
	ds_read_b128 v[224:227], v195 offset:22528
	ds_read_b128 v[228:231], v195 offset:23552
	global_load_lds_dwordx4 v[186:187], off
	s_add_i32 m0, s68, 0x2000
	s_add_u32 s68, s4, 0x40000
	v_lshl_add_u64 v[210:211], s[4:5], 0, v[152:153]
	s_addc_u32 s69, s5, 0
	s_add_i32 s70, s62, s35
	global_load_lds_dwordx4 v[210:211], off
	v_lshl_add_u64 v[232:233], s[68:69], 0, v[148:149]
	s_mov_b32 m0, s70
	v_lshl_add_u64 v[234:235], s[28:29], 0, v[150:151]
	global_load_lds_dwordx4 v[232:233], off
	v_lshl_add_u64 v[232:233], s[68:69], 0, v[152:153]
	s_add_i32 m0, s70, 0x2000
	s_nop 0
	global_load_lds_dwordx4 v[232:233], off
	v_lshl_add_u64 v[232:233], s[28:29], 0, v[146:147]
	s_mov_b32 m0, s45
	s_nop 0
	global_load_lds_dwordx4 v[232:233], off
	s_mov_b32 m0, s52
	s_nop 0
	global_load_lds_dwordx4 v[234:235], off
	s_waitcnt vmcnt(8)
	s_waitcnt lgkmcnt(0)
	s_barrier
; #define PG8_STAGE(bufoff, gbase, voff) do { _Pragma("unroll") for (int _i = 0; _i < 2; ++_i) \
;         __builtin_amdgcn_global_load_lds((const unsigned*)((const char*)(gbase) + (voff)[_i]), (PG8_LAS unsigned*)(lds + (bufoff) + ldsw + _i * 8192), 16, 0, 0); } while (0)
; #define PG8_LDA(dst, b, h) do { _Pragma("unroll") for (int m = 0; m < 4; ++m) _Pragma("unroll") for (int k = 0; k < 2; ++k) dst[m][k] = *(const PG8_LAS bf16x8*)(lds + PG8_SA(b, h) + aoff + m * 2048 + k * 1024); } while (0)
; #define PG8_LDB(dst, b, h) do { _Pragma("unroll") for (int n = 0; n < 2; ++n) _Pragma("unroll") for (int k = 0; k < 2; ++k) dst[n][k] = *(const PG8_LAS bf16x8*)(lds + PG8_SB(b, h) + boff + n * 2048 + k * 1024); } while (0)
; #define PG8_MMA(ai, bj, At, Bt) do { __builtin_amdgcn_s_setprio(1); _Pragma("unroll") for (int m = 0; m < 4; ++m) _Pragma("unroll") for (int n = 0; n < 2; ++n) _Pragma("unroll") for (int k = 0; k < 2; ++k) \
;         acc[ai][bj][m][n] = __builtin_amdgcn_mfma_f32_16x16x32_bf16(Bt[n][k], At[m][k], acc[ai][bj][m][n], 0, 0, 0); __builtin_amdgcn_s_setprio(0); } while (0)
; #define PG8_WAIT_V(n) asm volatile("s_waitcnt vmcnt(" #n ")" ::: "memory")
; template <class Epi, class Sched, bool ALIGN_EPI = false, bool SP2 = false>
; __device__ __forceinline__ void gemm_phase(PG8_LAS unsigned char* lds, const Gemm g, const Sched& S, const Epi& E) {
;     ...
;             PG8_LDB(B0, 0, 0); PG8_LDB(B1, 0, 1); PG8_SCHED; PG8_LDA(At, 0, 0); PG8_STAGE(PG8_SA(1, 1), a1 + ahstep, voffA);
;             PG8_WAIT_V(8); PG8_WAIT_L(0); PG8_BAR; PG8_MMA(0, 0, At, B0); PG8_MMA(0, 1, At, B1); PG8_BAR; PG8_SCHED;
;             PG8_LDA(At, 0, 1); PG8_STAGE(PG8_SB(0, 0), b2, voffB); PG8_STAGE(PG8_SB(0, 1), b2 + hstep, voffB); PG8_STAGE(PG8_SA(0, 0), a2, voffA);
;             PG8_WAIT_V(8); PG8_WAIT_L(0); PG8_BAR; PG8_MMA(1, 0, At, B0); PG8_MMA(1, 1, At, B1); PG8_BAR; PG8_SCHED;
;             PG8_LDB(B0, 1, 0); PG8_LDB(B1, 1, 1); PG8_SCHED; PG8_LDA(At, 1, 0); PG8_STAGE(PG8_SA(0, 1), a2 + ahstep, voffA);
;             PG8_WAIT_V(8); PG8_WAIT_L(0); PG8_BAR; PG8_MMA(0, 0, At, B0); PG8_MMA(0, 1, At, B1); PG8_BAR; PG8_SCHED;
;             PG8_LDA(At, 1, 1); PG8_STAGE(PG8_SB(1, 0), b3, voffB); PG8_STAGE(PG8_SB(1, 1), b3 + hstep, voffB); PG8_STAGE(PG8_SA(1, 0), a3, voffA);
;             PG8_WAIT_V(8); PG8_WAIT_L(0); PG8_BAR; PG8_MMA(1, 0, At, B0); PG8_MMA(1, 1, At, B1); PG8_BAR; PG8_SCHED;
	s_setprio 1
	s_waitcnt lgkmcnt(0)
	v_mfma_f32_16x16x32_bf16 v[62:65], v[130:133], v[182:185], v[62:65]
	v_mfma_f32_16x16x32_bf16 v[58:61], v[138:141], v[182:185], v[58:61]
	v_mfma_f32_16x16x32_bf16 v[54:57], v[130:133], v[206:209], v[54:57]
	v_mfma_f32_16x16x32_bf16 v[50:53], v[138:141], v[206:209], v[50:53]
	v_mfma_f32_16x16x32_bf16 v[38:41], v[130:133], v[216:219], v[38:41]
	v_mfma_f32_16x16x32_bf16 v[34:37], v[138:141], v[216:219], v[34:37]
	v_mfma_f32_16x16x32_bf16 v[22:25], v[130:133], v[224:227], v[22:25]
	v_mfma_f32_16x16x32_bf16 v[18:21], v[138:141], v[224:227], v[18:21]
	v_mfma_f32_16x16x32_bf16 v[62:65], v[134:137], v[202:205], v[62:65]
	v_mfma_f32_16x16x32_bf16 v[58:61], v[142:145], v[202:205], v[58:61]
	v_mfma_f32_16x16x32_bf16 v[54:57], v[134:137], v[212:215], v[54:57]
	v_mfma_f32_16x16x32_bf16 v[50:53], v[142:145], v[212:215], v[50:53]
	v_mfma_f32_16x16x32_bf16 v[38:41], v[134:137], v[220:223], v[38:41]
	v_mfma_f32_16x16x32_bf16 v[34:37], v[142:145], v[220:223], v[34:37]
	v_mfma_f32_16x16x32_bf16 v[22:25], v[134:137], v[228:231], v[22:25]
	v_mfma_f32_16x16x32_bf16 v[18:21], v[142:145], v[228:231], v[18:21]
	v_mfma_f32_16x16x32_bf16 v[46:49], v[166:169], v[182:185], v[46:49]
	v_mfma_f32_16x16x32_bf16 v[42:45], v[174:177], v[182:185], v[42:45]
	v_mfma_f32_16x16x32_bf16 v[30:33], v[166:169], v[206:209], v[30:33]
	v_mfma_f32_16x16x32_bf16 v[26:29], v[174:177], v[206:209], v[26:29]
	v_mfma_f32_16x16x32_bf16 v[14:17], v[166:169], v[216:219], v[14:17]
	v_mfma_f32_16x16x32_bf16 v[10:13], v[174:177], v[216:219], v[10:13]
	v_mfma_f32_16x16x32_bf16 v[6:9], v[166:169], v[224:227], v[6:9]
	v_mfma_f32_16x16x32_bf16 v[2:5], v[174:177], v[224:227], v[2:5]
	v_mfma_f32_16x16x32_bf16 v[46:49], v[170:173], v[202:205], v[46:49]
	v_mfma_f32_16x16x32_bf16 v[42:45], v[178:181], v[202:205], v[42:45]
	v_mfma_f32_16x16x32_bf16 v[30:33], v[170:173], v[212:215], v[30:33]
	v_mfma_f32_16x16x32_bf16 v[26:29], v[178:181], v[212:215], v[26:29]
	v_mfma_f32_16x16x32_bf16 v[14:17], v[170:173], v[220:223], v[14:17]
	v_mfma_f32_16x16x32_bf16 v[10:13], v[178:181], v[220:223], v[10:13]
	v_mfma_f32_16x16x32_bf16 v[6:9], v[170:173], v[228:231], v[6:9]
	v_mfma_f32_16x16x32_bf16 v[2:5], v[178:181], v[228:231], v[2:5]
	s_setprio 0
	s_barrier
	s_add_i32 s68, 0, 0x18000
	s_add_i32 s69, 0, 0x1c000
	v_add_u32_e32 v142, s68, v190
	v_add_u32_e32 v154, s69, v190
	ds_read_b128 v[130:133], v142
	ds_read_b128 v[134:137], v142 offset:1024
	ds_read_b128 v[138:141], v142 offset:2048
	ds_read_b128 v[142:145], v142 offset:3072
	ds_read_b128 v[166:169], v154
	ds_read_b128 v[170:173], v154 offset:1024
	ds_read_b128 v[174:177], v154 offset:2048
	ds_read_b128 v[178:181], v154 offset:3072
	s_add_u32 s28, s28, 0x40000
	s_addc_u32 s29, s29, 0
	s_mov_b32 m0, s53
	v_lshl_add_u64 v[236:237], s[28:29], 0, v[146:147]
	ds_read_b128 v[182:185], v195 offset:32768
	ds_read_b128 v[202:205], v195 offset:33792
	ds_read_b128 v[206:209], v195 offset:34816
	ds_read_b128 v[212:215], v195 offset:35840
	ds_read_b128 v[216:219], v195 offset:36864
	ds_read_b128 v[220:223], v195 offset:37888
	ds_read_b128 v[224:227], v195 offset:38912
	ds_read_b128 v[228:231], v195 offset:39936
	global_load_lds_dwordx4 v[236:237], off
	v_lshl_add_u64 v[236:237], s[28:29], 0, v[150:151]
	s_mov_b32 m0, s54
	s_nop 0
	global_load_lds_dwordx4 v[236:237], off
	s_waitcnt vmcnt(8)
	s_waitcnt lgkmcnt(0)
	s_barrier
	s_setprio 1
	s_waitcnt lgkmcnt(0)
	v_mfma_f32_16x16x32_bf16 v[126:129], v[130:133], v[182:185], v[126:129]
	v_mfma_f32_16x16x32_bf16 v[122:125], v[138:141], v[182:185], v[122:125]
	v_mfma_f32_16x16x32_bf16 v[118:121], v[130:133], v[206:209], v[118:121]
	v_mfma_f32_16x16x32_bf16 v[114:117], v[138:141], v[206:209], v[114:117]
	v_mfma_f32_16x16x32_bf16 v[102:105], v[130:133], v[216:219], v[102:105]
	v_mfma_f32_16x16x32_bf16 v[98:101], v[138:141], v[216:219], v[98:101]
	v_mfma_f32_16x16x32_bf16 v[86:89], v[130:133], v[224:227], v[86:89]
	v_mfma_f32_16x16x32_bf16 v[82:85], v[138:141], v[224:227], v[82:85]
	v_mfma_f32_16x16x32_bf16 v[126:129], v[134:137], v[202:205], v[126:129]
	v_mfma_f32_16x16x32_bf16 v[122:125], v[142:145], v[202:205], v[122:125]
	v_mfma_f32_16x16x32_bf16 v[118:121], v[134:137], v[212:215], v[118:121]
	v_mfma_f32_16x16x32_bf16 v[114:117], v[142:145], v[212:215], v[114:117]
	v_mfma_f32_16x16x32_bf16 v[102:105], v[134:137], v[220:223], v[102:105]
	v_mfma_f32_16x16x32_bf16 v[98:101], v[142:145], v[220:223], v[98:101]
	v_mfma_f32_16x16x32_bf16 v[86:89], v[134:137], v[228:231], v[86:89]
	v_mfma_f32_16x16x32_bf16 v[82:85], v[142:145], v[228:231], v[82:85]
	v_mfma_f32_16x16x32_bf16 v[110:113], v[166:169], v[182:185], v[110:113]
	v_mfma_f32_16x16x32_bf16 v[106:109], v[174:177], v[182:185], v[106:109]
	v_mfma_f32_16x16x32_bf16 v[94:97], v[166:169], v[206:209], v[94:97]
	v_mfma_f32_16x16x32_bf16 v[90:93], v[174:177], v[206:209], v[90:93]
	v_mfma_f32_16x16x32_bf16 v[78:81], v[166:169], v[216:219], v[78:81]
	v_mfma_f32_16x16x32_bf16 v[74:77], v[174:177], v[216:219], v[74:77]
	v_mfma_f32_16x16x32_bf16 v[70:73], v[166:169], v[224:227], v[70:73]
	v_mfma_f32_16x16x32_bf16 v[66:69], v[174:177], v[224:227], v[66:69]
	v_mfma_f32_16x16x32_bf16 v[110:113], v[170:173], v[202:205], v[110:113]
	v_mfma_f32_16x16x32_bf16 v[106:109], v[178:181], v[202:205], v[106:109]
	v_mfma_f32_16x16x32_bf16 v[94:97], v[170:173], v[212:215], v[94:97]
	v_mfma_f32_16x16x32_bf16 v[90:93], v[178:181], v[212:215], v[90:93]
	v_mfma_f32_16x16x32_bf16 v[78:81], v[170:173], v[220:223], v[78:81]
	v_mfma_f32_16x16x32_bf16 v[74:77], v[178:181], v[220:223], v[74:77]
	v_mfma_f32_16x16x32_bf16 v[70:73], v[170:173], v[228:231], v[70:73]
	v_mfma_f32_16x16x32_bf16 v[66:69], v[178:181], v[228:231], v[66:69]
	s_setprio 0
	s_barrier
; #define PG8_STAGE(bufoff, gbase, voff) do { _Pragma("unroll") for (int _i = 0; _i < 2; ++_i) \
;         __builtin_amdgcn_global_load_lds((const unsigned*)((const char*)(gbase) + (voff)[_i]), (PG8_LAS unsigned*)(lds + (bufoff) + ldsw + _i * 8192), 16, 0, 0); } while (0)
; #define PG8_LDA(dst, b, h) do { _Pragma("unroll") for (int m = 0; m < 4; ++m) _Pragma("unroll") for (int k = 0; k < 2; ++k) dst[m][k] = *(const PG8_LAS bf16x8*)(lds + PG8_SA(b, h) + aoff + m * 2048 + k * 1024); } while (0)
; #define PG8_LDB(dst, b, h) do { _Pragma("unroll") for (int n = 0; n < 2; ++n) _Pragma("unroll") for (int k = 0; k < 2; ++k) dst[n][k] = *(const PG8_LAS bf16x8*)(lds + PG8_SB(b, h) + boff + n * 2048 + k * 1024); } while (0)
; #define PG8_MMA(ai, bj, At, Bt) do { __builtin_amdgcn_s_setprio(1); _Pragma("unroll") for (int m = 0; m < 4; ++m) _Pragma("unroll") for (int n = 0; n < 2; ++n) _Pragma("unroll") for (int k = 0; k < 2; ++k) \
;         acc[ai][bj][m][n] = __builtin_amdgcn_mfma_f32_16x16x32_bf16(Bt[n][k], At[m][k], acc[ai][bj][m][n], 0, 0, 0); __builtin_amdgcn_s_setprio(0); } while (0)
; #define PG8_WAIT_V(n) asm volatile("s_waitcnt vmcnt(" #n ")" ::: "memory")
; template <class Epi, class Sched, bool ALIGN_EPI = false, bool SP2 = false>
; __device__ __forceinline__ void gemm_phase(PG8_LAS unsigned char* lds, const Gemm g, const Sched& S, const Epi& E) {
;     ...
;             PG8_LDB(B0, 0, 0); PG8_LDB(B1, 0, 1); PG8_SCHED; PG8_LDA(At, 0, 0); PG8_STAGE(PG8_SA(1, 1), a1 + ahstep, voffA);
;             PG8_WAIT_V(8); PG8_WAIT_L(0); PG8_BAR; PG8_MMA(0, 0, At, B0); PG8_MMA(0, 1, At, B1); PG8_BAR; PG8_SCHED;
;             PG8_LDA(At, 0, 1); PG8_STAGE(PG8_SB(0, 0), b2, voffB); PG8_STAGE(PG8_SB(0, 1), b2 + hstep, voffB); PG8_STAGE(PG8_SA(0, 0), a2, voffA);
;             PG8_WAIT_V(8); PG8_WAIT_L(0); PG8_BAR; PG8_MMA(1, 0, At, B0); PG8_MMA(1, 1, At, B1); PG8_BAR; PG8_SCHED;
;             PG8_LDB(B0, 1, 0); PG8_LDB(B1, 1, 1); PG8_SCHED; PG8_LDA(At, 1, 0); PG8_STAGE(PG8_SA(0, 1), a2 + ahstep, voffA);
;             PG8_WAIT_V(8); PG8_WAIT_L(0); PG8_BAR; PG8_MMA(0, 0, At, B0); PG8_MMA(0, 1, At, B1); PG8_BAR; PG8_SCHED;
;             PG8_LDA(At, 1, 1); PG8_STAGE(PG8_SB(1, 0), b3, voffB); PG8_STAGE(PG8_SB(1, 1), b3 + hstep, voffB); PG8_STAGE(PG8_SA(1, 0), a3, voffA);
;             PG8_WAIT_V(8); PG8_WAIT_L(0); PG8_BAR; PG8_MMA(1, 0, At, B0); PG8_MMA(1, 1, At, B1); PG8_BAR; PG8_SCHED;
	s_add_i32 s28, s68, s35
	v_lshl_add_u64 v[186:187], v[186:187], 0, s[22:23]
	s_mov_b32 m0, s28
	ds_read_b128 v[182:185], v195 offset:49152
	ds_read_b128 v[202:205], v195 offset:50176
	ds_read_b128 v[206:209], v195 offset:51200
	ds_read_b128 v[212:215], v195 offset:52224
	ds_read_b128 v[216:219], v195 offset:53248
	ds_read_b128 v[220:223], v195 offset:54272
	ds_read_b128 v[224:227], v195 offset:55296
	ds_read_b128 v[228:231], v195 offset:56320
	global_load_lds_dwordx4 v[186:187], off
	s_add_i32 m0, s28, 0x2000
	s_add_u32 s4, s4, 0x40080
	v_lshl_add_u64 v[186:187], v[210:211], 0, s[22:23]
	s_addc_u32 s5, s5, 0
	s_add_i32 s28, s69, s35
	global_load_lds_dwordx4 v[186:187], off
	v_lshl_add_u64 v[186:187], s[4:5], 0, v[148:149]
	s_mov_b32 m0, s28
	s_nop 0
	global_load_lds_dwordx4 v[186:187], off
	v_lshl_add_u64 v[186:187], s[4:5], 0, v[152:153]
	s_add_i32 m0, s28, 0x2000
	s_nop 0
	global_load_lds_dwordx4 v[186:187], off
	v_lshl_add_u64 v[186:187], v[232:233], 0, s[22:23]
	s_mov_b32 m0, s56
	s_nop 0
	global_load_lds_dwordx4 v[186:187], off
	v_lshl_add_u64 v[186:187], v[234:235], 0, s[22:23]
	s_mov_b32 m0, s57
	s_nop 0
	global_load_lds_dwordx4 v[186:187], off
	s_waitcnt vmcnt(8)
	s_waitcnt lgkmcnt(0)
	s_barrier
	s_setprio 1
	s_waitcnt lgkmcnt(0)
	v_mfma_f32_16x16x32_bf16 v[62:65], v[130:133], v[182:185], v[62:65]
	v_mfma_f32_16x16x32_bf16 v[58:61], v[138:141], v[182:185], v[58:61]
	v_mfma_f32_16x16x32_bf16 v[54:57], v[130:133], v[206:209], v[54:57]
	v_mfma_f32_16x16x32_bf16 v[50:53], v[138:141], v[206:209], v[50:53]
	v_mfma_f32_16x16x32_bf16 v[38:41], v[130:133], v[216:219], v[38:41]
	v_mfma_f32_16x16x32_bf16 v[34:37], v[138:141], v[216:219], v[34:37]
	v_mfma_f32_16x16x32_bf16 v[22:25], v[130:133], v[224:227], v[22:25]
	v_mfma_f32_16x16x32_bf16 v[18:21], v[138:141], v[224:227], v[18:21]
	v_mfma_f32_16x16x32_bf16 v[62:65], v[134:137], v[202:205], v[62:65]
	v_mfma_f32_16x16x32_bf16 v[58:61], v[142:145], v[202:205], v[58:61]
	v_mfma_f32_16x16x32_bf16 v[54:57], v[134:137], v[212:215], v[54:57]
	v_mfma_f32_16x16x32_bf16 v[50:53], v[142:145], v[212:215], v[50:53]
	v_mfma_f32_16x16x32_bf16 v[38:41], v[134:137], v[220:223], v[38:41]
	v_mfma_f32_16x16x32_bf16 v[34:37], v[142:145], v[220:223], v[34:37]
	v_mfma_f32_16x16x32_bf16 v[22:25], v[134:137], v[228:231], v[22:25]
	v_mfma_f32_16x16x32_bf16 v[18:21], v[142:145], v[228:231], v[18:21]
	v_mfma_f32_16x16x32_bf16 v[46:49], v[166:169], v[182:185], v[46:49]
	v_mfma_f32_16x16x32_bf16 v[42:45], v[174:177], v[182:185], v[42:45]
	v_mfma_f32_16x16x32_bf16 v[30:33], v[166:169], v[206:209], v[30:33]
	v_mfma_f32_16x16x32_bf16 v[26:29], v[174:177], v[206:209], v[26:29]
	v_mfma_f32_16x16x32_bf16 v[14:17], v[166:169], v[216:219], v[14:17]
	v_mfma_f32_16x16x32_bf16 v[10:13], v[174:177], v[216:219], v[10:13]
	v_mfma_f32_16x16x32_bf16 v[6:9], v[166:169], v[224:227], v[6:9]
	v_mfma_f32_16x16x32_bf16 v[2:5], v[174:177], v[224:227], v[2:5]
	v_mfma_f32_16x16x32_bf16 v[46:49], v[170:173], v[202:205], v[46:49]
	v_mfma_f32_16x16x32_bf16 v[42:45], v[178:181], v[202:205], v[42:45]
	v_mfma_f32_16x16x32_bf16 v[30:33], v[170:173], v[212:215], v[30:33]
	v_mfma_f32_16x16x32_bf16 v[26:29], v[178:181], v[212:215], v[26:29]
	v_mfma_f32_16x16x32_bf16 v[14:17], v[170:173], v[220:223], v[14:17]
	v_mfma_f32_16x16x32_bf16 v[10:13], v[178:181], v[220:223], v[10:13]
	v_mfma_f32_16x16x32_bf16 v[6:9], v[170:173], v[228:231], v[6:9]
	v_mfma_f32_16x16x32_bf16 v[2:5], v[178:181], v[228:231], v[2:5]
	s_setprio 0
	s_barrier
	s_add_i32 s85, s85, 2
	s_add_u32 s0, s0, 0x100
	s_addc_u32 s1, s1, 0
	s_add_u32 s73, s73, 0x100
	s_addc_u32 s84, s84, 0
	s_cmp_gt_u32 s85, 13
	s_cbranch_scc0 .LBB0_206
	s_and_b64 vcc, exec, s[42:43]
	s_cbranch_vccz .LBB0_211
	s_barrier
	v_lshl_add_u32 v166, s72, 8, v189
	s_cmp_gt_i32 s44, 1
	s_mov_b64 s[0:1], -1
	s_cbranch_scc1 .LBB0_212

; #define PG8_STAGE(bufoff, gbase, voff) do { _Pragma("unroll") for (int _i = 0; _i < 2; ++_i) \
;         __builtin_amdgcn_global_load_lds((const unsigned*)((const char*)(gbase) + (voff)[_i]), (PG8_LAS unsigned*)(lds + (bufoff) + ldsw + _i * 8192), 16, 0, 0); } while (0)
; #define PG8_LDA(dst, b, h) do { _Pragma("unroll") for (int m = 0; m < 4; ++m) _Pragma("unroll") for (int k = 0; k < 2; ++k) dst[m][k] = *(const PG8_LAS bf16x8*)(lds + PG8_SA(b, h) + aoff + m * 2048 + k * 1024); } while (0)
; #define PG8_LDB(dst, b, h) do { _Pragma("unroll") for (int n = 0; n < 2; ++n) _Pragma("unroll") for (int k = 0; k < 2; ++k) dst[n][k] = *(const PG8_LAS bf16x8*)(lds + PG8_SB(b, h) + boff + n * 2048 + k * 1024); } while (0)
; #define PG8_MMA(ai, bj, At, Bt) do { __builtin_amdgcn_s_setprio(1); _Pragma("unroll") for (int m = 0; m < 4; ++m) _Pragma("unroll") for (int n = 0; n < 2; ++n) _Pragma("unroll") for (int k = 0; k < 2; ++k) \
;         acc[ai][bj][m][n] = __builtin_amdgcn_mfma_f32_16x16x32_bf16(Bt[n][k], At[m][k], acc[ai][bj][m][n], 0, 0, 0); __builtin_amdgcn_s_setprio(0); } while (0)
; #define PG8_WAIT_V(n) asm volatile("s_waitcnt vmcnt(" #n ")" ::: "memory")
; template <class Epi, class Sched, bool ALIGN_EPI = false, bool SP2 = false>
; __device__ __forceinline__ void gemm_phase(PG8_LAS unsigned char* lds, const Gemm g, const Sched& S, const Epi& E) {
;     ...
;             PG8_LDB(B0, 0, 0); PG8_LDB(B1, 0, 1); PG8_SCHED; PG8_LDA(At, 0, 0); PG8_STAGE(PG8_SA(1, 1), a1 + ahstep, voffA);
;             PG8_WAIT_V(8); PG8_WAIT_L(0); PG8_BAR; PG8_MMA(0, 0, At, B0); PG8_MMA(0, 1, At, B1); PG8_BAR; PG8_SCHED;
;             PG8_LDA(At, 0, 1); PG8_STAGE(PG8_SB(0, 0), b2, voffB); PG8_STAGE(PG8_SB(0, 1), b2 + hstep, voffB); PG8_STAGE(PG8_SA(0, 0), a2, voffA);
;             PG8_WAIT_V(8); PG8_WAIT_L(0); PG8_BAR; PG8_MMA(1, 0, At, B0); PG8_MMA(1, 1, At, B1); PG8_BAR; PG8_SCHED;
;             PG8_LDB(B0, 1, 0); PG8_LDB(B1, 1, 1); PG8_SCHED; PG8_LDA(At, 1, 0); PG8_STAGE(PG8_SA(0, 1), a2 + ahstep, voffA);
;             PG8_WAIT_V(8); PG8_WAIT_L(0); PG8_BAR; PG8_MMA(0, 0, At, B0); PG8_MMA(0, 1, At, B1); PG8_BAR; PG8_SCHED;
;             PG8_LDA(At, 1, 1); PG8_STAGE(PG8_SB(1, 0), b3, voffB); PG8_STAGE(PG8_SB(1, 1), b3 + hstep, voffB); PG8_STAGE(PG8_SA(1, 0), a3, voffA);
;             PG8_WAIT_V(8); PG8_WAIT_L(0); PG8_BAR; PG8_MMA(1, 0, At, B0); PG8_MMA(1, 1, At, B1); PG8_BAR; PG8_SCHED;
.LBB0_339:
	s_waitcnt vmcnt(0)
	ds_read_b128 v[114:117], v188
	ds_read_b128 v[122:125], v188 offset:1024
	ds_read_b128 v[130:133], v188 offset:2048
	ds_read_b128 v[134:137], v188 offset:3072
	ds_read_b128 v[162:165], v189
	ds_read_b128 v[166:169], v189 offset:1024
	ds_read_b128 v[170:173], v189 offset:2048
	ds_read_b128 v[174:177], v189 offset:3072
	s_add_u32 s4, s0, 0xfffc0080
	s_addc_u32 s5, s1, -1
	s_cmp_eq_u32 s89, 12
	s_cselect_b32 s31, s43, s5
	s_cselect_b32 s30, s48, s4
	s_cselect_b32 s5, s23, s88
	s_cselect_b32 s4, s49, s60
	v_lshl_add_u64 v[210:211], s[0:1], 0, v[158:159]
	s_add_i32 m0, s29, 0xc000
	ds_read_b128 v[178:181], v190
	ds_read_b128 v[194:197], v190 offset:1024
	ds_read_b128 v[198:201], v190 offset:2048
	ds_read_b128 v[202:205], v190 offset:3072
	ds_read_b128 v[206:209], v190 offset:4096
	ds_read_b128 v[214:217], v190 offset:5120
	ds_read_b128 v[218:221], v190 offset:6144
	ds_read_b128 v[222:225], v190 offset:7168
	global_load_lds_dwordx4 v[210:211], off
	v_lshl_add_u64 v[210:211], s[0:1], 0, v[160:161]
	s_add_i32 m0, s29, 0xe000
	s_nop 0
	global_load_lds_dwordx4 v[210:211], off
	s_waitcnt vmcnt(8)
	s_waitcnt lgkmcnt(0)
	s_barrier
	s_setprio 1
	s_waitcnt lgkmcnt(0)
	v_mfma_f32_16x16x32_bf16 v[138:141], v[114:117], v[178:181], v[138:141]
	v_mfma_f32_16x16x32_bf16 v[142:145], v[130:133], v[178:181], v[142:145]
	v_mfma_f32_16x16x32_bf16 v[106:109], v[114:117], v[198:201], v[106:109]
	v_mfma_f32_16x16x32_bf16 v[110:113], v[130:133], v[198:201], v[110:113]
	v_mfma_f32_16x16x32_bf16 v[90:93], v[114:117], v[206:209], v[90:93]
	v_mfma_f32_16x16x32_bf16 v[94:97], v[130:133], v[206:209], v[94:97]
	v_mfma_f32_16x16x32_bf16 v[74:77], v[114:117], v[218:221], v[74:77]
	v_mfma_f32_16x16x32_bf16 v[78:81], v[130:133], v[218:221], v[78:81]
	v_mfma_f32_16x16x32_bf16 v[138:141], v[122:125], v[194:197], v[138:141]
	v_mfma_f32_16x16x32_bf16 v[142:145], v[134:137], v[194:197], v[142:145]
	v_mfma_f32_16x16x32_bf16 v[106:109], v[122:125], v[202:205], v[106:109]
	v_mfma_f32_16x16x32_bf16 v[110:113], v[134:137], v[202:205], v[110:113]
	v_mfma_f32_16x16x32_bf16 v[90:93], v[122:125], v[214:217], v[90:93]
	v_mfma_f32_16x16x32_bf16 v[94:97], v[134:137], v[214:217], v[94:97]
	v_mfma_f32_16x16x32_bf16 v[74:77], v[122:125], v[222:225], v[74:77]
	v_mfma_f32_16x16x32_bf16 v[78:81], v[134:137], v[222:225], v[78:81]
	v_mfma_f32_16x16x32_bf16 v[118:121], v[162:165], v[178:181], v[118:121]
	v_mfma_f32_16x16x32_bf16 v[126:129], v[170:173], v[178:181], v[126:129]
	v_mfma_f32_16x16x32_bf16 v[98:101], v[162:165], v[198:201], v[98:101]
	v_mfma_f32_16x16x32_bf16 v[102:105], v[170:173], v[198:201], v[102:105]
	v_mfma_f32_16x16x32_bf16 v[82:85], v[162:165], v[206:209], v[82:85]
	v_mfma_f32_16x16x32_bf16 v[86:89], v[170:173], v[206:209], v[86:89]
	v_mfma_f32_16x16x32_bf16 v[66:69], v[162:165], v[218:221], v[66:69]
	v_mfma_f32_16x16x32_bf16 v[70:73], v[170:173], v[218:221], v[70:73]
	v_mfma_f32_16x16x32_bf16 v[118:121], v[166:169], v[194:197], v[118:121]
	v_mfma_f32_16x16x32_bf16 v[126:129], v[174:177], v[194:197], v[126:129]
	v_mfma_f32_16x16x32_bf16 v[98:101], v[166:169], v[202:205], v[98:101]
	v_mfma_f32_16x16x32_bf16 v[102:105], v[174:177], v[202:205], v[102:105]
	v_mfma_f32_16x16x32_bf16 v[82:85], v[166:169], v[214:217], v[82:85]
	v_mfma_f32_16x16x32_bf16 v[86:89], v[174:177], v[214:217], v[86:89]
	v_mfma_f32_16x16x32_bf16 v[66:69], v[166:169], v[222:225], v[66:69]
	v_mfma_f32_16x16x32_bf16 v[70:73], v[174:177], v[222:225], v[70:73]
	s_setprio 0
	s_barrier
	s_add_i32 s68, s85, s53
	v_lshl_add_u64 v[210:211], s[4:5], 0, v[148:149]
	s_mov_b32 m0, s68
	ds_read_b128 v[178:181], v190 offset:16384
	ds_read_b128 v[194:197], v190 offset:17408
	ds_read_b128 v[198:201], v190 offset:18432
	ds_read_b128 v[202:205], v190 offset:19456
	ds_read_b128 v[206:209], v190 offset:20480
	ds_read_b128 v[214:217], v190 offset:21504
	ds_read_b128 v[218:221], v190 offset:22528
	ds_read_b128 v[222:225], v190 offset:23552
	global_load_lds_dwordx4 v[210:211], off
	s_add_i32 m0, s68, 0x2000
	s_add_u32 s68, s4, 0x40000
	v_lshl_add_u64 v[212:213], s[4:5], 0, v[152:153]
	s_addc_u32 s69, s5, 0
	s_add_i32 s70, s86, s53
	global_load_lds_dwordx4 v[212:213], off
	v_lshl_add_u64 v[226:227], s[68:69], 0, v[148:149]
	s_mov_b32 m0, s70
	v_lshl_add_u64 v[228:229], s[30:31], 0, v[150:151]
	global_load_lds_dwordx4 v[226:227], off
	v_lshl_add_u64 v[226:227], s[68:69], 0, v[152:153]
	s_add_i32 m0, s70, 0x2000
	s_nop 0
	global_load_lds_dwordx4 v[226:227], off
	v_lshl_add_u64 v[226:227], s[30:31], 0, v[146:147]
	s_mov_b32 m0, s29
	s_nop 0
	global_load_lds_dwordx4 v[226:227], off
	s_mov_b32 m0, s35
	s_nop 0
	global_load_lds_dwordx4 v[228:229], off
	s_waitcnt vmcnt(8)
	s_waitcnt lgkmcnt(0)
	s_barrier
; #define PG8_STAGE(bufoff, gbase, voff) do { _Pragma("unroll") for (int _i = 0; _i < 2; ++_i) \
;         __builtin_amdgcn_global_load_lds((const unsigned*)((const char*)(gbase) + (voff)[_i]), (PG8_LAS unsigned*)(lds + (bufoff) + ldsw + _i * 8192), 16, 0, 0); } while (0)
; #define PG8_LDA(dst, b, h) do { _Pragma("unroll") for (int m = 0; m < 4; ++m) _Pragma("unroll") for (int k = 0; k < 2; ++k) dst[m][k] = *(const PG8_LAS bf16x8*)(lds + PG8_SA(b, h) + aoff + m * 2048 + k * 1024); } while (0)
; #define PG8_LDB(dst, b, h) do { _Pragma("unroll") for (int n = 0; n < 2; ++n) _Pragma("unroll") for (int k = 0; k < 2; ++k) dst[n][k] = *(const PG8_LAS bf16x8*)(lds + PG8_SB(b, h) + boff + n * 2048 + k * 1024); } while (0)
; #define PG8_MMA(ai, bj, At, Bt) do { __builtin_amdgcn_s_setprio(1); _Pragma("unroll") for (int m = 0; m < 4; ++m) _Pragma("unroll") for (int n = 0; n < 2; ++n) _Pragma("unroll") for (int k = 0; k < 2; ++k) \
;         acc[ai][bj][m][n] = __builtin_amdgcn_mfma_f32_16x16x32_bf16(Bt[n][k], At[m][k], acc[ai][bj][m][n], 0, 0, 0); __builtin_amdgcn_s_setprio(0); } while (0)
; #define PG8_WAIT_V(n) asm volatile("s_waitcnt vmcnt(" #n ")" ::: "memory")
; template <class Epi, class Sched, bool ALIGN_EPI = false, bool SP2 = false>
; __device__ __forceinline__ void gemm_phase(PG8_LAS unsigned char* lds, const Gemm g, const Sched& S, const Epi& E) {
;     ...
;             PG8_LDB(B0, 0, 0); PG8_LDB(B1, 0, 1); PG8_SCHED; PG8_LDA(At, 0, 0); PG8_STAGE(PG8_SA(1, 1), a1 + ahstep, voffA);
;             PG8_WAIT_V(8); PG8_WAIT_L(0); PG8_BAR; PG8_MMA(0, 0, At, B0); PG8_MMA(0, 1, At, B1); PG8_BAR; PG8_SCHED;
;             PG8_LDA(At, 0, 1); PG8_STAGE(PG8_SB(0, 0), b2, voffB); PG8_STAGE(PG8_SB(0, 1), b2 + hstep, voffB); PG8_STAGE(PG8_SA(0, 0), a2, voffA);
;             PG8_WAIT_V(8); PG8_WAIT_L(0); PG8_BAR; PG8_MMA(1, 0, At, B0); PG8_MMA(1, 1, At, B1); PG8_BAR; PG8_SCHED;
;             PG8_LDB(B0, 1, 0); PG8_LDB(B1, 1, 1); PG8_SCHED; PG8_LDA(At, 1, 0); PG8_STAGE(PG8_SA(0, 1), a2 + ahstep, voffA);
;             PG8_WAIT_V(8); PG8_WAIT_L(0); PG8_BAR; PG8_MMA(0, 0, At, B0); PG8_MMA(0, 1, At, B1); PG8_BAR; PG8_SCHED;
;             PG8_LDA(At, 1, 1); PG8_STAGE(PG8_SB(1, 0), b3, voffB); PG8_STAGE(PG8_SB(1, 1), b3 + hstep, voffB); PG8_STAGE(PG8_SA(1, 0), a3, voffA);
;             PG8_WAIT_V(8); PG8_WAIT_L(0); PG8_BAR; PG8_MMA(1, 0, At, B0); PG8_MMA(1, 1, At, B1); PG8_BAR; PG8_SCHED;
	s_setprio 1
	s_waitcnt lgkmcnt(0)
	v_mfma_f32_16x16x32_bf16 v[58:61], v[114:117], v[178:181], v[58:61]
	v_mfma_f32_16x16x32_bf16 v[62:65], v[130:133], v[178:181], v[62:65]
	v_mfma_f32_16x16x32_bf16 v[42:45], v[114:117], v[198:201], v[42:45]
	v_mfma_f32_16x16x32_bf16 v[46:49], v[130:133], v[198:201], v[46:49]
	v_mfma_f32_16x16x32_bf16 v[26:29], v[114:117], v[206:209], v[26:29]
	v_mfma_f32_16x16x32_bf16 v[30:33], v[130:133], v[206:209], v[30:33]
	v_mfma_f32_16x16x32_bf16 v[10:13], v[114:117], v[218:221], v[10:13]
	v_mfma_f32_16x16x32_bf16 v[14:17], v[130:133], v[218:221], v[14:17]
	v_mfma_f32_16x16x32_bf16 v[58:61], v[122:125], v[194:197], v[58:61]
	v_mfma_f32_16x16x32_bf16 v[62:65], v[134:137], v[194:197], v[62:65]
	v_mfma_f32_16x16x32_bf16 v[42:45], v[122:125], v[202:205], v[42:45]
	v_mfma_f32_16x16x32_bf16 v[46:49], v[134:137], v[202:205], v[46:49]
	v_mfma_f32_16x16x32_bf16 v[26:29], v[122:125], v[214:217], v[26:29]
	v_mfma_f32_16x16x32_bf16 v[30:33], v[134:137], v[214:217], v[30:33]
	v_mfma_f32_16x16x32_bf16 v[10:13], v[122:125], v[222:225], v[10:13]
	v_mfma_f32_16x16x32_bf16 v[14:17], v[134:137], v[222:225], v[14:17]
	v_mfma_f32_16x16x32_bf16 v[50:53], v[162:165], v[178:181], v[50:53]
	v_mfma_f32_16x16x32_bf16 v[54:57], v[170:173], v[178:181], v[54:57]
	v_mfma_f32_16x16x32_bf16 v[34:37], v[162:165], v[198:201], v[34:37]
	v_mfma_f32_16x16x32_bf16 v[38:41], v[170:173], v[198:201], v[38:41]
	v_mfma_f32_16x16x32_bf16 v[18:21], v[162:165], v[206:209], v[18:21]
	v_mfma_f32_16x16x32_bf16 v[22:25], v[170:173], v[206:209], v[22:25]
	v_mfma_f32_16x16x32_bf16 v[2:5], v[162:165], v[218:221], v[2:5]
	v_mfma_f32_16x16x32_bf16 v[6:9], v[170:173], v[218:221], v[6:9]
	v_mfma_f32_16x16x32_bf16 v[50:53], v[166:169], v[194:197], v[50:53]
	v_mfma_f32_16x16x32_bf16 v[54:57], v[174:177], v[194:197], v[54:57]
	v_mfma_f32_16x16x32_bf16 v[34:37], v[166:169], v[202:205], v[34:37]
	v_mfma_f32_16x16x32_bf16 v[38:41], v[174:177], v[202:205], v[38:41]
	v_mfma_f32_16x16x32_bf16 v[18:21], v[166:169], v[214:217], v[18:21]
	v_mfma_f32_16x16x32_bf16 v[22:25], v[174:177], v[214:217], v[22:25]
	v_mfma_f32_16x16x32_bf16 v[2:5], v[166:169], v[222:225], v[2:5]
	v_mfma_f32_16x16x32_bf16 v[6:9], v[174:177], v[222:225], v[6:9]
	s_setprio 0
	s_barrier
	s_add_i32 s68, 0, 0x18000
	v_add_u32_e32 v1, s68, v185
	s_add_i32 s69, 0, 0x1c000
	ds_read_b128 v[114:117], v1
	ds_read_b128 v[122:125], v1 offset:1024
	ds_read_b128 v[130:133], v1 offset:2048
	ds_read_b128 v[134:137], v1 offset:3072
	v_add_u32_e32 v1, s69, v185
	ds_read_b128 v[162:165], v1
	ds_read_b128 v[166:169], v1 offset:1024
	ds_read_b128 v[170:173], v1 offset:2048
	ds_read_b128 v[174:177], v1 offset:3072
	s_add_u32 s30, s30, 0x40000
	s_addc_u32 s31, s31, 0
	s_mov_b32 m0, s54
	v_lshl_add_u64 v[230:231], s[30:31], 0, v[146:147]
	ds_read_b128 v[178:181], v190 offset:32768
	ds_read_b128 v[194:197], v190 offset:33792
	ds_read_b128 v[198:201], v190 offset:34816
	ds_read_b128 v[202:205], v190 offset:35840
	ds_read_b128 v[206:209], v190 offset:36864
	ds_read_b128 v[214:217], v190 offset:37888
	ds_read_b128 v[218:221], v190 offset:38912
	ds_read_b128 v[222:225], v190 offset:39936
	global_load_lds_dwordx4 v[230:231], off
	v_lshl_add_u64 v[230:231], s[30:31], 0, v[150:151]
	s_mov_b32 m0, s55
	s_nop 0
	global_load_lds_dwordx4 v[230:231], off
	s_waitcnt vmcnt(8)
	s_waitcnt lgkmcnt(0)
	s_barrier
	s_setprio 1
	s_waitcnt lgkmcnt(0)
	v_mfma_f32_16x16x32_bf16 v[138:141], v[114:117], v[178:181], v[138:141]
	v_mfma_f32_16x16x32_bf16 v[142:145], v[130:133], v[178:181], v[142:145]
	v_mfma_f32_16x16x32_bf16 v[106:109], v[114:117], v[198:201], v[106:109]
	v_mfma_f32_16x16x32_bf16 v[110:113], v[130:133], v[198:201], v[110:113]
	v_mfma_f32_16x16x32_bf16 v[90:93], v[114:117], v[206:209], v[90:93]
	v_mfma_f32_16x16x32_bf16 v[94:97], v[130:133], v[206:209], v[94:97]
	v_mfma_f32_16x16x32_bf16 v[74:77], v[114:117], v[218:221], v[74:77]
	v_mfma_f32_16x16x32_bf16 v[78:81], v[130:133], v[218:221], v[78:81]
	v_mfma_f32_16x16x32_bf16 v[138:141], v[122:125], v[194:197], v[138:141]
	v_mfma_f32_16x16x32_bf16 v[142:145], v[134:137], v[194:197], v[142:145]
	v_mfma_f32_16x16x32_bf16 v[106:109], v[122:125], v[202:205], v[106:109]
	v_mfma_f32_16x16x32_bf16 v[110:113], v[134:137], v[202:205], v[110:113]
	v_mfma_f32_16x16x32_bf16 v[90:93], v[122:125], v[214:217], v[90:93]
	v_mfma_f32_16x16x32_bf16 v[94:97], v[134:137], v[214:217], v[94:97]
	v_mfma_f32_16x16x32_bf16 v[74:77], v[122:125], v[222:225], v[74:77]
	v_mfma_f32_16x16x32_bf16 v[78:81], v[134:137], v[222:225], v[78:81]
	v_mfma_f32_16x16x32_bf16 v[118:121], v[162:165], v[178:181], v[118:121]
	v_mfma_f32_16x16x32_bf16 v[126:129], v[170:173], v[178:181], v[126:129]
	v_mfma_f32_16x16x32_bf16 v[98:101], v[162:165], v[198:201], v[98:101]
	v_mfma_f32_16x16x32_bf16 v[102:105], v[170:173], v[198:201], v[102:105]
	v_mfma_f32_16x16x32_bf16 v[82:85], v[162:165], v[206:209], v[82:85]
	v_mfma_f32_16x16x32_bf16 v[86:89], v[170:173], v[206:209], v[86:89]
	v_mfma_f32_16x16x32_bf16 v[66:69], v[162:165], v[218:221], v[66:69]
	v_mfma_f32_16x16x32_bf16 v[70:73], v[170:173], v[218:221], v[70:73]
	v_mfma_f32_16x16x32_bf16 v[118:121], v[166:169], v[194:197], v[118:121]
	v_mfma_f32_16x16x32_bf16 v[126:129], v[174:177], v[194:197], v[126:129]
	v_mfma_f32_16x16x32_bf16 v[98:101], v[166:169], v[202:205], v[98:101]
	v_mfma_f32_16x16x32_bf16 v[102:105], v[174:177], v[202:205], v[102:105]
	v_mfma_f32_16x16x32_bf16 v[82:85], v[166:169], v[214:217], v[82:85]
	v_mfma_f32_16x16x32_bf16 v[86:89], v[174:177], v[214:217], v[86:89]
	v_mfma_f32_16x16x32_bf16 v[66:69], v[166:169], v[222:225], v[66:69]
	v_mfma_f32_16x16x32_bf16 v[70:73], v[174:177], v[222:225], v[70:73]
	s_setprio 0
	s_barrier
; #define PG8_STAGE(bufoff, gbase, voff) do { _Pragma("unroll") for (int _i = 0; _i < 2; ++_i) \
;         __builtin_amdgcn_global_load_lds((const unsigned*)((const char*)(gbase) + (voff)[_i]), (PG8_LAS unsigned*)(lds + (bufoff) + ldsw + _i * 8192), 16, 0, 0); } while (0)
; #define PG8_LDA(dst, b, h) do { _Pragma("unroll") for (int m = 0; m < 4; ++m) _Pragma("unroll") for (int k = 0; k < 2; ++k) dst[m][k] = *(const PG8_LAS bf16x8*)(lds + PG8_SA(b, h) + aoff + m * 2048 + k * 1024); } while (0)
; #define PG8_LDB(dst, b, h) do { _Pragma("unroll") for (int n = 0; n < 2; ++n) _Pragma("unroll") for (int k = 0; k < 2; ++k) dst[n][k] = *(const PG8_LAS bf16x8*)(lds + PG8_SB(b, h) + boff + n * 2048 + k * 1024); } while (0)
; #define PG8_MMA(ai, bj, At, Bt) do { __builtin_amdgcn_s_setprio(1); _Pragma("unroll") for (int m = 0; m < 4; ++m) _Pragma("unroll") for (int n = 0; n < 2; ++n) _Pragma("unroll") for (int k = 0; k < 2; ++k) \
;         acc[ai][bj][m][n] = __builtin_amdgcn_mfma_f32_16x16x32_bf16(Bt[n][k], At[m][k], acc[ai][bj][m][n], 0, 0, 0); __builtin_amdgcn_s_setprio(0); } while (0)
; #define PG8_WAIT_V(n) asm volatile("s_waitcnt vmcnt(" #n ")" ::: "memory")
; template <class Epi, class Sched, bool ALIGN_EPI = false, bool SP2 = false>
; __device__ __forceinline__ void gemm_phase(PG8_LAS unsigned char* lds, const Gemm g, const Sched& S, const Epi& E) {
;     ...
;             PG8_LDB(B0, 0, 0); PG8_LDB(B1, 0, 1); PG8_SCHED; PG8_LDA(At, 0, 0); PG8_STAGE(PG8_SA(1, 1), a1 + ahstep, voffA);
;             PG8_WAIT_V(8); PG8_WAIT_L(0); PG8_BAR; PG8_MMA(0, 0, At, B0); PG8_MMA(0, 1, At, B1); PG8_BAR; PG8_SCHED;
;             PG8_LDA(At, 0, 1); PG8_STAGE(PG8_SB(0, 0), b2, voffB); PG8_STAGE(PG8_SB(0, 1), b2 + hstep, voffB); PG8_STAGE(PG8_SA(0, 0), a2, voffA);
;             PG8_WAIT_V(8); PG8_WAIT_L(0); PG8_BAR; PG8_MMA(1, 0, At, B0); PG8_MMA(1, 1, At, B1); PG8_BAR; PG8_SCHED;
;             PG8_LDB(B0, 1, 0); PG8_LDB(B1, 1, 1); PG8_SCHED; PG8_LDA(At, 1, 0); PG8_STAGE(PG8_SA(0, 1), a2 + ahstep, voffA);
;             PG8_WAIT_V(8); PG8_WAIT_L(0); PG8_BAR; PG8_MMA(0, 0, At, B0); PG8_MMA(0, 1, At, B1); PG8_BAR; PG8_SCHED;
;             PG8_LDA(At, 1, 1); PG8_STAGE(PG8_SB(1, 0), b3, voffB); PG8_STAGE(PG8_SB(1, 1), b3 + hstep, voffB); PG8_STAGE(PG8_SA(1, 0), a3, voffA);
;             PG8_WAIT_V(8); PG8_WAIT_L(0); PG8_BAR; PG8_MMA(1, 0, At, B0); PG8_MMA(1, 1, At, B1); PG8_BAR; PG8_SCHED;
	s_add_i32 s30, s68, s53
	v_lshl_add_u64 v[210:211], v[210:211], 0, s[8:9]
	s_mov_b32 m0, s30
	ds_read_b128 v[178:181], v190 offset:49152
	ds_read_b128 v[194:197], v190 offset:50176
	ds_read_b128 v[198:201], v190 offset:51200
	ds_read_b128 v[202:205], v190 offset:52224
	ds_read_b128 v[206:209], v190 offset:53248
	ds_read_b128 v[214:217], v190 offset:54272
	ds_read_b128 v[218:221], v190 offset:55296
	ds_read_b128 v[222:225], v190 offset:56320
	global_load_lds_dwordx4 v[210:211], off
	s_add_i32 m0, s30, 0x2000
	s_add_u32 s4, s4, 0x40080
	v_lshl_add_u64 v[210:211], v[212:213], 0, s[8:9]
	s_addc_u32 s5, s5, 0
	s_add_i32 s30, s69, s53
	global_load_lds_dwordx4 v[210:211], off
	v_lshl_add_u64 v[210:211], s[4:5], 0, v[148:149]
	s_mov_b32 m0, s30
	s_nop 0
	global_load_lds_dwordx4 v[210:211], off
	v_lshl_add_u64 v[210:211], s[4:5], 0, v[152:153]
	s_add_i32 m0, s30, 0x2000
	s_nop 0
	global_load_lds_dwordx4 v[210:211], off
	v_lshl_add_u64 v[210:211], v[226:227], 0, s[8:9]
	s_mov_b32 m0, s57
	s_nop 0
	global_load_lds_dwordx4 v[210:211], off
	v_lshl_add_u64 v[210:211], v[228:229], 0, s[8:9]
	s_mov_b32 m0, s58
	s_nop 0
	global_load_lds_dwordx4 v[210:211], off
	s_waitcnt vmcnt(8)
	s_waitcnt lgkmcnt(0)
	s_barrier
	s_setprio 1
	s_waitcnt lgkmcnt(0)
	v_mfma_f32_16x16x32_bf16 v[58:61], v[114:117], v[178:181], v[58:61]
	v_mfma_f32_16x16x32_bf16 v[62:65], v[130:133], v[178:181], v[62:65]
	v_mfma_f32_16x16x32_bf16 v[42:45], v[114:117], v[198:201], v[42:45]
	v_mfma_f32_16x16x32_bf16 v[46:49], v[130:133], v[198:201], v[46:49]
	v_mfma_f32_16x16x32_bf16 v[26:29], v[114:117], v[206:209], v[26:29]
	v_mfma_f32_16x16x32_bf16 v[30:33], v[130:133], v[206:209], v[30:33]
	v_mfma_f32_16x16x32_bf16 v[10:13], v[114:117], v[218:221], v[10:13]
	v_mfma_f32_16x16x32_bf16 v[14:17], v[130:133], v[218:221], v[14:17]
	v_mfma_f32_16x16x32_bf16 v[58:61], v[122:125], v[194:197], v[58:61]
	v_mfma_f32_16x16x32_bf16 v[62:65], v[134:137], v[194:197], v[62:65]
	v_mfma_f32_16x16x32_bf16 v[42:45], v[122:125], v[202:205], v[42:45]
	v_mfma_f32_16x16x32_bf16 v[46:49], v[134:137], v[202:205], v[46:49]
	v_mfma_f32_16x16x32_bf16 v[26:29], v[122:125], v[214:217], v[26:29]
	v_mfma_f32_16x16x32_bf16 v[30:33], v[134:137], v[214:217], v[30:33]
	v_mfma_f32_16x16x32_bf16 v[10:13], v[122:125], v[222:225], v[10:13]
	v_mfma_f32_16x16x32_bf16 v[14:17], v[134:137], v[222:225], v[14:17]
	v_mfma_f32_16x16x32_bf16 v[50:53], v[162:165], v[178:181], v[50:53]
	v_mfma_f32_16x16x32_bf16 v[54:57], v[170:173], v[178:181], v[54:57]
	v_mfma_f32_16x16x32_bf16 v[34:37], v[162:165], v[198:201], v[34:37]
	v_mfma_f32_16x16x32_bf16 v[38:41], v[170:173], v[198:201], v[38:41]
	v_mfma_f32_16x16x32_bf16 v[18:21], v[162:165], v[206:209], v[18:21]
	v_mfma_f32_16x16x32_bf16 v[22:25], v[170:173], v[206:209], v[22:25]
	v_mfma_f32_16x16x32_bf16 v[2:5], v[162:165], v[218:221], v[2:5]
	v_mfma_f32_16x16x32_bf16 v[6:9], v[170:173], v[218:221], v[6:9]
	v_mfma_f32_16x16x32_bf16 v[50:53], v[166:169], v[194:197], v[50:53]
	v_mfma_f32_16x16x32_bf16 v[54:57], v[174:177], v[194:197], v[54:57]
	v_mfma_f32_16x16x32_bf16 v[34:37], v[166:169], v[202:205], v[34:37]
	v_mfma_f32_16x16x32_bf16 v[38:41], v[174:177], v[202:205], v[38:41]
	v_mfma_f32_16x16x32_bf16 v[18:21], v[166:169], v[214:217], v[18:21]
	v_mfma_f32_16x16x32_bf16 v[22:25], v[174:177], v[214:217], v[22:25]
	v_mfma_f32_16x16x32_bf16 v[2:5], v[166:169], v[222:225], v[2:5]
	v_mfma_f32_16x16x32_bf16 v[6:9], v[174:177], v[222:225], v[6:9]
	s_setprio 0
	s_barrier
	s_add_i32 s89, s89, 2
	s_add_u32 s0, s0, 0x100
	s_addc_u32 s1, s1, 0
	s_add_u32 s60, s60, 0x100
	s_addc_u32 s88, s88, 0
	s_cmp_gt_u32 s89, 13
	s_cbranch_scc0 .LBB0_339
	s_and_b64 vcc, exec, s[10:11]
	s_cbranch_vccz .LBB0_342
	s_barrier

; __global__ void __launch_bounds__(512, 2) mk_fwd(Args a) {
;     ...
; #pragma unroll 1
;         for (int c0_ = bid; c0_ < 256; c0_ += G) {
;             const int c = (G == 256) ? (c0_ & 7) * 32 + (c0_ >> 3) : c0_;
;             const int grp = c >> 4, j = c & 15, b = grp >> 2, map = (grp >> 1) & 1, vh = grp & 1;
;             bf16x8 qrx[4];
; #pragma unroll
;             for (int d = 0; d < 4; ++d) qrx[d] = bf16x8{};
; #pragma unroll 1
;             for (int i = 0; i < 4; ++i) { const int h = 3 - i, qb = (i & 1) ? 15 - j : j;
;                 const float a2 = __builtin_bit_cast(float, __builtin_amdgcn_readfirstlane(__builtin_bit_cast(int, exp2f(-2.f * (float)(h + 1)) * LOG2E)));
;                 const int W = (int)fminf((2.f * smax2 + 36.f) / a2 + 1.f, 1.0e6f); int t0 = (qb * 256 - W) >> 6; t0 = (t0 < 0 ? 0 : t0) & ~1;
;                 t0 = __builtin_amdgcn_readfirstlane(t0);
;                 const size_t qoff = (size_t)(h * 128 + map * 64) * 2, voff = (size_t)(h * 128 + vh * 64) * 2;
;                 const int hn = i < 3 ? 2 - i : 0, qbn = (i & 1) ? j : 15 - j;
;                 const float a2n = exp2f(-2.f * (float)(hn + 1)) * LOG2E; const int Wn = (int)fminf((2.f * smax2 + 36.f) / a2n + 1.f, 1.0e6f); int t0n = (qbn * 256 - Wn) >> 6; t0n = (t0n < 0 ? 0 : t0n) & ~1;
;                 t0n = __builtin_amdgcn_readfirstlane(t0n);
;                 const size_t qoffn = (size_t)(hn * 128 + map * 64) * 2;
;     ...
;                 attn_body::attn_unit<60>(b, qb, (const attn_body::bf16*)(ws + WS_QB + qoff), (const attn_body::bf16*)(ws + WS_KB + qoff), (const attn_body::bf16*)(ws + WS_VB + voff),
;                                         (attn_body::bf16*)(ws + (map ? WS_O1 : WS_O0) + voff), (char*)lds_raw, a2, t0, smax2 * 1.01f + 0.25f,
;                                         qrx, i > 0, i < 3, qbn, (const attn_body::bf16*)(ws + WS_QB + qoffn), (const attn_body::bf16*)(ws + WS_KB + qoffn), t0n);
.Lp2_attn:
	s_mov_b32 s0, 1
	v_writelane_b32 v255, s0, 50
	v_readlane_b32 s0, v254, 63
	s_cmp_ge_u32 s0, 4
	s_cbranch_scc0 .Lattn_prio_done
	s_setprio 1
.Lattn_prio_done:
	s_cmpk_eq_i32 s75, 0x100
	s_cselect_b64 s[70:71], -1, 0
	s_add_u32 s34, s94, 0x6900000
	s_addc_u32 s35, s95, 0
	s_add_u32 s42, s94, 0x7a00000
	s_addc_u32 s43, s95, 0
	s_add_u32 s44, s94, 0x8b00000
	v_mov_b32_e32 v1, 0x3e800000
	s_mov_b32 s12, 0xffff0000
	s_addc_u32 s45, s95, 0
	v_fmac_f32_e32 v1, 0x3f8147ae, v2
	s_mov_b32 s46, 0xc2fc0000
	s_mov_b32 s5, 0
	v_mov_b32_e32 v183, 0x42800000
	v_mov_b32_e32 v184, 0x3fb8aa3b
	v_mov_b32_e32 v177, 0
	s_mov_b64 s[6:7], 0x10000
	s_mov_b64 s[8:9], 0x20000
	s_mov_b64 s[10:11], 0x30000
	s_mov_b32 s13, -1
	v_mov_b32_e32 v185, 0xff800000
	s_mov_b32 s47, s96
	s_branch .LBB0_425

; __global__ void __launch_bounds__(512, 2) mk_fwd(Args a) {
;     ...
;             }
;         }
.LBB0_479:
	s_setprio 0
	v_mov_b32_e32 v1, v182

; #define PG8_STAGE(bufoff, gbase, voff) do { _Pragma("unroll") for (int _i = 0; _i < 2; ++_i) \
;         __builtin_amdgcn_global_load_lds((const unsigned*)((const char*)(gbase) + (voff)[_i]), (PG8_LAS unsigned*)(lds + (bufoff) + ldsw + _i * 8192), 16, 0, 0); } while (0)
; #define PG8_LDA(dst, b, h) do { _Pragma("unroll") for (int m = 0; m < 4; ++m) _Pragma("unroll") for (int k = 0; k < 2; ++k) dst[m][k] = *(const PG8_LAS bf16x8*)(lds + PG8_SA(b, h) + aoff + m * 2048 + k * 1024); } while (0)
; #define PG8_LDB(dst, b, h) do { _Pragma("unroll") for (int n = 0; n < 2; ++n) _Pragma("unroll") for (int k = 0; k < 2; ++k) dst[n][k] = *(const PG8_LAS bf16x8*)(lds + PG8_SB(b, h) + boff + n * 2048 + k * 1024); } while (0)
; #define PG8_MMA(ai, bj, At, Bt) do { __builtin_amdgcn_s_setprio(1); _Pragma("unroll") for (int m = 0; m < 4; ++m) _Pragma("unroll") for (int n = 0; n < 2; ++n) _Pragma("unroll") for (int k = 0; k < 2; ++k) \
;         acc[ai][bj][m][n] = __builtin_amdgcn_mfma_f32_16x16x32_bf16(Bt[n][k], At[m][k], acc[ai][bj][m][n], 0, 0, 0); __builtin_amdgcn_s_setprio(0); } while (0)
; #define PG8_WAIT_V(n) asm volatile("s_waitcnt vmcnt(" #n ")" ::: "memory")
; template <class Epi, class Sched, bool ALIGN_EPI = false, bool SP2 = false>
; __device__ __forceinline__ void gemm_phase(PG8_LAS unsigned char* lds, const Gemm g, const Sched& S, const Epi& E) {
;     ...
;             PG8_LDB(B0, 0, 0); PG8_LDB(B1, 0, 1); PG8_SCHED; PG8_LDA(At, 0, 0); PG8_STAGE(PG8_SA(1, 1), a1 + ahstep, voffA);
;             PG8_WAIT_V(8); PG8_WAIT_L(0); PG8_BAR; PG8_MMA(0, 0, At, B0); PG8_MMA(0, 1, At, B1); PG8_BAR; PG8_SCHED;
;             PG8_LDA(At, 0, 1); PG8_STAGE(PG8_SB(0, 0), b2, voffB); PG8_STAGE(PG8_SB(0, 1), b2 + hstep, voffB); PG8_STAGE(PG8_SA(0, 0), a2, voffA);
;             PG8_WAIT_V(8); PG8_WAIT_L(0); PG8_BAR; PG8_MMA(1, 0, At, B0); PG8_MMA(1, 1, At, B1); PG8_BAR; PG8_SCHED;
;             PG8_LDB(B0, 1, 0); PG8_LDB(B1, 1, 1); PG8_SCHED; PG8_LDA(At, 1, 0); PG8_STAGE(PG8_SA(0, 1), a2 + ahstep, voffA);
;             PG8_WAIT_V(8); PG8_WAIT_L(0); PG8_BAR; PG8_MMA(0, 0, At, B0); PG8_MMA(0, 1, At, B1); PG8_BAR; PG8_SCHED;
;             PG8_LDA(At, 1, 1); PG8_STAGE(PG8_SB(1, 0), b3, voffB); PG8_STAGE(PG8_SB(1, 1), b3 + hstep, voffB); PG8_STAGE(PG8_SA(1, 0), a3, voffA);
;             PG8_WAIT_V(8); PG8_WAIT_L(0); PG8_BAR; PG8_MMA(1, 0, At, B0); PG8_MMA(1, 1, At, B1); PG8_BAR; PG8_SCHED;
.LBB0_599:
	ds_read_b128 v[130:133], v158
	ds_read_b128 v[150:153], v158 offset:1024
	ds_read_b128 v[162:165], v158 offset:2048
	ds_read_b128 v[166:169], v158 offset:3072
	ds_read_b128 v[170:173], v159
	ds_read_b128 v[174:177], v159 offset:1024
	ds_read_b128 v[178:181], v159 offset:2048
	ds_read_b128 v[182:185], v159 offset:3072
	s_add_u32 s6, s4, 0xfffe0080
	s_addc_u32 s7, s5, -1
	s_cmp_eq_u32 s53, 4
	s_cselect_b32 s27, s21, s7
	s_cselect_b32 s26, s33, s6
	s_cselect_b32 s7, s19, s52
	s_cselect_b32 s6, s50, s51
	v_lshl_add_u64 v[218:219], s[4:5], 0, v[142:143]
	s_add_i32 m0, s34, 0xc000
	ds_read_b128 v[186:189], v160
	ds_read_b128 v[190:193], v160 offset:1024
	ds_read_b128 v[194:197], v160 offset:2048
	ds_read_b128 v[198:201], v160 offset:3072
	ds_read_b128 v[202:205], v160 offset:4096
	ds_read_b128 v[206:209], v160 offset:5120
	ds_read_b128 v[210:213], v160 offset:6144
	ds_read_b128 v[214:217], v160 offset:7168
	global_load_lds_dwordx4 v[218:219], off
	v_lshl_add_u64 v[218:219], s[4:5], 0, v[144:145]
	s_add_i32 m0, s34, 0xe000
	s_nop 0
	global_load_lds_dwordx4 v[218:219], off
	s_waitcnt vmcnt(8)
	s_waitcnt lgkmcnt(0)
	s_barrier
	s_setprio 1
	s_waitcnt lgkmcnt(0)
	v_mfma_f32_16x16x32_bf16 v[126:129], v[130:133], v[186:189], v[126:129]
	v_mfma_f32_16x16x32_bf16 v[122:125], v[162:165], v[186:189], v[122:125]
	v_mfma_f32_16x16x32_bf16 v[110:113], v[130:133], v[194:197], v[110:113]
	v_mfma_f32_16x16x32_bf16 v[106:109], v[162:165], v[194:197], v[106:109]
	v_mfma_f32_16x16x32_bf16 v[94:97], v[130:133], v[202:205], v[94:97]
	v_mfma_f32_16x16x32_bf16 v[90:93], v[162:165], v[202:205], v[90:93]
	v_mfma_f32_16x16x32_bf16 v[78:81], v[130:133], v[210:213], v[78:81]
	v_mfma_f32_16x16x32_bf16 v[74:77], v[162:165], v[210:213], v[74:77]
	v_mfma_f32_16x16x32_bf16 v[126:129], v[150:153], v[190:193], v[126:129]
	v_mfma_f32_16x16x32_bf16 v[122:125], v[166:169], v[190:193], v[122:125]
	v_mfma_f32_16x16x32_bf16 v[110:113], v[150:153], v[198:201], v[110:113]
	v_mfma_f32_16x16x32_bf16 v[106:109], v[166:169], v[198:201], v[106:109]
	v_mfma_f32_16x16x32_bf16 v[94:97], v[150:153], v[206:209], v[94:97]
	v_mfma_f32_16x16x32_bf16 v[90:93], v[166:169], v[206:209], v[90:93]
	v_mfma_f32_16x16x32_bf16 v[78:81], v[150:153], v[214:217], v[78:81]
	v_mfma_f32_16x16x32_bf16 v[74:77], v[166:169], v[214:217], v[74:77]
	v_mfma_f32_16x16x32_bf16 v[118:121], v[170:173], v[186:189], v[118:121]
	v_mfma_f32_16x16x32_bf16 v[114:117], v[178:181], v[186:189], v[114:117]
	v_mfma_f32_16x16x32_bf16 v[102:105], v[170:173], v[194:197], v[102:105]
	v_mfma_f32_16x16x32_bf16 v[98:101], v[178:181], v[194:197], v[98:101]
	v_mfma_f32_16x16x32_bf16 v[86:89], v[170:173], v[202:205], v[86:89]
	v_mfma_f32_16x16x32_bf16 v[82:85], v[178:181], v[202:205], v[82:85]
	v_mfma_f32_16x16x32_bf16 v[70:73], v[170:173], v[210:213], v[70:73]
	v_mfma_f32_16x16x32_bf16 v[66:69], v[178:181], v[210:213], v[66:69]
	v_mfma_f32_16x16x32_bf16 v[118:121], v[174:177], v[190:193], v[118:121]
	v_mfma_f32_16x16x32_bf16 v[114:117], v[182:185], v[190:193], v[114:117]
	v_mfma_f32_16x16x32_bf16 v[102:105], v[174:177], v[198:201], v[102:105]
	v_mfma_f32_16x16x32_bf16 v[98:101], v[182:185], v[198:201], v[98:101]
	v_mfma_f32_16x16x32_bf16 v[86:89], v[174:177], v[206:209], v[86:89]
	v_mfma_f32_16x16x32_bf16 v[82:85], v[182:185], v[206:209], v[82:85]
	v_mfma_f32_16x16x32_bf16 v[70:73], v[174:177], v[214:217], v[70:73]
	v_mfma_f32_16x16x32_bf16 v[66:69], v[182:185], v[214:217], v[66:69]
	s_setprio 0
	s_barrier
	s_add_i32 s54, s48, s31
	v_lshl_add_u64 v[218:219], s[6:7], 0, v[136:137]
	s_mov_b32 m0, s54
	ds_read_b128 v[186:189], v160 offset:16384
	ds_read_b128 v[190:193], v160 offset:17408
	ds_read_b128 v[194:197], v160 offset:18432
	ds_read_b128 v[198:201], v160 offset:19456
	ds_read_b128 v[202:205], v160 offset:20480
	ds_read_b128 v[206:209], v160 offset:21504
	ds_read_b128 v[210:213], v160 offset:22528
	ds_read_b128 v[214:217], v160 offset:23552
	global_load_lds_dwordx4 v[218:219], off
	s_add_i32 m0, s54, 0x2000
	s_add_u32 s54, s6, 0x20000
	v_lshl_add_u64 v[220:221], s[6:7], 0, v[140:141]
	s_addc_u32 s55, s7, 0
	s_add_i32 s56, s49, s31
	global_load_lds_dwordx4 v[220:221], off
	v_lshl_add_u64 v[222:223], s[54:55], 0, v[136:137]
	s_mov_b32 m0, s56
	v_lshl_add_u64 v[224:225], s[26:27], 0, v[138:139]
	global_load_lds_dwordx4 v[222:223], off
	v_lshl_add_u64 v[222:223], s[54:55], 0, v[140:141]
	s_add_i32 m0, s56, 0x2000
	s_nop 0
	global_load_lds_dwordx4 v[222:223], off
	v_lshl_add_u64 v[222:223], s[26:27], 0, v[134:135]
	s_mov_b32 m0, s34
	s_nop 0
	global_load_lds_dwordx4 v[222:223], off
	s_mov_b32 m0, s35
	s_nop 0
	global_load_lds_dwordx4 v[224:225], off
	s_waitcnt vmcnt(8)
	s_waitcnt lgkmcnt(0)
	s_barrier
; #define PG8_STAGE(bufoff, gbase, voff) do { _Pragma("unroll") for (int _i = 0; _i < 2; ++_i) \
;         __builtin_amdgcn_global_load_lds((const unsigned*)((const char*)(gbase) + (voff)[_i]), (PG8_LAS unsigned*)(lds + (bufoff) + ldsw + _i * 8192), 16, 0, 0); } while (0)
; #define PG8_LDA(dst, b, h) do { _Pragma("unroll") for (int m = 0; m < 4; ++m) _Pragma("unroll") for (int k = 0; k < 2; ++k) dst[m][k] = *(const PG8_LAS bf16x8*)(lds + PG8_SA(b, h) + aoff + m * 2048 + k * 1024); } while (0)
; #define PG8_LDB(dst, b, h) do { _Pragma("unroll") for (int n = 0; n < 2; ++n) _Pragma("unroll") for (int k = 0; k < 2; ++k) dst[n][k] = *(const PG8_LAS bf16x8*)(lds + PG8_SB(b, h) + boff + n * 2048 + k * 1024); } while (0)
; #define PG8_MMA(ai, bj, At, Bt) do { __builtin_amdgcn_s_setprio(1); _Pragma("unroll") for (int m = 0; m < 4; ++m) _Pragma("unroll") for (int n = 0; n < 2; ++n) _Pragma("unroll") for (int k = 0; k < 2; ++k) \
;         acc[ai][bj][m][n] = __builtin_amdgcn_mfma_f32_16x16x32_bf16(Bt[n][k], At[m][k], acc[ai][bj][m][n], 0, 0, 0); __builtin_amdgcn_s_setprio(0); } while (0)
; #define PG8_WAIT_V(n) asm volatile("s_waitcnt vmcnt(" #n ")" ::: "memory")
; template <class Epi, class Sched, bool ALIGN_EPI = false, bool SP2 = false>
; __device__ __forceinline__ void gemm_phase(PG8_LAS unsigned char* lds, const Gemm g, const Sched& S, const Epi& E) {
;     ...
;             PG8_LDB(B0, 0, 0); PG8_LDB(B1, 0, 1); PG8_SCHED; PG8_LDA(At, 0, 0); PG8_STAGE(PG8_SA(1, 1), a1 + ahstep, voffA);
;             PG8_WAIT_V(8); PG8_WAIT_L(0); PG8_BAR; PG8_MMA(0, 0, At, B0); PG8_MMA(0, 1, At, B1); PG8_BAR; PG8_SCHED;
;             PG8_LDA(At, 0, 1); PG8_STAGE(PG8_SB(0, 0), b2, voffB); PG8_STAGE(PG8_SB(0, 1), b2 + hstep, voffB); PG8_STAGE(PG8_SA(0, 0), a2, voffA);
;             PG8_WAIT_V(8); PG8_WAIT_L(0); PG8_BAR; PG8_MMA(1, 0, At, B0); PG8_MMA(1, 1, At, B1); PG8_BAR; PG8_SCHED;
;             PG8_LDB(B0, 1, 0); PG8_LDB(B1, 1, 1); PG8_SCHED; PG8_LDA(At, 1, 0); PG8_STAGE(PG8_SA(0, 1), a2 + ahstep, voffA);
;             PG8_WAIT_V(8); PG8_WAIT_L(0); PG8_BAR; PG8_MMA(0, 0, At, B0); PG8_MMA(0, 1, At, B1); PG8_BAR; PG8_SCHED;
;             PG8_LDA(At, 1, 1); PG8_STAGE(PG8_SB(1, 0), b3, voffB); PG8_STAGE(PG8_SB(1, 1), b3 + hstep, voffB); PG8_STAGE(PG8_SA(1, 0), a3, voffA);
;             PG8_WAIT_V(8); PG8_WAIT_L(0); PG8_BAR; PG8_MMA(1, 0, At, B0); PG8_MMA(1, 1, At, B1); PG8_BAR; PG8_SCHED;
	s_setprio 1
	s_waitcnt lgkmcnt(0)
	v_mfma_f32_16x16x32_bf16 v[62:65], v[130:133], v[186:189], v[62:65]
	v_mfma_f32_16x16x32_bf16 v[58:61], v[162:165], v[186:189], v[58:61]
	v_mfma_f32_16x16x32_bf16 v[46:49], v[130:133], v[194:197], v[46:49]
	v_mfma_f32_16x16x32_bf16 v[42:45], v[162:165], v[194:197], v[42:45]
	v_mfma_f32_16x16x32_bf16 v[30:33], v[130:133], v[202:205], v[30:33]
	v_mfma_f32_16x16x32_bf16 v[26:29], v[162:165], v[202:205], v[26:29]
	v_mfma_f32_16x16x32_bf16 v[14:17], v[130:133], v[210:213], v[14:17]
	v_mfma_f32_16x16x32_bf16 v[10:13], v[162:165], v[210:213], v[10:13]
	v_mfma_f32_16x16x32_bf16 v[62:65], v[150:153], v[190:193], v[62:65]
	v_mfma_f32_16x16x32_bf16 v[58:61], v[166:169], v[190:193], v[58:61]
	v_mfma_f32_16x16x32_bf16 v[46:49], v[150:153], v[198:201], v[46:49]
	v_mfma_f32_16x16x32_bf16 v[42:45], v[166:169], v[198:201], v[42:45]
	v_mfma_f32_16x16x32_bf16 v[30:33], v[150:153], v[206:209], v[30:33]
	v_mfma_f32_16x16x32_bf16 v[26:29], v[166:169], v[206:209], v[26:29]
	v_mfma_f32_16x16x32_bf16 v[14:17], v[150:153], v[214:217], v[14:17]
	v_mfma_f32_16x16x32_bf16 v[10:13], v[166:169], v[214:217], v[10:13]
	v_mfma_f32_16x16x32_bf16 v[54:57], v[170:173], v[186:189], v[54:57]
	v_mfma_f32_16x16x32_bf16 v[50:53], v[178:181], v[186:189], v[50:53]
	v_mfma_f32_16x16x32_bf16 v[38:41], v[170:173], v[194:197], v[38:41]
	v_mfma_f32_16x16x32_bf16 v[34:37], v[178:181], v[194:197], v[34:37]
	v_mfma_f32_16x16x32_bf16 v[22:25], v[170:173], v[202:205], v[22:25]
	v_mfma_f32_16x16x32_bf16 v[18:21], v[178:181], v[202:205], v[18:21]
	v_mfma_f32_16x16x32_bf16 v[6:9], v[170:173], v[210:213], v[6:9]
	v_mfma_f32_16x16x32_bf16 v[2:5], v[178:181], v[210:213], v[2:5]
	v_mfma_f32_16x16x32_bf16 v[54:57], v[174:177], v[190:193], v[54:57]
	v_mfma_f32_16x16x32_bf16 v[50:53], v[182:185], v[190:193], v[50:53]
	v_mfma_f32_16x16x32_bf16 v[38:41], v[174:177], v[198:201], v[38:41]
	v_mfma_f32_16x16x32_bf16 v[34:37], v[182:185], v[198:201], v[34:37]
	v_mfma_f32_16x16x32_bf16 v[22:25], v[174:177], v[206:209], v[22:25]
	v_mfma_f32_16x16x32_bf16 v[18:21], v[182:185], v[206:209], v[18:21]
	v_mfma_f32_16x16x32_bf16 v[6:9], v[174:177], v[214:217], v[6:9]
	v_mfma_f32_16x16x32_bf16 v[2:5], v[182:185], v[214:217], v[2:5]
	s_setprio 0
	s_barrier
	s_add_i32 s54, 0, 0x18000
	v_add_u32_e32 v161, s54, v156
	s_add_i32 s55, 0, 0x1c000
	ds_read_b128 v[130:133], v161
	ds_read_b128 v[150:153], v161 offset:1024
	ds_read_b128 v[162:165], v161 offset:2048
	ds_read_b128 v[166:169], v161 offset:3072
	v_add_u32_e32 v161, s55, v156
	ds_read_b128 v[170:173], v161
	ds_read_b128 v[174:177], v161 offset:1024
	ds_read_b128 v[178:181], v161 offset:2048
	ds_read_b128 v[182:185], v161 offset:3072
	s_add_u32 s26, s26, 0x20000
	s_addc_u32 s27, s27, 0
	s_mov_b32 m0, s42
	v_lshl_add_u64 v[226:227], s[26:27], 0, v[134:135]
	ds_read_b128 v[186:189], v160 offset:32768
	ds_read_b128 v[190:193], v160 offset:33792
	ds_read_b128 v[194:197], v160 offset:34816
	ds_read_b128 v[198:201], v160 offset:35840
	ds_read_b128 v[202:205], v160 offset:36864
	ds_read_b128 v[206:209], v160 offset:37888
	ds_read_b128 v[210:213], v160 offset:38912
	ds_read_b128 v[214:217], v160 offset:39936
	global_load_lds_dwordx4 v[226:227], off
	v_lshl_add_u64 v[226:227], s[26:27], 0, v[138:139]
	s_mov_b32 m0, s43
	s_nop 0
	global_load_lds_dwordx4 v[226:227], off
	s_waitcnt vmcnt(8)
	s_waitcnt lgkmcnt(0)
	s_barrier
	s_setprio 1
	s_waitcnt lgkmcnt(0)
	v_mfma_f32_16x16x32_bf16 v[126:129], v[130:133], v[186:189], v[126:129]
	v_mfma_f32_16x16x32_bf16 v[122:125], v[162:165], v[186:189], v[122:125]
	v_mfma_f32_16x16x32_bf16 v[110:113], v[130:133], v[194:197], v[110:113]
	v_mfma_f32_16x16x32_bf16 v[106:109], v[162:165], v[194:197], v[106:109]
	v_mfma_f32_16x16x32_bf16 v[94:97], v[130:133], v[202:205], v[94:97]
	v_mfma_f32_16x16x32_bf16 v[90:93], v[162:165], v[202:205], v[90:93]
	v_mfma_f32_16x16x32_bf16 v[78:81], v[130:133], v[210:213], v[78:81]
	v_mfma_f32_16x16x32_bf16 v[74:77], v[162:165], v[210:213], v[74:77]
	v_mfma_f32_16x16x32_bf16 v[126:129], v[150:153], v[190:193], v[126:129]
	v_mfma_f32_16x16x32_bf16 v[122:125], v[166:169], v[190:193], v[122:125]
	v_mfma_f32_16x16x32_bf16 v[110:113], v[150:153], v[198:201], v[110:113]
	v_mfma_f32_16x16x32_bf16 v[106:109], v[166:169], v[198:201], v[106:109]
	v_mfma_f32_16x16x32_bf16 v[94:97], v[150:153], v[206:209], v[94:97]
	v_mfma_f32_16x16x32_bf16 v[90:93], v[166:169], v[206:209], v[90:93]
	v_mfma_f32_16x16x32_bf16 v[78:81], v[150:153], v[214:217], v[78:81]
	v_mfma_f32_16x16x32_bf16 v[74:77], v[166:169], v[214:217], v[74:77]
	v_mfma_f32_16x16x32_bf16 v[118:121], v[170:173], v[186:189], v[118:121]
	v_mfma_f32_16x16x32_bf16 v[114:117], v[178:181], v[186:189], v[114:117]
	v_mfma_f32_16x16x32_bf16 v[102:105], v[170:173], v[194:197], v[102:105]
	v_mfma_f32_16x16x32_bf16 v[98:101], v[178:181], v[194:197], v[98:101]
	v_mfma_f32_16x16x32_bf16 v[86:89], v[170:173], v[202:205], v[86:89]
	v_mfma_f32_16x16x32_bf16 v[82:85], v[178:181], v[202:205], v[82:85]
	v_mfma_f32_16x16x32_bf16 v[70:73], v[170:173], v[210:213], v[70:73]
	v_mfma_f32_16x16x32_bf16 v[66:69], v[178:181], v[210:213], v[66:69]
	v_mfma_f32_16x16x32_bf16 v[118:121], v[174:177], v[190:193], v[118:121]
	v_mfma_f32_16x16x32_bf16 v[114:117], v[182:185], v[190:193], v[114:117]
	v_mfma_f32_16x16x32_bf16 v[102:105], v[174:177], v[198:201], v[102:105]
	v_mfma_f32_16x16x32_bf16 v[98:101], v[182:185], v[198:201], v[98:101]
	v_mfma_f32_16x16x32_bf16 v[86:89], v[174:177], v[206:209], v[86:89]
	v_mfma_f32_16x16x32_bf16 v[82:85], v[182:185], v[206:209], v[82:85]
	v_mfma_f32_16x16x32_bf16 v[70:73], v[174:177], v[214:217], v[70:73]
	v_mfma_f32_16x16x32_bf16 v[66:69], v[182:185], v[214:217], v[66:69]
	s_setprio 0
	s_barrier
; #define PG8_STAGE(bufoff, gbase, voff) do { _Pragma("unroll") for (int _i = 0; _i < 2; ++_i) \
;         __builtin_amdgcn_global_load_lds((const unsigned*)((const char*)(gbase) + (voff)[_i]), (PG8_LAS unsigned*)(lds + (bufoff) + ldsw + _i * 8192), 16, 0, 0); } while (0)
; #define PG8_LDA(dst, b, h) do { _Pragma("unroll") for (int m = 0; m < 4; ++m) _Pragma("unroll") for (int k = 0; k < 2; ++k) dst[m][k] = *(const PG8_LAS bf16x8*)(lds + PG8_SA(b, h) + aoff + m * 2048 + k * 1024); } while (0)
; #define PG8_LDB(dst, b, h) do { _Pragma("unroll") for (int n = 0; n < 2; ++n) _Pragma("unroll") for (int k = 0; k < 2; ++k) dst[n][k] = *(const PG8_LAS bf16x8*)(lds + PG8_SB(b, h) + boff + n * 2048 + k * 1024); } while (0)
; #define PG8_MMA(ai, bj, At, Bt) do { __builtin_amdgcn_s_setprio(1); _Pragma("unroll") for (int m = 0; m < 4; ++m) _Pragma("unroll") for (int n = 0; n < 2; ++n) _Pragma("unroll") for (int k = 0; k < 2; ++k) \
;         acc[ai][bj][m][n] = __builtin_amdgcn_mfma_f32_16x16x32_bf16(Bt[n][k], At[m][k], acc[ai][bj][m][n], 0, 0, 0); __builtin_amdgcn_s_setprio(0); } while (0)
; #define PG8_WAIT_V(n) asm volatile("s_waitcnt vmcnt(" #n ")" ::: "memory")
; template <class Epi, class Sched, bool ALIGN_EPI = false, bool SP2 = false>
; __device__ __forceinline__ void gemm_phase(PG8_LAS unsigned char* lds, const Gemm g, const Sched& S, const Epi& E) {
;     ...
;             PG8_LDB(B0, 0, 0); PG8_LDB(B1, 0, 1); PG8_SCHED; PG8_LDA(At, 0, 0); PG8_STAGE(PG8_SA(1, 1), a1 + ahstep, voffA);
;             PG8_WAIT_V(8); PG8_WAIT_L(0); PG8_BAR; PG8_MMA(0, 0, At, B0); PG8_MMA(0, 1, At, B1); PG8_BAR; PG8_SCHED;
;             PG8_LDA(At, 0, 1); PG8_STAGE(PG8_SB(0, 0), b2, voffB); PG8_STAGE(PG8_SB(0, 1), b2 + hstep, voffB); PG8_STAGE(PG8_SA(0, 0), a2, voffA);
;             PG8_WAIT_V(8); PG8_WAIT_L(0); PG8_BAR; PG8_MMA(1, 0, At, B0); PG8_MMA(1, 1, At, B1); PG8_BAR; PG8_SCHED;
;             PG8_LDB(B0, 1, 0); PG8_LDB(B1, 1, 1); PG8_SCHED; PG8_LDA(At, 1, 0); PG8_STAGE(PG8_SA(0, 1), a2 + ahstep, voffA);
;             PG8_WAIT_V(8); PG8_WAIT_L(0); PG8_BAR; PG8_MMA(0, 0, At, B0); PG8_MMA(0, 1, At, B1); PG8_BAR; PG8_SCHED;
;             PG8_LDA(At, 1, 1); PG8_STAGE(PG8_SB(1, 0), b3, voffB); PG8_STAGE(PG8_SB(1, 1), b3 + hstep, voffB); PG8_STAGE(PG8_SA(1, 0), a3, voffA);
;             PG8_WAIT_V(8); PG8_WAIT_L(0); PG8_BAR; PG8_MMA(1, 0, At, B0); PG8_MMA(1, 1, At, B1); PG8_BAR; PG8_SCHED;
	s_add_i32 s26, s54, s31
	v_lshl_add_u64 v[218:219], v[218:219], 0, s[10:11]
	s_mov_b32 m0, s26
	ds_read_b128 v[186:189], v160 offset:49152
	ds_read_b128 v[190:193], v160 offset:50176
	ds_read_b128 v[194:197], v160 offset:51200
	ds_read_b128 v[198:201], v160 offset:52224
	ds_read_b128 v[202:205], v160 offset:53248
	ds_read_b128 v[206:209], v160 offset:54272
	ds_read_b128 v[210:213], v160 offset:55296
	ds_read_b128 v[214:217], v160 offset:56320
	global_load_lds_dwordx4 v[218:219], off
	s_add_i32 m0, s26, 0x2000
	s_add_u32 s6, s6, 0x20080
	v_lshl_add_u64 v[218:219], v[220:221], 0, s[10:11]
	s_addc_u32 s7, s7, 0
	s_add_i32 s26, s55, s31
	global_load_lds_dwordx4 v[218:219], off
	v_lshl_add_u64 v[218:219], s[6:7], 0, v[136:137]
	s_mov_b32 m0, s26
	s_nop 0
	global_load_lds_dwordx4 v[218:219], off
	v_lshl_add_u64 v[218:219], s[6:7], 0, v[140:141]
	s_add_i32 m0, s26, 0x2000
	s_nop 0
	global_load_lds_dwordx4 v[218:219], off
	v_lshl_add_u64 v[218:219], v[222:223], 0, s[10:11]
	s_mov_b32 m0, s45
	s_nop 0
	global_load_lds_dwordx4 v[218:219], off
	v_lshl_add_u64 v[218:219], v[224:225], 0, s[10:11]
	s_mov_b32 m0, s46
	s_nop 0
	global_load_lds_dwordx4 v[218:219], off
	s_waitcnt vmcnt(8)
	s_waitcnt lgkmcnt(0)
	s_barrier
	s_setprio 1
	s_waitcnt lgkmcnt(0)
	v_mfma_f32_16x16x32_bf16 v[62:65], v[130:133], v[186:189], v[62:65]
	v_mfma_f32_16x16x32_bf16 v[58:61], v[162:165], v[186:189], v[58:61]
	v_mfma_f32_16x16x32_bf16 v[46:49], v[130:133], v[194:197], v[46:49]
	v_mfma_f32_16x16x32_bf16 v[42:45], v[162:165], v[194:197], v[42:45]
	v_mfma_f32_16x16x32_bf16 v[30:33], v[130:133], v[202:205], v[30:33]
	v_mfma_f32_16x16x32_bf16 v[26:29], v[162:165], v[202:205], v[26:29]
	v_mfma_f32_16x16x32_bf16 v[14:17], v[130:133], v[210:213], v[14:17]
	v_mfma_f32_16x16x32_bf16 v[10:13], v[162:165], v[210:213], v[10:13]
	v_mfma_f32_16x16x32_bf16 v[62:65], v[150:153], v[190:193], v[62:65]
	v_mfma_f32_16x16x32_bf16 v[58:61], v[166:169], v[190:193], v[58:61]
	v_mfma_f32_16x16x32_bf16 v[46:49], v[150:153], v[198:201], v[46:49]
	v_mfma_f32_16x16x32_bf16 v[42:45], v[166:169], v[198:201], v[42:45]
	v_mfma_f32_16x16x32_bf16 v[30:33], v[150:153], v[206:209], v[30:33]
	v_mfma_f32_16x16x32_bf16 v[26:29], v[166:169], v[206:209], v[26:29]
	v_mfma_f32_16x16x32_bf16 v[14:17], v[150:153], v[214:217], v[14:17]
	v_mfma_f32_16x16x32_bf16 v[10:13], v[166:169], v[214:217], v[10:13]
	v_mfma_f32_16x16x32_bf16 v[54:57], v[170:173], v[186:189], v[54:57]
	v_mfma_f32_16x16x32_bf16 v[50:53], v[178:181], v[186:189], v[50:53]
	v_mfma_f32_16x16x32_bf16 v[38:41], v[170:173], v[194:197], v[38:41]
	v_mfma_f32_16x16x32_bf16 v[34:37], v[178:181], v[194:197], v[34:37]
	v_mfma_f32_16x16x32_bf16 v[22:25], v[170:173], v[202:205], v[22:25]
	v_mfma_f32_16x16x32_bf16 v[18:21], v[178:181], v[202:205], v[18:21]
	v_mfma_f32_16x16x32_bf16 v[6:9], v[170:173], v[210:213], v[6:9]
	v_mfma_f32_16x16x32_bf16 v[2:5], v[178:181], v[210:213], v[2:5]
	v_mfma_f32_16x16x32_bf16 v[54:57], v[174:177], v[190:193], v[54:57]
	v_mfma_f32_16x16x32_bf16 v[50:53], v[182:185], v[190:193], v[50:53]
	v_mfma_f32_16x16x32_bf16 v[38:41], v[174:177], v[198:201], v[38:41]
	v_mfma_f32_16x16x32_bf16 v[34:37], v[182:185], v[198:201], v[34:37]
	v_mfma_f32_16x16x32_bf16 v[22:25], v[174:177], v[206:209], v[22:25]
	v_mfma_f32_16x16x32_bf16 v[18:21], v[182:185], v[206:209], v[18:21]
	v_mfma_f32_16x16x32_bf16 v[6:9], v[174:177], v[214:217], v[6:9]
	v_mfma_f32_16x16x32_bf16 v[2:5], v[182:185], v[214:217], v[2:5]
	s_setprio 0
	s_barrier
	s_add_i32 s53, s53, 2
	s_add_u32 s4, s4, 0x100
	s_addc_u32 s5, s5, 0
	s_add_u32 s51, s51, 0x100
	s_addc_u32 s52, s52, 0
	s_cmp_gt_u32 s53, 5
	s_cbranch_scc0 .LBB0_599
	s_and_b64 vcc, exec, s[12:13]
	s_cbranch_vccz .LBB0_602
	s_barrier

; #define PG8_STAGE(bufoff, gbase, voff) do { _Pragma("unroll") for (int _i = 0; _i < 2; ++_i) \
;         __builtin_amdgcn_global_load_lds((const unsigned*)((const char*)(gbase) + (voff)[_i]), (PG8_LAS unsigned*)(lds + (bufoff) + ldsw + _i * 8192), 16, 0, 0); } while (0)
; #define PG8_LDA(dst, b, h) do { _Pragma("unroll") for (int m = 0; m < 4; ++m) _Pragma("unroll") for (int k = 0; k < 2; ++k) dst[m][k] = *(const PG8_LAS bf16x8*)(lds + PG8_SA(b, h) + aoff + m * 2048 + k * 1024); } while (0)
; #define PG8_LDB(dst, b, h) do { _Pragma("unroll") for (int n = 0; n < 2; ++n) _Pragma("unroll") for (int k = 0; k < 2; ++k) dst[n][k] = *(const PG8_LAS bf16x8*)(lds + PG8_SB(b, h) + boff + n * 2048 + k * 1024); } while (0)
; #define PG8_MMA(ai, bj, At, Bt) do { __builtin_amdgcn_s_setprio(1); _Pragma("unroll") for (int m = 0; m < 4; ++m) _Pragma("unroll") for (int n = 0; n < 2; ++n) _Pragma("unroll") for (int k = 0; k < 2; ++k) \
;         acc[ai][bj][m][n] = __builtin_amdgcn_mfma_f32_16x16x32_bf16(Bt[n][k], At[m][k], acc[ai][bj][m][n], 0, 0, 0); __builtin_amdgcn_s_setprio(0); } while (0)
; #define PG8_WAIT_V(n) asm volatile("s_waitcnt vmcnt(" #n ")" ::: "memory")
; template <class Epi, class Sched, bool ALIGN_EPI = false, bool SP2 = false>
; __device__ __forceinline__ void gemm_phase(PG8_LAS unsigned char* lds, const Gemm g, const Sched& S, const Epi& E) {
;     ...
;             PG8_LDB(B0, 0, 0); PG8_LDB(B1, 0, 1); PG8_SCHED; PG8_LDA(At, 0, 0); PG8_STAGE(PG8_SA(1, 1), a1 + ahstep, voffA);
;             PG8_WAIT_V(8); PG8_WAIT_L(0); PG8_BAR; PG8_MMA(0, 0, At, B0); PG8_MMA(0, 1, At, B1); PG8_BAR; PG8_SCHED;
;             PG8_LDA(At, 0, 1); PG8_STAGE(PG8_SB(0, 0), b2, voffB); PG8_STAGE(PG8_SB(0, 1), b2 + hstep, voffB); PG8_STAGE(PG8_SA(0, 0), a2, voffA);
;             PG8_WAIT_V(8); PG8_WAIT_L(0); PG8_BAR; PG8_MMA(1, 0, At, B0); PG8_MMA(1, 1, At, B1); PG8_BAR; PG8_SCHED;
;             PG8_LDB(B0, 1, 0); PG8_LDB(B1, 1, 1); PG8_SCHED; PG8_LDA(At, 1, 0); PG8_STAGE(PG8_SA(0, 1), a2 + ahstep, voffA);
;             PG8_WAIT_V(8); PG8_WAIT_L(0); PG8_BAR; PG8_MMA(0, 0, At, B0); PG8_MMA(0, 1, At, B1); PG8_BAR; PG8_SCHED;
;             PG8_LDA(At, 1, 1); PG8_STAGE(PG8_SB(1, 0), b3, voffB); PG8_STAGE(PG8_SB(1, 1), b3 + hstep, voffB); PG8_STAGE(PG8_SA(1, 0), a3, voffA);
;             PG8_WAIT_V(8); PG8_WAIT_L(0); PG8_BAR; PG8_MMA(1, 0, At, B0); PG8_MMA(1, 1, At, B1); PG8_BAR; PG8_SCHED;
.LBB0_693:
	ds_read_b128 v[130:133], v208
	ds_read_b128 v[134:137], v208 offset:1024
	ds_read_b128 v[138:141], v208 offset:2048
	ds_read_b128 v[142:145], v208 offset:3072
	ds_read_b128 v[146:149], v209
	ds_read_b128 v[150:153], v209 offset:1024
	ds_read_b128 v[154:157], v209 offset:2048
	ds_read_b128 v[158:161], v209 offset:3072
	s_add_u32 s28, s26, 0xfffc0080
	s_addc_u32 s29, s27, -1
	s_cmp_eq_u32 s59, 12
	s_cselect_b32 s31, s19, s29
	s_cselect_b32 s30, s25, s28
	s_cselect_b32 s29, s17, s58
	s_cselect_b32 s28, s56, s57
	v_lshl_add_u64 v[218:219], s[26:27], 0, v[186:187]
	s_add_i32 m0, s44, 0xc000
	ds_read_b128 v[162:165], v211
	ds_read_b128 v[166:169], v211 offset:1024
	ds_read_b128 v[170:173], v211 offset:2048
	ds_read_b128 v[174:177], v211 offset:3072
	ds_read_b128 v[194:197], v211 offset:4096
	ds_read_b128 v[198:201], v211 offset:5120
	ds_read_b128 v[202:205], v211 offset:6144
	ds_read_b128 v[214:217], v211 offset:7168
	global_load_lds_dwordx4 v[218:219], off
	v_lshl_add_u64 v[218:219], s[26:27], 0, v[188:189]
	s_add_i32 m0, s44, 0xe000
	s_nop 0
	global_load_lds_dwordx4 v[218:219], off
	s_waitcnt vmcnt(8)
	s_waitcnt lgkmcnt(0)
	s_barrier
	s_setprio 1
	s_waitcnt lgkmcnt(0)
	v_mfma_f32_16x16x32_bf16 v[126:129], v[130:133], v[162:165], v[126:129]
	v_mfma_f32_16x16x32_bf16 v[122:125], v[138:141], v[162:165], v[122:125]
	v_mfma_f32_16x16x32_bf16 v[110:113], v[130:133], v[170:173], v[110:113]
	v_mfma_f32_16x16x32_bf16 v[106:109], v[138:141], v[170:173], v[106:109]
	v_mfma_f32_16x16x32_bf16 v[94:97], v[130:133], v[194:197], v[94:97]
	v_mfma_f32_16x16x32_bf16 v[90:93], v[138:141], v[194:197], v[90:93]
	v_mfma_f32_16x16x32_bf16 v[78:81], v[130:133], v[202:205], v[78:81]
	v_mfma_f32_16x16x32_bf16 v[74:77], v[138:141], v[202:205], v[74:77]
	v_mfma_f32_16x16x32_bf16 v[126:129], v[134:137], v[166:169], v[126:129]
	v_mfma_f32_16x16x32_bf16 v[122:125], v[142:145], v[166:169], v[122:125]
	v_mfma_f32_16x16x32_bf16 v[110:113], v[134:137], v[174:177], v[110:113]
	v_mfma_f32_16x16x32_bf16 v[106:109], v[142:145], v[174:177], v[106:109]
	v_mfma_f32_16x16x32_bf16 v[94:97], v[134:137], v[198:201], v[94:97]
	v_mfma_f32_16x16x32_bf16 v[90:93], v[142:145], v[198:201], v[90:93]
	v_mfma_f32_16x16x32_bf16 v[78:81], v[134:137], v[214:217], v[78:81]
	v_mfma_f32_16x16x32_bf16 v[74:77], v[142:145], v[214:217], v[74:77]
	v_mfma_f32_16x16x32_bf16 v[118:121], v[146:149], v[162:165], v[118:121]
	v_mfma_f32_16x16x32_bf16 v[114:117], v[154:157], v[162:165], v[114:117]
	v_mfma_f32_16x16x32_bf16 v[102:105], v[146:149], v[170:173], v[102:105]
	v_mfma_f32_16x16x32_bf16 v[98:101], v[154:157], v[170:173], v[98:101]
	v_mfma_f32_16x16x32_bf16 v[86:89], v[146:149], v[194:197], v[86:89]
	v_mfma_f32_16x16x32_bf16 v[82:85], v[154:157], v[194:197], v[82:85]
	v_mfma_f32_16x16x32_bf16 v[70:73], v[146:149], v[202:205], v[70:73]
	v_mfma_f32_16x16x32_bf16 v[66:69], v[154:157], v[202:205], v[66:69]
	v_mfma_f32_16x16x32_bf16 v[118:121], v[150:153], v[166:169], v[118:121]
	v_mfma_f32_16x16x32_bf16 v[114:117], v[158:161], v[166:169], v[114:117]
	v_mfma_f32_16x16x32_bf16 v[102:105], v[150:153], v[174:177], v[102:105]
	v_mfma_f32_16x16x32_bf16 v[98:101], v[158:161], v[174:177], v[98:101]
	v_mfma_f32_16x16x32_bf16 v[86:89], v[150:153], v[198:201], v[86:89]
	v_mfma_f32_16x16x32_bf16 v[82:85], v[158:161], v[198:201], v[82:85]
	v_mfma_f32_16x16x32_bf16 v[70:73], v[150:153], v[214:217], v[70:73]
	v_mfma_f32_16x16x32_bf16 v[66:69], v[158:161], v[214:217], v[66:69]
	s_setprio 0
	s_barrier
	s_add_i32 s60, s53, s35
	v_lshl_add_u64 v[218:219], s[28:29], 0, v[180:181]
	s_mov_b32 m0, s60
	ds_read_b128 v[162:165], v211 offset:16384
	ds_read_b128 v[166:169], v211 offset:17408
	ds_read_b128 v[170:173], v211 offset:18432
	ds_read_b128 v[174:177], v211 offset:19456
	ds_read_b128 v[194:197], v211 offset:20480
	ds_read_b128 v[198:201], v211 offset:21504
	ds_read_b128 v[202:205], v211 offset:22528
	ds_read_b128 v[214:217], v211 offset:23552
	global_load_lds_dwordx4 v[218:219], off
	s_add_i32 m0, s60, 0x2000
	s_add_u32 s60, s28, 0x40000
	v_lshl_add_u64 v[220:221], s[28:29], 0, v[184:185]
	s_addc_u32 s61, s29, 0
	s_add_i32 s62, s54, s35
	global_load_lds_dwordx4 v[220:221], off
	v_lshl_add_u64 v[222:223], s[60:61], 0, v[180:181]
	s_mov_b32 m0, s62
	v_lshl_add_u64 v[224:225], s[30:31], 0, v[182:183]
	global_load_lds_dwordx4 v[222:223], off
	v_lshl_add_u64 v[222:223], s[60:61], 0, v[184:185]
	s_add_i32 m0, s62, 0x2000
	s_nop 0
	global_load_lds_dwordx4 v[222:223], off
	v_lshl_add_u64 v[222:223], s[30:31], 0, v[178:179]
	s_mov_b32 m0, s44
	s_nop 0
	global_load_lds_dwordx4 v[222:223], off
	s_mov_b32 m0, s45
	s_nop 0
	global_load_lds_dwordx4 v[224:225], off
	s_waitcnt vmcnt(8)
	s_waitcnt lgkmcnt(0)
	s_barrier
; #define PG8_STAGE(bufoff, gbase, voff) do { _Pragma("unroll") for (int _i = 0; _i < 2; ++_i) \
;         __builtin_amdgcn_global_load_lds((const unsigned*)((const char*)(gbase) + (voff)[_i]), (PG8_LAS unsigned*)(lds + (bufoff) + ldsw + _i * 8192), 16, 0, 0); } while (0)
; #define PG8_LDA(dst, b, h) do { _Pragma("unroll") for (int m = 0; m < 4; ++m) _Pragma("unroll") for (int k = 0; k < 2; ++k) dst[m][k] = *(const PG8_LAS bf16x8*)(lds + PG8_SA(b, h) + aoff + m * 2048 + k * 1024); } while (0)
; #define PG8_LDB(dst, b, h) do { _Pragma("unroll") for (int n = 0; n < 2; ++n) _Pragma("unroll") for (int k = 0; k < 2; ++k) dst[n][k] = *(const PG8_LAS bf16x8*)(lds + PG8_SB(b, h) + boff + n * 2048 + k * 1024); } while (0)
; #define PG8_MMA(ai, bj, At, Bt) do { __builtin_amdgcn_s_setprio(1); _Pragma("unroll") for (int m = 0; m < 4; ++m) _Pragma("unroll") for (int n = 0; n < 2; ++n) _Pragma("unroll") for (int k = 0; k < 2; ++k) \
;         acc[ai][bj][m][n] = __builtin_amdgcn_mfma_f32_16x16x32_bf16(Bt[n][k], At[m][k], acc[ai][bj][m][n], 0, 0, 0); __builtin_amdgcn_s_setprio(0); } while (0)
; #define PG8_WAIT_V(n) asm volatile("s_waitcnt vmcnt(" #n ")" ::: "memory")
; template <class Epi, class Sched, bool ALIGN_EPI = false, bool SP2 = false>
; __device__ __forceinline__ void gemm_phase(PG8_LAS unsigned char* lds, const Gemm g, const Sched& S, const Epi& E) {
;     ...
;             PG8_LDB(B0, 0, 0); PG8_LDB(B1, 0, 1); PG8_SCHED; PG8_LDA(At, 0, 0); PG8_STAGE(PG8_SA(1, 1), a1 + ahstep, voffA);
;             PG8_WAIT_V(8); PG8_WAIT_L(0); PG8_BAR; PG8_MMA(0, 0, At, B0); PG8_MMA(0, 1, At, B1); PG8_BAR; PG8_SCHED;
;             PG8_LDA(At, 0, 1); PG8_STAGE(PG8_SB(0, 0), b2, voffB); PG8_STAGE(PG8_SB(0, 1), b2 + hstep, voffB); PG8_STAGE(PG8_SA(0, 0), a2, voffA);
;             PG8_WAIT_V(8); PG8_WAIT_L(0); PG8_BAR; PG8_MMA(1, 0, At, B0); PG8_MMA(1, 1, At, B1); PG8_BAR; PG8_SCHED;
;             PG8_LDB(B0, 1, 0); PG8_LDB(B1, 1, 1); PG8_SCHED; PG8_LDA(At, 1, 0); PG8_STAGE(PG8_SA(0, 1), a2 + ahstep, voffA);
;             PG8_WAIT_V(8); PG8_WAIT_L(0); PG8_BAR; PG8_MMA(0, 0, At, B0); PG8_MMA(0, 1, At, B1); PG8_BAR; PG8_SCHED;
;             PG8_LDA(At, 1, 1); PG8_STAGE(PG8_SB(1, 0), b3, voffB); PG8_STAGE(PG8_SB(1, 1), b3 + hstep, voffB); PG8_STAGE(PG8_SA(1, 0), a3, voffA);
;             PG8_WAIT_V(8); PG8_WAIT_L(0); PG8_BAR; PG8_MMA(1, 0, At, B0); PG8_MMA(1, 1, At, B1); PG8_BAR; PG8_SCHED;
	s_setprio 1
	s_waitcnt lgkmcnt(0)
	v_mfma_f32_16x16x32_bf16 v[62:65], v[130:133], v[162:165], v[62:65]
	v_mfma_f32_16x16x32_bf16 v[58:61], v[138:141], v[162:165], v[58:61]
	v_mfma_f32_16x16x32_bf16 v[46:49], v[130:133], v[170:173], v[46:49]
	v_mfma_f32_16x16x32_bf16 v[42:45], v[138:141], v[170:173], v[42:45]
	v_mfma_f32_16x16x32_bf16 v[30:33], v[130:133], v[194:197], v[30:33]
	v_mfma_f32_16x16x32_bf16 v[26:29], v[138:141], v[194:197], v[26:29]
	v_mfma_f32_16x16x32_bf16 v[14:17], v[130:133], v[202:205], v[14:17]
	v_mfma_f32_16x16x32_bf16 v[10:13], v[138:141], v[202:205], v[10:13]
	v_mfma_f32_16x16x32_bf16 v[62:65], v[134:137], v[166:169], v[62:65]
	v_mfma_f32_16x16x32_bf16 v[58:61], v[142:145], v[166:169], v[58:61]
	v_mfma_f32_16x16x32_bf16 v[46:49], v[134:137], v[174:177], v[46:49]
	v_mfma_f32_16x16x32_bf16 v[42:45], v[142:145], v[174:177], v[42:45]
	v_mfma_f32_16x16x32_bf16 v[30:33], v[134:137], v[198:201], v[30:33]
	v_mfma_f32_16x16x32_bf16 v[26:29], v[142:145], v[198:201], v[26:29]
	v_mfma_f32_16x16x32_bf16 v[14:17], v[134:137], v[214:217], v[14:17]
	v_mfma_f32_16x16x32_bf16 v[10:13], v[142:145], v[214:217], v[10:13]
	v_mfma_f32_16x16x32_bf16 v[54:57], v[146:149], v[162:165], v[54:57]
	v_mfma_f32_16x16x32_bf16 v[50:53], v[154:157], v[162:165], v[50:53]
	v_mfma_f32_16x16x32_bf16 v[38:41], v[146:149], v[170:173], v[38:41]
	v_mfma_f32_16x16x32_bf16 v[34:37], v[154:157], v[170:173], v[34:37]
	v_mfma_f32_16x16x32_bf16 v[22:25], v[146:149], v[194:197], v[22:25]
	v_mfma_f32_16x16x32_bf16 v[18:21], v[154:157], v[194:197], v[18:21]
	v_mfma_f32_16x16x32_bf16 v[6:9], v[146:149], v[202:205], v[6:9]
	v_mfma_f32_16x16x32_bf16 v[2:5], v[154:157], v[202:205], v[2:5]
	v_mfma_f32_16x16x32_bf16 v[54:57], v[150:153], v[166:169], v[54:57]
	v_mfma_f32_16x16x32_bf16 v[50:53], v[158:161], v[166:169], v[50:53]
	v_mfma_f32_16x16x32_bf16 v[38:41], v[150:153], v[174:177], v[38:41]
	v_mfma_f32_16x16x32_bf16 v[34:37], v[158:161], v[174:177], v[34:37]
	v_mfma_f32_16x16x32_bf16 v[22:25], v[150:153], v[198:201], v[22:25]
	v_mfma_f32_16x16x32_bf16 v[18:21], v[158:161], v[198:201], v[18:21]
	v_mfma_f32_16x16x32_bf16 v[6:9], v[150:153], v[214:217], v[6:9]
	v_mfma_f32_16x16x32_bf16 v[2:5], v[158:161], v[214:217], v[2:5]
	s_setprio 0
	s_barrier
	s_add_i32 s60, 0, 0x18000
	s_add_i32 s61, 0, 0x1c000
	v_add_u32_e32 v142, s60, v206
	v_add_u32_e32 v158, s61, v206
	ds_read_b128 v[130:133], v142
	ds_read_b128 v[134:137], v142 offset:1024
	ds_read_b128 v[138:141], v142 offset:2048
	ds_read_b128 v[142:145], v142 offset:3072
	ds_read_b128 v[146:149], v158
	ds_read_b128 v[150:153], v158 offset:1024
	ds_read_b128 v[154:157], v158 offset:2048
	ds_read_b128 v[158:161], v158 offset:3072
	s_add_u32 s30, s30, 0x40000
	s_addc_u32 s31, s31, 0
	s_mov_b32 m0, s46
	v_lshl_add_u64 v[226:227], s[30:31], 0, v[178:179]
	ds_read_b128 v[162:165], v211 offset:32768
	ds_read_b128 v[166:169], v211 offset:33792
	ds_read_b128 v[170:173], v211 offset:34816
	ds_read_b128 v[174:177], v211 offset:35840
	ds_read_b128 v[194:197], v211 offset:36864
	ds_read_b128 v[198:201], v211 offset:37888
	ds_read_b128 v[202:205], v211 offset:38912
	ds_read_b128 v[214:217], v211 offset:39936
	global_load_lds_dwordx4 v[226:227], off
	v_lshl_add_u64 v[226:227], s[30:31], 0, v[182:183]
	s_mov_b32 m0, s47
	s_nop 0
	global_load_lds_dwordx4 v[226:227], off
	s_waitcnt vmcnt(8)
	s_waitcnt lgkmcnt(0)
	s_barrier
	s_setprio 1
	s_waitcnt lgkmcnt(0)
	v_mfma_f32_16x16x32_bf16 v[126:129], v[130:133], v[162:165], v[126:129]
	v_mfma_f32_16x16x32_bf16 v[122:125], v[138:141], v[162:165], v[122:125]
	v_mfma_f32_16x16x32_bf16 v[110:113], v[130:133], v[170:173], v[110:113]
	v_mfma_f32_16x16x32_bf16 v[106:109], v[138:141], v[170:173], v[106:109]
	v_mfma_f32_16x16x32_bf16 v[94:97], v[130:133], v[194:197], v[94:97]
	v_mfma_f32_16x16x32_bf16 v[90:93], v[138:141], v[194:197], v[90:93]
	v_mfma_f32_16x16x32_bf16 v[78:81], v[130:133], v[202:205], v[78:81]
	v_mfma_f32_16x16x32_bf16 v[74:77], v[138:141], v[202:205], v[74:77]
	v_mfma_f32_16x16x32_bf16 v[126:129], v[134:137], v[166:169], v[126:129]
	v_mfma_f32_16x16x32_bf16 v[122:125], v[142:145], v[166:169], v[122:125]
	v_mfma_f32_16x16x32_bf16 v[110:113], v[134:137], v[174:177], v[110:113]
	v_mfma_f32_16x16x32_bf16 v[106:109], v[142:145], v[174:177], v[106:109]
	v_mfma_f32_16x16x32_bf16 v[94:97], v[134:137], v[198:201], v[94:97]
	v_mfma_f32_16x16x32_bf16 v[90:93], v[142:145], v[198:201], v[90:93]
	v_mfma_f32_16x16x32_bf16 v[78:81], v[134:137], v[214:217], v[78:81]
	v_mfma_f32_16x16x32_bf16 v[74:77], v[142:145], v[214:217], v[74:77]
	v_mfma_f32_16x16x32_bf16 v[118:121], v[146:149], v[162:165], v[118:121]
	v_mfma_f32_16x16x32_bf16 v[114:117], v[154:157], v[162:165], v[114:117]
	v_mfma_f32_16x16x32_bf16 v[102:105], v[146:149], v[170:173], v[102:105]
	v_mfma_f32_16x16x32_bf16 v[98:101], v[154:157], v[170:173], v[98:101]
	v_mfma_f32_16x16x32_bf16 v[86:89], v[146:149], v[194:197], v[86:89]
	v_mfma_f32_16x16x32_bf16 v[82:85], v[154:157], v[194:197], v[82:85]
	v_mfma_f32_16x16x32_bf16 v[70:73], v[146:149], v[202:205], v[70:73]
	v_mfma_f32_16x16x32_bf16 v[66:69], v[154:157], v[202:205], v[66:69]
	v_mfma_f32_16x16x32_bf16 v[118:121], v[150:153], v[166:169], v[118:121]
	v_mfma_f32_16x16x32_bf16 v[114:117], v[158:161], v[166:169], v[114:117]
	v_mfma_f32_16x16x32_bf16 v[102:105], v[150:153], v[174:177], v[102:105]
	v_mfma_f32_16x16x32_bf16 v[98:101], v[158:161], v[174:177], v[98:101]
	v_mfma_f32_16x16x32_bf16 v[86:89], v[150:153], v[198:201], v[86:89]
	v_mfma_f32_16x16x32_bf16 v[82:85], v[158:161], v[198:201], v[82:85]
	v_mfma_f32_16x16x32_bf16 v[70:73], v[150:153], v[214:217], v[70:73]
	v_mfma_f32_16x16x32_bf16 v[66:69], v[158:161], v[214:217], v[66:69]
	s_setprio 0
	s_barrier
; #define PG8_STAGE(bufoff, gbase, voff) do { _Pragma("unroll") for (int _i = 0; _i < 2; ++_i) \
;         __builtin_amdgcn_global_load_lds((const unsigned*)((const char*)(gbase) + (voff)[_i]), (PG8_LAS unsigned*)(lds + (bufoff) + ldsw + _i * 8192), 16, 0, 0); } while (0)
; #define PG8_LDA(dst, b, h) do { _Pragma("unroll") for (int m = 0; m < 4; ++m) _Pragma("unroll") for (int k = 0; k < 2; ++k) dst[m][k] = *(const PG8_LAS bf16x8*)(lds + PG8_SA(b, h) + aoff + m * 2048 + k * 1024); } while (0)
; #define PG8_LDB(dst, b, h) do { _Pragma("unroll") for (int n = 0; n < 2; ++n) _Pragma("unroll") for (int k = 0; k < 2; ++k) dst[n][k] = *(const PG8_LAS bf16x8*)(lds + PG8_SB(b, h) + boff + n * 2048 + k * 1024); } while (0)
; #define PG8_MMA(ai, bj, At, Bt) do { __builtin_amdgcn_s_setprio(1); _Pragma("unroll") for (int m = 0; m < 4; ++m) _Pragma("unroll") for (int n = 0; n < 2; ++n) _Pragma("unroll") for (int k = 0; k < 2; ++k) \
;         acc[ai][bj][m][n] = __builtin_amdgcn_mfma_f32_16x16x32_bf16(Bt[n][k], At[m][k], acc[ai][bj][m][n], 0, 0, 0); __builtin_amdgcn_s_setprio(0); } while (0)
; #define PG8_WAIT_V(n) asm volatile("s_waitcnt vmcnt(" #n ")" ::: "memory")
; template <class Epi, class Sched, bool ALIGN_EPI = false, bool SP2 = false>
; __device__ __forceinline__ void gemm_phase(PG8_LAS unsigned char* lds, const Gemm g, const Sched& S, const Epi& E) {
;     ...
;             PG8_LDB(B0, 0, 0); PG8_LDB(B1, 0, 1); PG8_SCHED; PG8_LDA(At, 0, 0); PG8_STAGE(PG8_SA(1, 1), a1 + ahstep, voffA);
;             PG8_WAIT_V(8); PG8_WAIT_L(0); PG8_BAR; PG8_MMA(0, 0, At, B0); PG8_MMA(0, 1, At, B1); PG8_BAR; PG8_SCHED;
;             PG8_LDA(At, 0, 1); PG8_STAGE(PG8_SB(0, 0), b2, voffB); PG8_STAGE(PG8_SB(0, 1), b2 + hstep, voffB); PG8_STAGE(PG8_SA(0, 0), a2, voffA);
;             PG8_WAIT_V(8); PG8_WAIT_L(0); PG8_BAR; PG8_MMA(1, 0, At, B0); PG8_MMA(1, 1, At, B1); PG8_BAR; PG8_SCHED;
;             PG8_LDB(B0, 1, 0); PG8_LDB(B1, 1, 1); PG8_SCHED; PG8_LDA(At, 1, 0); PG8_STAGE(PG8_SA(0, 1), a2 + ahstep, voffA);
;             PG8_WAIT_V(8); PG8_WAIT_L(0); PG8_BAR; PG8_MMA(0, 0, At, B0); PG8_MMA(0, 1, At, B1); PG8_BAR; PG8_SCHED;
;             PG8_LDA(At, 1, 1); PG8_STAGE(PG8_SB(1, 0), b3, voffB); PG8_STAGE(PG8_SB(1, 1), b3 + hstep, voffB); PG8_STAGE(PG8_SA(1, 0), a3, voffA);
;             PG8_WAIT_V(8); PG8_WAIT_L(0); PG8_BAR; PG8_MMA(1, 0, At, B0); PG8_MMA(1, 1, At, B1); PG8_BAR; PG8_SCHED;
	s_add_i32 s30, s60, s35
	v_lshl_add_u64 v[218:219], v[218:219], 0, s[12:13]
	s_mov_b32 m0, s30
	ds_read_b128 v[162:165], v211 offset:49152
	ds_read_b128 v[166:169], v211 offset:50176
	ds_read_b128 v[170:173], v211 offset:51200
	ds_read_b128 v[174:177], v211 offset:52224
	ds_read_b128 v[194:197], v211 offset:53248
	ds_read_b128 v[198:201], v211 offset:54272
	ds_read_b128 v[202:205], v211 offset:55296
	ds_read_b128 v[214:217], v211 offset:56320
	global_load_lds_dwordx4 v[218:219], off
	s_add_i32 m0, s30, 0x2000
	s_add_u32 s28, s28, 0x40080
	v_lshl_add_u64 v[218:219], v[220:221], 0, s[12:13]
	s_addc_u32 s29, s29, 0
	s_add_i32 s30, s61, s35
	global_load_lds_dwordx4 v[218:219], off
	v_lshl_add_u64 v[218:219], s[28:29], 0, v[180:181]
	s_mov_b32 m0, s30
	s_nop 0
	global_load_lds_dwordx4 v[218:219], off
	v_lshl_add_u64 v[218:219], s[28:29], 0, v[184:185]
	s_add_i32 m0, s30, 0x2000
	s_nop 0
	global_load_lds_dwordx4 v[218:219], off
	v_lshl_add_u64 v[218:219], v[222:223], 0, s[12:13]
	s_mov_b32 m0, s49
	s_nop 0
	global_load_lds_dwordx4 v[218:219], off
	v_lshl_add_u64 v[218:219], v[224:225], 0, s[12:13]
	s_mov_b32 m0, s50
	s_nop 0
	global_load_lds_dwordx4 v[218:219], off
	s_waitcnt vmcnt(8)
	s_waitcnt lgkmcnt(0)
	s_barrier
	s_setprio 1
	s_waitcnt lgkmcnt(0)
	v_mfma_f32_16x16x32_bf16 v[62:65], v[130:133], v[162:165], v[62:65]
	v_mfma_f32_16x16x32_bf16 v[58:61], v[138:141], v[162:165], v[58:61]
	v_mfma_f32_16x16x32_bf16 v[46:49], v[130:133], v[170:173], v[46:49]
	v_mfma_f32_16x16x32_bf16 v[42:45], v[138:141], v[170:173], v[42:45]
	v_mfma_f32_16x16x32_bf16 v[30:33], v[130:133], v[194:197], v[30:33]
	v_mfma_f32_16x16x32_bf16 v[26:29], v[138:141], v[194:197], v[26:29]
	v_mfma_f32_16x16x32_bf16 v[14:17], v[130:133], v[202:205], v[14:17]
	v_mfma_f32_16x16x32_bf16 v[10:13], v[138:141], v[202:205], v[10:13]
	v_mfma_f32_16x16x32_bf16 v[62:65], v[134:137], v[166:169], v[62:65]
	v_mfma_f32_16x16x32_bf16 v[58:61], v[142:145], v[166:169], v[58:61]
	v_mfma_f32_16x16x32_bf16 v[46:49], v[134:137], v[174:177], v[46:49]
	v_mfma_f32_16x16x32_bf16 v[42:45], v[142:145], v[174:177], v[42:45]
	v_mfma_f32_16x16x32_bf16 v[30:33], v[134:137], v[198:201], v[30:33]
	v_mfma_f32_16x16x32_bf16 v[26:29], v[142:145], v[198:201], v[26:29]
	v_mfma_f32_16x16x32_bf16 v[14:17], v[134:137], v[214:217], v[14:17]
	v_mfma_f32_16x16x32_bf16 v[10:13], v[142:145], v[214:217], v[10:13]
	v_mfma_f32_16x16x32_bf16 v[54:57], v[146:149], v[162:165], v[54:57]
	v_mfma_f32_16x16x32_bf16 v[50:53], v[154:157], v[162:165], v[50:53]
	v_mfma_f32_16x16x32_bf16 v[38:41], v[146:149], v[170:173], v[38:41]
	v_mfma_f32_16x16x32_bf16 v[34:37], v[154:157], v[170:173], v[34:37]
	v_mfma_f32_16x16x32_bf16 v[22:25], v[146:149], v[194:197], v[22:25]
	v_mfma_f32_16x16x32_bf16 v[18:21], v[154:157], v[194:197], v[18:21]
	v_mfma_f32_16x16x32_bf16 v[6:9], v[146:149], v[202:205], v[6:9]
	v_mfma_f32_16x16x32_bf16 v[2:5], v[154:157], v[202:205], v[2:5]
	v_mfma_f32_16x16x32_bf16 v[54:57], v[150:153], v[166:169], v[54:57]
	v_mfma_f32_16x16x32_bf16 v[50:53], v[158:161], v[166:169], v[50:53]
	v_mfma_f32_16x16x32_bf16 v[38:41], v[150:153], v[174:177], v[38:41]
	v_mfma_f32_16x16x32_bf16 v[34:37], v[158:161], v[174:177], v[34:37]
	v_mfma_f32_16x16x32_bf16 v[22:25], v[150:153], v[198:201], v[22:25]
	v_mfma_f32_16x16x32_bf16 v[18:21], v[158:161], v[198:201], v[18:21]
	v_mfma_f32_16x16x32_bf16 v[6:9], v[150:153], v[214:217], v[6:9]
	v_mfma_f32_16x16x32_bf16 v[2:5], v[158:161], v[214:217], v[2:5]
	s_setprio 0
	s_barrier
	s_add_i32 s59, s59, 2
	s_add_u32 s26, s26, 0x100
	s_addc_u32 s27, s27, 0
	s_add_u32 s57, s57, 0x100
	s_addc_u32 s58, s58, 0
	s_cmp_gt_u32 s59, 13
	s_cbranch_scc0 .LBB0_693
	s_and_b64 vcc, exec, s[14:15]
	s_cbranch_vccz .LBB0_696
	s_barrier

; #define PG8_STAGE(bufoff, gbase, voff) do { _Pragma("unroll") for (int _i = 0; _i < 2; ++_i) \
;         __builtin_amdgcn_global_load_lds((const unsigned*)((const char*)(gbase) + (voff)[_i]), (PG8_LAS unsigned*)(lds + (bufoff) + ldsw + _i * 8192), 16, 0, 0); } while (0)
; #define PG8_LDA(dst, b, h) do { _Pragma("unroll") for (int m = 0; m < 4; ++m) _Pragma("unroll") for (int k = 0; k < 2; ++k) dst[m][k] = *(const PG8_LAS bf16x8*)(lds + PG8_SA(b, h) + aoff + m * 2048 + k * 1024); } while (0)
; #define PG8_LDB(dst, b, h) do { _Pragma("unroll") for (int n = 0; n < 2; ++n) _Pragma("unroll") for (int k = 0; k < 2; ++k) dst[n][k] = *(const PG8_LAS bf16x8*)(lds + PG8_SB(b, h) + boff + n * 2048 + k * 1024); } while (0)
; #define PG8_MMA(ai, bj, At, Bt) do { __builtin_amdgcn_s_setprio(1); _Pragma("unroll") for (int m = 0; m < 4; ++m) _Pragma("unroll") for (int n = 0; n < 2; ++n) _Pragma("unroll") for (int k = 0; k < 2; ++k) \
;         acc[ai][bj][m][n] = __builtin_amdgcn_mfma_f32_16x16x32_bf16(Bt[n][k], At[m][k], acc[ai][bj][m][n], 0, 0, 0); __builtin_amdgcn_s_setprio(0); } while (0)
; #define PG8_WAIT_V(n) asm volatile("s_waitcnt vmcnt(" #n ")" ::: "memory")
; template <class Epi, class Sched, bool ALIGN_EPI = false, bool SP2 = false>
; __device__ __forceinline__ void gemm_phase(PG8_LAS unsigned char* lds, const Gemm g, const Sched& S, const Epi& E) {
;     ...
;             PG8_LDB(B0, 0, 0); PG8_LDB(B1, 0, 1); PG8_SCHED; PG8_LDA(At, 0, 0); PG8_STAGE(PG8_SA(1, 1), a1 + ahstep, voffA);
;             PG8_WAIT_V(8); PG8_WAIT_L(0); PG8_BAR; PG8_MMA(0, 0, At, B0); PG8_MMA(0, 1, At, B1); PG8_BAR; PG8_SCHED;
;             PG8_LDA(At, 0, 1); PG8_STAGE(PG8_SB(0, 0), b2, voffB); PG8_STAGE(PG8_SB(0, 1), b2 + hstep, voffB); PG8_STAGE(PG8_SA(0, 0), a2, voffA);
;             PG8_WAIT_V(8); PG8_WAIT_L(0); PG8_BAR; PG8_MMA(1, 0, At, B0); PG8_MMA(1, 1, At, B1); PG8_BAR; PG8_SCHED;
;             PG8_LDB(B0, 1, 0); PG8_LDB(B1, 1, 1); PG8_SCHED; PG8_LDA(At, 1, 0); PG8_STAGE(PG8_SA(0, 1), a2 + ahstep, voffA);
;             PG8_WAIT_V(8); PG8_WAIT_L(0); PG8_BAR; PG8_MMA(0, 0, At, B0); PG8_MMA(0, 1, At, B1); PG8_BAR; PG8_SCHED;
;             PG8_LDA(At, 1, 1); PG8_STAGE(PG8_SB(1, 0), b3, voffB); PG8_STAGE(PG8_SB(1, 1), b3 + hstep, voffB); PG8_STAGE(PG8_SA(1, 0), a3, voffA);
;             PG8_WAIT_V(8); PG8_WAIT_L(0); PG8_BAR; PG8_MMA(1, 0, At, B0); PG8_MMA(1, 1, At, B1); PG8_BAR; PG8_SCHED;
.LBB0_808:
	ds_read_b128 v[130:133], v201
	ds_read_b128 v[134:137], v201 offset:1024
	ds_read_b128 v[138:141], v201 offset:2048
	ds_read_b128 v[142:145], v201 offset:3072
	ds_read_b128 v[146:149], v202
	ds_read_b128 v[150:153], v202 offset:1024
	ds_read_b128 v[154:157], v202 offset:2048
	ds_read_b128 v[158:161], v202 offset:3072
	s_add_u32 s30, s28, 0xfffc0080
	s_addc_u32 s31, s29, -1
	s_cmp_eq_u32 s71, 12
	s_cselect_b32 s35, s1, s31
	s_cselect_b32 s34, s23, s30
	s_cselect_b32 s31, s21, s70
	s_cselect_b32 s30, s68, s69
	v_lshl_add_u64 v[224:225], s[28:29], 0, v[186:187]
	s_add_i32 m0, s46, 0xc000
	ds_read_b128 v[162:165], v203
	ds_read_b128 v[166:169], v203 offset:1024
	ds_read_b128 v[170:173], v203 offset:2048
	ds_read_b128 v[194:197], v203 offset:3072
	ds_read_b128 v[208:211], v203 offset:4096
	ds_read_b128 v[212:215], v203 offset:5120
	ds_read_b128 v[216:219], v203 offset:6144
	ds_read_b128 v[220:223], v203 offset:7168
	global_load_lds_dwordx4 v[224:225], off
	v_lshl_add_u64 v[224:225], s[28:29], 0, v[188:189]
	s_add_i32 m0, s46, 0xe000
	s_nop 0
	global_load_lds_dwordx4 v[224:225], off
	s_waitcnt vmcnt(8)
	s_waitcnt lgkmcnt(0)
	s_barrier
	s_setprio 1
	s_waitcnt lgkmcnt(0)
	v_mfma_f32_16x16x32_bf16 v[126:129], v[130:133], v[162:165], v[126:129]
	v_mfma_f32_16x16x32_bf16 v[122:125], v[138:141], v[162:165], v[122:125]
	v_mfma_f32_16x16x32_bf16 v[110:113], v[130:133], v[170:173], v[110:113]
	v_mfma_f32_16x16x32_bf16 v[106:109], v[138:141], v[170:173], v[106:109]
	v_mfma_f32_16x16x32_bf16 v[94:97], v[130:133], v[208:211], v[94:97]
	v_mfma_f32_16x16x32_bf16 v[90:93], v[138:141], v[208:211], v[90:93]
	v_mfma_f32_16x16x32_bf16 v[78:81], v[130:133], v[216:219], v[78:81]
	v_mfma_f32_16x16x32_bf16 v[74:77], v[138:141], v[216:219], v[74:77]
	v_mfma_f32_16x16x32_bf16 v[126:129], v[134:137], v[166:169], v[126:129]
	v_mfma_f32_16x16x32_bf16 v[122:125], v[142:145], v[166:169], v[122:125]
	v_mfma_f32_16x16x32_bf16 v[110:113], v[134:137], v[194:197], v[110:113]
	v_mfma_f32_16x16x32_bf16 v[106:109], v[142:145], v[194:197], v[106:109]
	v_mfma_f32_16x16x32_bf16 v[94:97], v[134:137], v[212:215], v[94:97]
	v_mfma_f32_16x16x32_bf16 v[90:93], v[142:145], v[212:215], v[90:93]
	v_mfma_f32_16x16x32_bf16 v[78:81], v[134:137], v[220:223], v[78:81]
	v_mfma_f32_16x16x32_bf16 v[74:77], v[142:145], v[220:223], v[74:77]
	v_mfma_f32_16x16x32_bf16 v[118:121], v[146:149], v[162:165], v[118:121]
	v_mfma_f32_16x16x32_bf16 v[114:117], v[154:157], v[162:165], v[114:117]
	v_mfma_f32_16x16x32_bf16 v[102:105], v[146:149], v[170:173], v[102:105]
	v_mfma_f32_16x16x32_bf16 v[98:101], v[154:157], v[170:173], v[98:101]
	v_mfma_f32_16x16x32_bf16 v[86:89], v[146:149], v[208:211], v[86:89]
	v_mfma_f32_16x16x32_bf16 v[82:85], v[154:157], v[208:211], v[82:85]
	v_mfma_f32_16x16x32_bf16 v[70:73], v[146:149], v[216:219], v[70:73]
	v_mfma_f32_16x16x32_bf16 v[66:69], v[154:157], v[216:219], v[66:69]
	v_mfma_f32_16x16x32_bf16 v[118:121], v[150:153], v[166:169], v[118:121]
	v_mfma_f32_16x16x32_bf16 v[114:117], v[158:161], v[166:169], v[114:117]
	v_mfma_f32_16x16x32_bf16 v[102:105], v[150:153], v[194:197], v[102:105]
	v_mfma_f32_16x16x32_bf16 v[98:101], v[158:161], v[194:197], v[98:101]
	v_mfma_f32_16x16x32_bf16 v[86:89], v[150:153], v[212:215], v[86:89]
	v_mfma_f32_16x16x32_bf16 v[82:85], v[158:161], v[212:215], v[82:85]
	v_mfma_f32_16x16x32_bf16 v[70:73], v[150:153], v[220:223], v[70:73]
	v_mfma_f32_16x16x32_bf16 v[66:69], v[158:161], v[220:223], v[66:69]
	s_setprio 0
	s_barrier
	s_add_i32 s72, s65, s43
	v_lshl_add_u64 v[224:225], s[30:31], 0, v[176:177]
	s_mov_b32 m0, s72
	ds_read_b128 v[162:165], v203 offset:16384
	ds_read_b128 v[166:169], v203 offset:17408
	ds_read_b128 v[170:173], v203 offset:18432
	ds_read_b128 v[194:197], v203 offset:19456
	ds_read_b128 v[208:211], v203 offset:20480
	ds_read_b128 v[212:215], v203 offset:21504
	ds_read_b128 v[216:219], v203 offset:22528
	ds_read_b128 v[220:223], v203 offset:23552
	global_load_lds_dwordx4 v[224:225], off
	s_add_i32 m0, s72, 0x2000
	s_add_u32 s72, s30, 0x40000
	v_lshl_add_u64 v[226:227], s[30:31], 0, v[180:181]
	s_addc_u32 s73, s31, 0
	s_add_i32 s74, s66, s43
	global_load_lds_dwordx4 v[226:227], off
	v_lshl_add_u64 v[228:229], s[72:73], 0, v[176:177]
	s_mov_b32 m0, s74
	v_lshl_add_u64 v[230:231], s[34:35], 0, v[178:179]
	global_load_lds_dwordx4 v[228:229], off
	v_lshl_add_u64 v[228:229], s[72:73], 0, v[180:181]
	s_add_i32 m0, s74, 0x2000
	s_nop 0
	global_load_lds_dwordx4 v[228:229], off
	v_lshl_add_u64 v[228:229], s[34:35], 0, v[174:175]
	s_mov_b32 m0, s46
	s_nop 0
	global_load_lds_dwordx4 v[228:229], off
	s_mov_b32 m0, s47
	s_nop 0
	global_load_lds_dwordx4 v[230:231], off
	s_waitcnt vmcnt(8)
	s_waitcnt lgkmcnt(0)
	s_barrier
; #define PG8_STAGE(bufoff, gbase, voff) do { _Pragma("unroll") for (int _i = 0; _i < 2; ++_i) \
;         __builtin_amdgcn_global_load_lds((const unsigned*)((const char*)(gbase) + (voff)[_i]), (PG8_LAS unsigned*)(lds + (bufoff) + ldsw + _i * 8192), 16, 0, 0); } while (0)
; #define PG8_LDA(dst, b, h) do { _Pragma("unroll") for (int m = 0; m < 4; ++m) _Pragma("unroll") for (int k = 0; k < 2; ++k) dst[m][k] = *(const PG8_LAS bf16x8*)(lds + PG8_SA(b, h) + aoff + m * 2048 + k * 1024); } while (0)
; #define PG8_LDB(dst, b, h) do { _Pragma("unroll") for (int n = 0; n < 2; ++n) _Pragma("unroll") for (int k = 0; k < 2; ++k) dst[n][k] = *(const PG8_LAS bf16x8*)(lds + PG8_SB(b, h) + boff + n * 2048 + k * 1024); } while (0)
; #define PG8_MMA(ai, bj, At, Bt) do { __builtin_amdgcn_s_setprio(1); _Pragma("unroll") for (int m = 0; m < 4; ++m) _Pragma("unroll") for (int n = 0; n < 2; ++n) _Pragma("unroll") for (int k = 0; k < 2; ++k) \
;         acc[ai][bj][m][n] = __builtin_amdgcn_mfma_f32_16x16x32_bf16(Bt[n][k], At[m][k], acc[ai][bj][m][n], 0, 0, 0); __builtin_amdgcn_s_setprio(0); } while (0)
; #define PG8_WAIT_V(n) asm volatile("s_waitcnt vmcnt(" #n ")" ::: "memory")
; template <class Epi, class Sched, bool ALIGN_EPI = false, bool SP2 = false>
; __device__ __forceinline__ void gemm_phase(PG8_LAS unsigned char* lds, const Gemm g, const Sched& S, const Epi& E) {
;     ...
;             PG8_LDB(B0, 0, 0); PG8_LDB(B1, 0, 1); PG8_SCHED; PG8_LDA(At, 0, 0); PG8_STAGE(PG8_SA(1, 1), a1 + ahstep, voffA);
;             PG8_WAIT_V(8); PG8_WAIT_L(0); PG8_BAR; PG8_MMA(0, 0, At, B0); PG8_MMA(0, 1, At, B1); PG8_BAR; PG8_SCHED;
;             PG8_LDA(At, 0, 1); PG8_STAGE(PG8_SB(0, 0), b2, voffB); PG8_STAGE(PG8_SB(0, 1), b2 + hstep, voffB); PG8_STAGE(PG8_SA(0, 0), a2, voffA);
;             PG8_WAIT_V(8); PG8_WAIT_L(0); PG8_BAR; PG8_MMA(1, 0, At, B0); PG8_MMA(1, 1, At, B1); PG8_BAR; PG8_SCHED;
;             PG8_LDB(B0, 1, 0); PG8_LDB(B1, 1, 1); PG8_SCHED; PG8_LDA(At, 1, 0); PG8_STAGE(PG8_SA(0, 1), a2 + ahstep, voffA);
;             PG8_WAIT_V(8); PG8_WAIT_L(0); PG8_BAR; PG8_MMA(0, 0, At, B0); PG8_MMA(0, 1, At, B1); PG8_BAR; PG8_SCHED;
;             PG8_LDA(At, 1, 1); PG8_STAGE(PG8_SB(1, 0), b3, voffB); PG8_STAGE(PG8_SB(1, 1), b3 + hstep, voffB); PG8_STAGE(PG8_SA(1, 0), a3, voffA);
;             PG8_WAIT_V(8); PG8_WAIT_L(0); PG8_BAR; PG8_MMA(1, 0, At, B0); PG8_MMA(1, 1, At, B1); PG8_BAR; PG8_SCHED;
	s_setprio 1
	s_waitcnt lgkmcnt(0)
	v_mfma_f32_16x16x32_bf16 v[62:65], v[130:133], v[162:165], v[62:65]
	v_mfma_f32_16x16x32_bf16 v[58:61], v[138:141], v[162:165], v[58:61]
	v_mfma_f32_16x16x32_bf16 v[46:49], v[130:133], v[170:173], v[46:49]
	v_mfma_f32_16x16x32_bf16 v[42:45], v[138:141], v[170:173], v[42:45]
	v_mfma_f32_16x16x32_bf16 v[30:33], v[130:133], v[208:211], v[30:33]
	v_mfma_f32_16x16x32_bf16 v[26:29], v[138:141], v[208:211], v[26:29]
	v_mfma_f32_16x16x32_bf16 v[14:17], v[130:133], v[216:219], v[14:17]
	v_mfma_f32_16x16x32_bf16 v[10:13], v[138:141], v[216:219], v[10:13]
	v_mfma_f32_16x16x32_bf16 v[62:65], v[134:137], v[166:169], v[62:65]
	v_mfma_f32_16x16x32_bf16 v[58:61], v[142:145], v[166:169], v[58:61]
	v_mfma_f32_16x16x32_bf16 v[46:49], v[134:137], v[194:197], v[46:49]
	v_mfma_f32_16x16x32_bf16 v[42:45], v[142:145], v[194:197], v[42:45]
	v_mfma_f32_16x16x32_bf16 v[30:33], v[134:137], v[212:215], v[30:33]
	v_mfma_f32_16x16x32_bf16 v[26:29], v[142:145], v[212:215], v[26:29]
	v_mfma_f32_16x16x32_bf16 v[14:17], v[134:137], v[220:223], v[14:17]
	v_mfma_f32_16x16x32_bf16 v[10:13], v[142:145], v[220:223], v[10:13]
	v_mfma_f32_16x16x32_bf16 v[54:57], v[146:149], v[162:165], v[54:57]
	v_mfma_f32_16x16x32_bf16 v[50:53], v[154:157], v[162:165], v[50:53]
	v_mfma_f32_16x16x32_bf16 v[38:41], v[146:149], v[170:173], v[38:41]
	v_mfma_f32_16x16x32_bf16 v[34:37], v[154:157], v[170:173], v[34:37]
	v_mfma_f32_16x16x32_bf16 v[22:25], v[146:149], v[208:211], v[22:25]
	v_mfma_f32_16x16x32_bf16 v[18:21], v[154:157], v[208:211], v[18:21]
	v_mfma_f32_16x16x32_bf16 v[6:9], v[146:149], v[216:219], v[6:9]
	v_mfma_f32_16x16x32_bf16 v[2:5], v[154:157], v[216:219], v[2:5]
	v_mfma_f32_16x16x32_bf16 v[54:57], v[150:153], v[166:169], v[54:57]
	v_mfma_f32_16x16x32_bf16 v[50:53], v[158:161], v[166:169], v[50:53]
	v_mfma_f32_16x16x32_bf16 v[38:41], v[150:153], v[194:197], v[38:41]
	v_mfma_f32_16x16x32_bf16 v[34:37], v[158:161], v[194:197], v[34:37]
	v_mfma_f32_16x16x32_bf16 v[22:25], v[150:153], v[212:215], v[22:25]
	v_mfma_f32_16x16x32_bf16 v[18:21], v[158:161], v[212:215], v[18:21]
	v_mfma_f32_16x16x32_bf16 v[6:9], v[150:153], v[220:223], v[6:9]
	v_mfma_f32_16x16x32_bf16 v[2:5], v[158:161], v[220:223], v[2:5]
	s_setprio 0
	s_barrier
	s_add_i32 s72, 0, 0x18000
	s_add_i32 s73, 0, 0x1c000
	v_add_u32_e32 v142, s72, v198
	v_add_u32_e32 v158, s73, v198
	ds_read_b128 v[130:133], v142
	ds_read_b128 v[134:137], v142 offset:1024
	ds_read_b128 v[138:141], v142 offset:2048
	ds_read_b128 v[142:145], v142 offset:3072
	ds_read_b128 v[146:149], v158
	ds_read_b128 v[150:153], v158 offset:1024
	ds_read_b128 v[154:157], v158 offset:2048
	ds_read_b128 v[158:161], v158 offset:3072
	s_add_u32 s34, s34, 0x40000
	s_addc_u32 s35, s35, 0
	s_mov_b32 m0, s48
	v_lshl_add_u64 v[232:233], s[34:35], 0, v[174:175]
	ds_read_b128 v[162:165], v203 offset:32768
	ds_read_b128 v[166:169], v203 offset:33792
	ds_read_b128 v[170:173], v203 offset:34816
	ds_read_b128 v[194:197], v203 offset:35840
	ds_read_b128 v[208:211], v203 offset:36864
	ds_read_b128 v[212:215], v203 offset:37888
	ds_read_b128 v[216:219], v203 offset:38912
	ds_read_b128 v[220:223], v203 offset:39936
	global_load_lds_dwordx4 v[232:233], off
	v_lshl_add_u64 v[232:233], s[34:35], 0, v[178:179]
	s_mov_b32 m0, s49
	s_nop 0
	global_load_lds_dwordx4 v[232:233], off
	s_waitcnt vmcnt(8)
	s_waitcnt lgkmcnt(0)
	s_barrier
	s_setprio 1
	s_waitcnt lgkmcnt(0)
	v_mfma_f32_16x16x32_bf16 v[126:129], v[130:133], v[162:165], v[126:129]
	v_mfma_f32_16x16x32_bf16 v[122:125], v[138:141], v[162:165], v[122:125]
	v_mfma_f32_16x16x32_bf16 v[110:113], v[130:133], v[170:173], v[110:113]
	v_mfma_f32_16x16x32_bf16 v[106:109], v[138:141], v[170:173], v[106:109]
	v_mfma_f32_16x16x32_bf16 v[94:97], v[130:133], v[208:211], v[94:97]
	v_mfma_f32_16x16x32_bf16 v[90:93], v[138:141], v[208:211], v[90:93]
	v_mfma_f32_16x16x32_bf16 v[78:81], v[130:133], v[216:219], v[78:81]
	v_mfma_f32_16x16x32_bf16 v[74:77], v[138:141], v[216:219], v[74:77]
	v_mfma_f32_16x16x32_bf16 v[126:129], v[134:137], v[166:169], v[126:129]
	v_mfma_f32_16x16x32_bf16 v[122:125], v[142:145], v[166:169], v[122:125]
	v_mfma_f32_16x16x32_bf16 v[110:113], v[134:137], v[194:197], v[110:113]
	v_mfma_f32_16x16x32_bf16 v[106:109], v[142:145], v[194:197], v[106:109]
	v_mfma_f32_16x16x32_bf16 v[94:97], v[134:137], v[212:215], v[94:97]
	v_mfma_f32_16x16x32_bf16 v[90:93], v[142:145], v[212:215], v[90:93]
	v_mfma_f32_16x16x32_bf16 v[78:81], v[134:137], v[220:223], v[78:81]
	v_mfma_f32_16x16x32_bf16 v[74:77], v[142:145], v[220:223], v[74:77]
	v_mfma_f32_16x16x32_bf16 v[118:121], v[146:149], v[162:165], v[118:121]
	v_mfma_f32_16x16x32_bf16 v[114:117], v[154:157], v[162:165], v[114:117]
	v_mfma_f32_16x16x32_bf16 v[102:105], v[146:149], v[170:173], v[102:105]
	v_mfma_f32_16x16x32_bf16 v[98:101], v[154:157], v[170:173], v[98:101]
	v_mfma_f32_16x16x32_bf16 v[86:89], v[146:149], v[208:211], v[86:89]
	v_mfma_f32_16x16x32_bf16 v[82:85], v[154:157], v[208:211], v[82:85]
	v_mfma_f32_16x16x32_bf16 v[70:73], v[146:149], v[216:219], v[70:73]
	v_mfma_f32_16x16x32_bf16 v[66:69], v[154:157], v[216:219], v[66:69]
	v_mfma_f32_16x16x32_bf16 v[118:121], v[150:153], v[166:169], v[118:121]
	v_mfma_f32_16x16x32_bf16 v[114:117], v[158:161], v[166:169], v[114:117]
	v_mfma_f32_16x16x32_bf16 v[102:105], v[150:153], v[194:197], v[102:105]
	v_mfma_f32_16x16x32_bf16 v[98:101], v[158:161], v[194:197], v[98:101]
	v_mfma_f32_16x16x32_bf16 v[86:89], v[150:153], v[212:215], v[86:89]
	v_mfma_f32_16x16x32_bf16 v[82:85], v[158:161], v[212:215], v[82:85]
	v_mfma_f32_16x16x32_bf16 v[70:73], v[150:153], v[220:223], v[70:73]
	v_mfma_f32_16x16x32_bf16 v[66:69], v[158:161], v[220:223], v[66:69]
	s_setprio 0
	s_barrier
; #define PG8_STAGE(bufoff, gbase, voff) do { _Pragma("unroll") for (int _i = 0; _i < 2; ++_i) \
;         __builtin_amdgcn_global_load_lds((const unsigned*)((const char*)(gbase) + (voff)[_i]), (PG8_LAS unsigned*)(lds + (bufoff) + ldsw + _i * 8192), 16, 0, 0); } while (0)
; #define PG8_LDA(dst, b, h) do { _Pragma("unroll") for (int m = 0; m < 4; ++m) _Pragma("unroll") for (int k = 0; k < 2; ++k) dst[m][k] = *(const PG8_LAS bf16x8*)(lds + PG8_SA(b, h) + aoff + m * 2048 + k * 1024); } while (0)
; #define PG8_LDB(dst, b, h) do { _Pragma("unroll") for (int n = 0; n < 2; ++n) _Pragma("unroll") for (int k = 0; k < 2; ++k) dst[n][k] = *(const PG8_LAS bf16x8*)(lds + PG8_SB(b, h) + boff + n * 2048 + k * 1024); } while (0)
; #define PG8_MMA(ai, bj, At, Bt) do { __builtin_amdgcn_s_setprio(1); _Pragma("unroll") for (int m = 0; m < 4; ++m) _Pragma("unroll") for (int n = 0; n < 2; ++n) _Pragma("unroll") for (int k = 0; k < 2; ++k) \
;         acc[ai][bj][m][n] = __builtin_amdgcn_mfma_f32_16x16x32_bf16(Bt[n][k], At[m][k], acc[ai][bj][m][n], 0, 0, 0); __builtin_amdgcn_s_setprio(0); } while (0)
; #define PG8_WAIT_V(n) asm volatile("s_waitcnt vmcnt(" #n ")" ::: "memory")
; template <class Epi, class Sched, bool ALIGN_EPI = false, bool SP2 = false>
; __device__ __forceinline__ void gemm_phase(PG8_LAS unsigned char* lds, const Gemm g, const Sched& S, const Epi& E) {
;     ...
;             PG8_LDB(B0, 0, 0); PG8_LDB(B1, 0, 1); PG8_SCHED; PG8_LDA(At, 0, 0); PG8_STAGE(PG8_SA(1, 1), a1 + ahstep, voffA);
;             PG8_WAIT_V(8); PG8_WAIT_L(0); PG8_BAR; PG8_MMA(0, 0, At, B0); PG8_MMA(0, 1, At, B1); PG8_BAR; PG8_SCHED;
;             PG8_LDA(At, 0, 1); PG8_STAGE(PG8_SB(0, 0), b2, voffB); PG8_STAGE(PG8_SB(0, 1), b2 + hstep, voffB); PG8_STAGE(PG8_SA(0, 0), a2, voffA);
;             PG8_WAIT_V(8); PG8_WAIT_L(0); PG8_BAR; PG8_MMA(1, 0, At, B0); PG8_MMA(1, 1, At, B1); PG8_BAR; PG8_SCHED;
;             PG8_LDB(B0, 1, 0); PG8_LDB(B1, 1, 1); PG8_SCHED; PG8_LDA(At, 1, 0); PG8_STAGE(PG8_SA(0, 1), a2 + ahstep, voffA);
;             PG8_WAIT_V(8); PG8_WAIT_L(0); PG8_BAR; PG8_MMA(0, 0, At, B0); PG8_MMA(0, 1, At, B1); PG8_BAR; PG8_SCHED;
;             PG8_LDA(At, 1, 1); PG8_STAGE(PG8_SB(1, 0), b3, voffB); PG8_STAGE(PG8_SB(1, 1), b3 + hstep, voffB); PG8_STAGE(PG8_SA(1, 0), a3, voffA);
;             PG8_WAIT_V(8); PG8_WAIT_L(0); PG8_BAR; PG8_MMA(1, 0, At, B0); PG8_MMA(1, 1, At, B1); PG8_BAR; PG8_SCHED;
	s_add_i32 s34, s72, s43
	v_lshl_add_u64 v[224:225], v[224:225], 0, s[14:15]
	s_mov_b32 m0, s34
	ds_read_b128 v[162:165], v203 offset:49152
	ds_read_b128 v[166:169], v203 offset:50176
	ds_read_b128 v[170:173], v203 offset:51200
	ds_read_b128 v[194:197], v203 offset:52224
	ds_read_b128 v[208:211], v203 offset:53248
	ds_read_b128 v[212:215], v203 offset:54272
	ds_read_b128 v[216:219], v203 offset:55296
	ds_read_b128 v[220:223], v203 offset:56320
	global_load_lds_dwordx4 v[224:225], off
	s_add_i32 m0, s34, 0x2000
	s_add_u32 s30, s30, 0x40080
	v_lshl_add_u64 v[224:225], v[226:227], 0, s[14:15]
	s_addc_u32 s31, s31, 0
	s_add_i32 s34, s73, s43
	global_load_lds_dwordx4 v[224:225], off
	v_lshl_add_u64 v[224:225], s[30:31], 0, v[176:177]
	s_mov_b32 m0, s34
	s_nop 0
	global_load_lds_dwordx4 v[224:225], off
	v_lshl_add_u64 v[224:225], s[30:31], 0, v[180:181]
	s_add_i32 m0, s34, 0x2000
	s_nop 0
	global_load_lds_dwordx4 v[224:225], off
	v_lshl_add_u64 v[224:225], v[228:229], 0, s[14:15]
	s_mov_b32 m0, s51
	s_nop 0
	global_load_lds_dwordx4 v[224:225], off
	v_lshl_add_u64 v[224:225], v[230:231], 0, s[14:15]
	s_mov_b32 m0, s52
	s_nop 0
	global_load_lds_dwordx4 v[224:225], off
	s_waitcnt vmcnt(8)
	s_waitcnt lgkmcnt(0)
	s_barrier
	s_setprio 1
	s_waitcnt lgkmcnt(0)
	v_mfma_f32_16x16x32_bf16 v[62:65], v[130:133], v[162:165], v[62:65]
	v_mfma_f32_16x16x32_bf16 v[58:61], v[138:141], v[162:165], v[58:61]
	v_mfma_f32_16x16x32_bf16 v[46:49], v[130:133], v[170:173], v[46:49]
	v_mfma_f32_16x16x32_bf16 v[42:45], v[138:141], v[170:173], v[42:45]
	v_mfma_f32_16x16x32_bf16 v[30:33], v[130:133], v[208:211], v[30:33]
	v_mfma_f32_16x16x32_bf16 v[26:29], v[138:141], v[208:211], v[26:29]
	v_mfma_f32_16x16x32_bf16 v[14:17], v[130:133], v[216:219], v[14:17]
	v_mfma_f32_16x16x32_bf16 v[10:13], v[138:141], v[216:219], v[10:13]
	v_mfma_f32_16x16x32_bf16 v[62:65], v[134:137], v[166:169], v[62:65]
	v_mfma_f32_16x16x32_bf16 v[58:61], v[142:145], v[166:169], v[58:61]
	v_mfma_f32_16x16x32_bf16 v[46:49], v[134:137], v[194:197], v[46:49]
	v_mfma_f32_16x16x32_bf16 v[42:45], v[142:145], v[194:197], v[42:45]
	v_mfma_f32_16x16x32_bf16 v[30:33], v[134:137], v[212:215], v[30:33]
	v_mfma_f32_16x16x32_bf16 v[26:29], v[142:145], v[212:215], v[26:29]
	v_mfma_f32_16x16x32_bf16 v[14:17], v[134:137], v[220:223], v[14:17]
	v_mfma_f32_16x16x32_bf16 v[10:13], v[142:145], v[220:223], v[10:13]
	v_mfma_f32_16x16x32_bf16 v[54:57], v[146:149], v[162:165], v[54:57]
	v_mfma_f32_16x16x32_bf16 v[50:53], v[154:157], v[162:165], v[50:53]
	v_mfma_f32_16x16x32_bf16 v[38:41], v[146:149], v[170:173], v[38:41]
	v_mfma_f32_16x16x32_bf16 v[34:37], v[154:157], v[170:173], v[34:37]
	v_mfma_f32_16x16x32_bf16 v[22:25], v[146:149], v[208:211], v[22:25]
	v_mfma_f32_16x16x32_bf16 v[18:21], v[154:157], v[208:211], v[18:21]
	v_mfma_f32_16x16x32_bf16 v[6:9], v[146:149], v[216:219], v[6:9]
	v_mfma_f32_16x16x32_bf16 v[2:5], v[154:157], v[216:219], v[2:5]
	v_mfma_f32_16x16x32_bf16 v[54:57], v[150:153], v[166:169], v[54:57]
	v_mfma_f32_16x16x32_bf16 v[50:53], v[158:161], v[166:169], v[50:53]
	v_mfma_f32_16x16x32_bf16 v[38:41], v[150:153], v[194:197], v[38:41]
	v_mfma_f32_16x16x32_bf16 v[34:37], v[158:161], v[194:197], v[34:37]
	v_mfma_f32_16x16x32_bf16 v[22:25], v[150:153], v[212:215], v[22:25]
	v_mfma_f32_16x16x32_bf16 v[18:21], v[158:161], v[212:215], v[18:21]
	v_mfma_f32_16x16x32_bf16 v[6:9], v[150:153], v[220:223], v[6:9]
	v_mfma_f32_16x16x32_bf16 v[2:5], v[158:161], v[220:223], v[2:5]
	s_setprio 0
	s_barrier
	s_add_i32 s71, s71, 2
	s_add_u32 s28, s28, 0x100
	s_addc_u32 s29, s29, 0
	s_add_u32 s69, s69, 0x100
	s_addc_u32 s70, s70, 0
	s_cmp_gt_u32 s71, 13
	s_cbranch_scc0 .LBB0_808
	s_and_b64 vcc, exec, s[16:17]
	s_cbranch_vccz .LBB0_811
	s_barrier

; #define PG8_STAGE(bufoff, gbase, voff) do { _Pragma("unroll") for (int _i = 0; _i < 2; ++_i) \
;         __builtin_amdgcn_global_load_lds((const unsigned*)((const char*)(gbase) + (voff)[_i]), (PG8_LAS unsigned*)(lds + (bufoff) + ldsw + _i * 8192), 16, 0, 0); } while (0)
; #define PG8_LDA(dst, b, h) do { _Pragma("unroll") for (int m = 0; m < 4; ++m) _Pragma("unroll") for (int k = 0; k < 2; ++k) dst[m][k] = *(const PG8_LAS bf16x8*)(lds + PG8_SA(b, h) + aoff + m * 2048 + k * 1024); } while (0)
; #define PG8_LDB(dst, b, h) do { _Pragma("unroll") for (int n = 0; n < 2; ++n) _Pragma("unroll") for (int k = 0; k < 2; ++k) dst[n][k] = *(const PG8_LAS bf16x8*)(lds + PG8_SB(b, h) + boff + n * 2048 + k * 1024); } while (0)
; #define PG8_MMA(ai, bj, At, Bt) do { __builtin_amdgcn_s_setprio(1); _Pragma("unroll") for (int m = 0; m < 4; ++m) _Pragma("unroll") for (int n = 0; n < 2; ++n) _Pragma("unroll") for (int k = 0; k < 2; ++k) \
;         acc[ai][bj][m][n] = __builtin_amdgcn_mfma_f32_16x16x32_bf16(Bt[n][k], At[m][k], acc[ai][bj][m][n], 0, 0, 0); __builtin_amdgcn_s_setprio(0); } while (0)
; #define PG8_WAIT_V(n) asm volatile("s_waitcnt vmcnt(" #n ")" ::: "memory")
; template <class Epi, class Sched, bool ALIGN_EPI = false, bool SP2 = false>
; __device__ __forceinline__ void gemm_phase(PG8_LAS unsigned char* lds, const Gemm g, const Sched& S, const Epi& E) {
;     ...
;             PG8_LDB(B0, 0, 0); PG8_LDB(B1, 0, 1); PG8_SCHED; PG8_LDA(At, 0, 0); PG8_STAGE(PG8_SA(1, 1), a1 + ahstep, voffA);
;             PG8_WAIT_V(8); PG8_WAIT_L(0); PG8_BAR; PG8_MMA(0, 0, At, B0); PG8_MMA(0, 1, At, B1); PG8_BAR; PG8_SCHED;
;             PG8_LDA(At, 0, 1); PG8_STAGE(PG8_SB(0, 0), b2, voffB); PG8_STAGE(PG8_SB(0, 1), b2 + hstep, voffB); PG8_STAGE(PG8_SA(0, 0), a2, voffA);
;             PG8_WAIT_V(8); PG8_WAIT_L(0); PG8_BAR; PG8_MMA(1, 0, At, B0); PG8_MMA(1, 1, At, B1); PG8_BAR; PG8_SCHED;
;             PG8_LDB(B0, 1, 0); PG8_LDB(B1, 1, 1); PG8_SCHED; PG8_LDA(At, 1, 0); PG8_STAGE(PG8_SA(0, 1), a2 + ahstep, voffA);
;             PG8_WAIT_V(8); PG8_WAIT_L(0); PG8_BAR; PG8_MMA(0, 0, At, B0); PG8_MMA(0, 1, At, B1); PG8_BAR; PG8_SCHED;
;             PG8_LDA(At, 1, 1); PG8_STAGE(PG8_SB(1, 0), b3, voffB); PG8_STAGE(PG8_SB(1, 1), b3 + hstep, voffB); PG8_STAGE(PG8_SA(1, 0), a3, voffA);
;             PG8_WAIT_V(8); PG8_WAIT_L(0); PG8_BAR; PG8_MMA(1, 0, At, B0); PG8_MMA(1, 1, At, B1); PG8_BAR; PG8_SCHED;
.LBB0_976:
	ds_read_b128 v[130:133], v190
	ds_read_b128 v[134:137], v190 offset:1024
	ds_read_b128 v[138:141], v190 offset:2048
	ds_read_b128 v[142:145], v190 offset:3072
	ds_read_b128 v[146:149], v191
	ds_read_b128 v[150:153], v191 offset:1024
	ds_read_b128 v[170:173], v191 offset:2048
	ds_read_b128 v[174:177], v191 offset:3072
	s_add_u32 s30, s28, 0xfffc0080
	s_addc_u32 s31, s29, -1
	s_cmp_eq_u32 s57, 12
	s_cselect_b32 s35, s21, s31
	s_cselect_b32 s34, s27, s30
	s_cselect_b32 s31, s19, s56
	s_cselect_b32 s30, s54, s55
	v_lshl_add_u64 v[186:187], s[28:29], 0, v[162:163]
	s_add_i32 m0, s42, 0xc000
	ds_read_b128 v[178:181], v192
	ds_read_b128 v[182:185], v192 offset:1024
	ds_read_b128 v[194:197], v192 offset:2048
	ds_read_b128 v[198:201], v192 offset:3072
	ds_read_b128 v[202:205], v192 offset:4096
	ds_read_b128 v[206:209], v192 offset:5120
	ds_read_b128 v[210:213], v192 offset:6144
	ds_read_b128 v[214:217], v192 offset:7168
	global_load_lds_dwordx4 v[186:187], off
	v_lshl_add_u64 v[186:187], s[28:29], 0, v[164:165]
	s_add_i32 m0, s42, 0xe000
	s_nop 0
	global_load_lds_dwordx4 v[186:187], off
	s_waitcnt vmcnt(8)
	s_waitcnt lgkmcnt(0)
	s_barrier
	s_setprio 1
	s_waitcnt lgkmcnt(0)
	v_mfma_f32_16x16x32_bf16 v[126:129], v[130:133], v[178:181], v[126:129]
	v_mfma_f32_16x16x32_bf16 v[122:125], v[138:141], v[178:181], v[122:125]
	v_mfma_f32_16x16x32_bf16 v[110:113], v[130:133], v[194:197], v[110:113]
	v_mfma_f32_16x16x32_bf16 v[106:109], v[138:141], v[194:197], v[106:109]
	v_mfma_f32_16x16x32_bf16 v[94:97], v[130:133], v[202:205], v[94:97]
	v_mfma_f32_16x16x32_bf16 v[90:93], v[138:141], v[202:205], v[90:93]
	v_mfma_f32_16x16x32_bf16 v[78:81], v[130:133], v[210:213], v[78:81]
	v_mfma_f32_16x16x32_bf16 v[74:77], v[138:141], v[210:213], v[74:77]
	v_mfma_f32_16x16x32_bf16 v[126:129], v[134:137], v[182:185], v[126:129]
	v_mfma_f32_16x16x32_bf16 v[122:125], v[142:145], v[182:185], v[122:125]
	v_mfma_f32_16x16x32_bf16 v[110:113], v[134:137], v[198:201], v[110:113]
	v_mfma_f32_16x16x32_bf16 v[106:109], v[142:145], v[198:201], v[106:109]
	v_mfma_f32_16x16x32_bf16 v[94:97], v[134:137], v[206:209], v[94:97]
	v_mfma_f32_16x16x32_bf16 v[90:93], v[142:145], v[206:209], v[90:93]
	v_mfma_f32_16x16x32_bf16 v[78:81], v[134:137], v[214:217], v[78:81]
	v_mfma_f32_16x16x32_bf16 v[74:77], v[142:145], v[214:217], v[74:77]
	v_mfma_f32_16x16x32_bf16 v[118:121], v[146:149], v[178:181], v[118:121]
	v_mfma_f32_16x16x32_bf16 v[114:117], v[170:173], v[178:181], v[114:117]
	v_mfma_f32_16x16x32_bf16 v[102:105], v[146:149], v[194:197], v[102:105]
	v_mfma_f32_16x16x32_bf16 v[98:101], v[170:173], v[194:197], v[98:101]
	v_mfma_f32_16x16x32_bf16 v[86:89], v[146:149], v[202:205], v[86:89]
	v_mfma_f32_16x16x32_bf16 v[82:85], v[170:173], v[202:205], v[82:85]
	v_mfma_f32_16x16x32_bf16 v[70:73], v[146:149], v[210:213], v[70:73]
	v_mfma_f32_16x16x32_bf16 v[66:69], v[170:173], v[210:213], v[66:69]
	v_mfma_f32_16x16x32_bf16 v[118:121], v[150:153], v[182:185], v[118:121]
	v_mfma_f32_16x16x32_bf16 v[114:117], v[174:177], v[182:185], v[114:117]
	v_mfma_f32_16x16x32_bf16 v[102:105], v[150:153], v[198:201], v[102:105]
	v_mfma_f32_16x16x32_bf16 v[98:101], v[174:177], v[198:201], v[98:101]
	v_mfma_f32_16x16x32_bf16 v[86:89], v[150:153], v[206:209], v[86:89]
	v_mfma_f32_16x16x32_bf16 v[82:85], v[174:177], v[206:209], v[82:85]
	v_mfma_f32_16x16x32_bf16 v[70:73], v[150:153], v[214:217], v[70:73]
	v_mfma_f32_16x16x32_bf16 v[66:69], v[174:177], v[214:217], v[66:69]
	s_setprio 0
	s_barrier
	s_add_i32 s58, s51, s39
	v_lshl_add_u64 v[186:187], s[30:31], 0, v[156:157]
	s_mov_b32 m0, s58
	ds_read_b128 v[178:181], v192 offset:16384
	ds_read_b128 v[182:185], v192 offset:17408
	ds_read_b128 v[194:197], v192 offset:18432
	ds_read_b128 v[198:201], v192 offset:19456
	ds_read_b128 v[202:205], v192 offset:20480
	ds_read_b128 v[206:209], v192 offset:21504
	ds_read_b128 v[210:213], v192 offset:22528
	ds_read_b128 v[214:217], v192 offset:23552
	global_load_lds_dwordx4 v[186:187], off
	s_add_i32 m0, s58, 0x2000
	s_add_u32 s58, s30, 0x40000
	v_lshl_add_u64 v[218:219], s[30:31], 0, v[160:161]
	s_addc_u32 s59, s31, 0
	s_add_i32 s60, s52, s39
	global_load_lds_dwordx4 v[218:219], off
	v_lshl_add_u64 v[220:221], s[58:59], 0, v[156:157]
	s_mov_b32 m0, s60
	v_lshl_add_u64 v[222:223], s[34:35], 0, v[158:159]
	global_load_lds_dwordx4 v[220:221], off
	v_lshl_add_u64 v[220:221], s[58:59], 0, v[160:161]
	s_add_i32 m0, s60, 0x2000
	s_nop 0
	global_load_lds_dwordx4 v[220:221], off
	v_lshl_add_u64 v[220:221], s[34:35], 0, v[154:155]
	s_mov_b32 m0, s42
	s_nop 0
	global_load_lds_dwordx4 v[220:221], off
	s_mov_b32 m0, s43
	s_nop 0
	global_load_lds_dwordx4 v[222:223], off
	s_waitcnt vmcnt(8)
	s_waitcnt lgkmcnt(0)
	s_barrier
; #define PG8_STAGE(bufoff, gbase, voff) do { _Pragma("unroll") for (int _i = 0; _i < 2; ++_i) \
;         __builtin_amdgcn_global_load_lds((const unsigned*)((const char*)(gbase) + (voff)[_i]), (PG8_LAS unsigned*)(lds + (bufoff) + ldsw + _i * 8192), 16, 0, 0); } while (0)
; #define PG8_LDA(dst, b, h) do { _Pragma("unroll") for (int m = 0; m < 4; ++m) _Pragma("unroll") for (int k = 0; k < 2; ++k) dst[m][k] = *(const PG8_LAS bf16x8*)(lds + PG8_SA(b, h) + aoff + m * 2048 + k * 1024); } while (0)
; #define PG8_LDB(dst, b, h) do { _Pragma("unroll") for (int n = 0; n < 2; ++n) _Pragma("unroll") for (int k = 0; k < 2; ++k) dst[n][k] = *(const PG8_LAS bf16x8*)(lds + PG8_SB(b, h) + boff + n * 2048 + k * 1024); } while (0)
; #define PG8_MMA(ai, bj, At, Bt) do { __builtin_amdgcn_s_setprio(1); _Pragma("unroll") for (int m = 0; m < 4; ++m) _Pragma("unroll") for (int n = 0; n < 2; ++n) _Pragma("unroll") for (int k = 0; k < 2; ++k) \
;         acc[ai][bj][m][n] = __builtin_amdgcn_mfma_f32_16x16x32_bf16(Bt[n][k], At[m][k], acc[ai][bj][m][n], 0, 0, 0); __builtin_amdgcn_s_setprio(0); } while (0)
; #define PG8_WAIT_V(n) asm volatile("s_waitcnt vmcnt(" #n ")" ::: "memory")
; template <class Epi, class Sched, bool ALIGN_EPI = false, bool SP2 = false>
; __device__ __forceinline__ void gemm_phase(PG8_LAS unsigned char* lds, const Gemm g, const Sched& S, const Epi& E) {
;     ...
;             PG8_LDB(B0, 0, 0); PG8_LDB(B1, 0, 1); PG8_SCHED; PG8_LDA(At, 0, 0); PG8_STAGE(PG8_SA(1, 1), a1 + ahstep, voffA);
;             PG8_WAIT_V(8); PG8_WAIT_L(0); PG8_BAR; PG8_MMA(0, 0, At, B0); PG8_MMA(0, 1, At, B1); PG8_BAR; PG8_SCHED;
;             PG8_LDA(At, 0, 1); PG8_STAGE(PG8_SB(0, 0), b2, voffB); PG8_STAGE(PG8_SB(0, 1), b2 + hstep, voffB); PG8_STAGE(PG8_SA(0, 0), a2, voffA);
;             PG8_WAIT_V(8); PG8_WAIT_L(0); PG8_BAR; PG8_MMA(1, 0, At, B0); PG8_MMA(1, 1, At, B1); PG8_BAR; PG8_SCHED;
;             PG8_LDB(B0, 1, 0); PG8_LDB(B1, 1, 1); PG8_SCHED; PG8_LDA(At, 1, 0); PG8_STAGE(PG8_SA(0, 1), a2 + ahstep, voffA);
;             PG8_WAIT_V(8); PG8_WAIT_L(0); PG8_BAR; PG8_MMA(0, 0, At, B0); PG8_MMA(0, 1, At, B1); PG8_BAR; PG8_SCHED;
;             PG8_LDA(At, 1, 1); PG8_STAGE(PG8_SB(1, 0), b3, voffB); PG8_STAGE(PG8_SB(1, 1), b3 + hstep, voffB); PG8_STAGE(PG8_SA(1, 0), a3, voffA);
;             PG8_WAIT_V(8); PG8_WAIT_L(0); PG8_BAR; PG8_MMA(1, 0, At, B0); PG8_MMA(1, 1, At, B1); PG8_BAR; PG8_SCHED;
	s_setprio 1
	s_waitcnt lgkmcnt(0)
	v_mfma_f32_16x16x32_bf16 v[62:65], v[130:133], v[178:181], v[62:65]
	v_mfma_f32_16x16x32_bf16 v[58:61], v[138:141], v[178:181], v[58:61]
	v_mfma_f32_16x16x32_bf16 v[46:49], v[130:133], v[194:197], v[46:49]
	v_mfma_f32_16x16x32_bf16 v[42:45], v[138:141], v[194:197], v[42:45]
	v_mfma_f32_16x16x32_bf16 v[30:33], v[130:133], v[202:205], v[30:33]
	v_mfma_f32_16x16x32_bf16 v[26:29], v[138:141], v[202:205], v[26:29]
	v_mfma_f32_16x16x32_bf16 v[14:17], v[130:133], v[210:213], v[14:17]
	v_mfma_f32_16x16x32_bf16 v[10:13], v[138:141], v[210:213], v[10:13]
	v_mfma_f32_16x16x32_bf16 v[62:65], v[134:137], v[182:185], v[62:65]
	v_mfma_f32_16x16x32_bf16 v[58:61], v[142:145], v[182:185], v[58:61]
	v_mfma_f32_16x16x32_bf16 v[46:49], v[134:137], v[198:201], v[46:49]
	v_mfma_f32_16x16x32_bf16 v[42:45], v[142:145], v[198:201], v[42:45]
	v_mfma_f32_16x16x32_bf16 v[30:33], v[134:137], v[206:209], v[30:33]
	v_mfma_f32_16x16x32_bf16 v[26:29], v[142:145], v[206:209], v[26:29]
	v_mfma_f32_16x16x32_bf16 v[14:17], v[134:137], v[214:217], v[14:17]
	v_mfma_f32_16x16x32_bf16 v[10:13], v[142:145], v[214:217], v[10:13]
	v_mfma_f32_16x16x32_bf16 v[54:57], v[146:149], v[178:181], v[54:57]
	v_mfma_f32_16x16x32_bf16 v[50:53], v[170:173], v[178:181], v[50:53]
	v_mfma_f32_16x16x32_bf16 v[38:41], v[146:149], v[194:197], v[38:41]
	v_mfma_f32_16x16x32_bf16 v[34:37], v[170:173], v[194:197], v[34:37]
	v_mfma_f32_16x16x32_bf16 v[22:25], v[146:149], v[202:205], v[22:25]
	v_mfma_f32_16x16x32_bf16 v[18:21], v[170:173], v[202:205], v[18:21]
	v_mfma_f32_16x16x32_bf16 v[6:9], v[146:149], v[210:213], v[6:9]
	v_mfma_f32_16x16x32_bf16 v[2:5], v[170:173], v[210:213], v[2:5]
	v_mfma_f32_16x16x32_bf16 v[54:57], v[150:153], v[182:185], v[54:57]
	v_mfma_f32_16x16x32_bf16 v[50:53], v[174:177], v[182:185], v[50:53]
	v_mfma_f32_16x16x32_bf16 v[38:41], v[150:153], v[198:201], v[38:41]
	v_mfma_f32_16x16x32_bf16 v[34:37], v[174:177], v[198:201], v[34:37]
	v_mfma_f32_16x16x32_bf16 v[22:25], v[150:153], v[206:209], v[22:25]
	v_mfma_f32_16x16x32_bf16 v[18:21], v[174:177], v[206:209], v[18:21]
	v_mfma_f32_16x16x32_bf16 v[6:9], v[150:153], v[214:217], v[6:9]
	v_mfma_f32_16x16x32_bf16 v[2:5], v[174:177], v[214:217], v[2:5]
	s_setprio 0
	s_barrier
	s_add_i32 s58, 0, 0x18000
	s_add_i32 s59, 0, 0x1c000
	v_add_u32_e32 v142, s58, v188
	v_add_u32_e32 v174, s59, v188
	ds_read_b128 v[130:133], v142
	ds_read_b128 v[134:137], v142 offset:1024
	ds_read_b128 v[138:141], v142 offset:2048
	ds_read_b128 v[142:145], v142 offset:3072
	ds_read_b128 v[146:149], v174
	ds_read_b128 v[150:153], v174 offset:1024
	ds_read_b128 v[170:173], v174 offset:2048
	ds_read_b128 v[174:177], v174 offset:3072
	s_add_u32 s34, s34, 0x40000
	s_addc_u32 s35, s35, 0
	s_mov_b32 m0, s44
	v_lshl_add_u64 v[224:225], s[34:35], 0, v[154:155]
	ds_read_b128 v[178:181], v192 offset:32768
	ds_read_b128 v[182:185], v192 offset:33792
	ds_read_b128 v[194:197], v192 offset:34816
	ds_read_b128 v[198:201], v192 offset:35840
	ds_read_b128 v[202:205], v192 offset:36864
	ds_read_b128 v[206:209], v192 offset:37888
	ds_read_b128 v[210:213], v192 offset:38912
	ds_read_b128 v[214:217], v192 offset:39936
	global_load_lds_dwordx4 v[224:225], off
	v_lshl_add_u64 v[224:225], s[34:35], 0, v[158:159]
	s_mov_b32 m0, s45
	s_nop 0
	global_load_lds_dwordx4 v[224:225], off
	s_waitcnt vmcnt(8)
	s_waitcnt lgkmcnt(0)
	s_barrier
	s_setprio 1
	s_waitcnt lgkmcnt(0)
	v_mfma_f32_16x16x32_bf16 v[126:129], v[130:133], v[178:181], v[126:129]
	v_mfma_f32_16x16x32_bf16 v[122:125], v[138:141], v[178:181], v[122:125]
	v_mfma_f32_16x16x32_bf16 v[110:113], v[130:133], v[194:197], v[110:113]
	v_mfma_f32_16x16x32_bf16 v[106:109], v[138:141], v[194:197], v[106:109]
	v_mfma_f32_16x16x32_bf16 v[94:97], v[130:133], v[202:205], v[94:97]
	v_mfma_f32_16x16x32_bf16 v[90:93], v[138:141], v[202:205], v[90:93]
	v_mfma_f32_16x16x32_bf16 v[78:81], v[130:133], v[210:213], v[78:81]
	v_mfma_f32_16x16x32_bf16 v[74:77], v[138:141], v[210:213], v[74:77]
	v_mfma_f32_16x16x32_bf16 v[126:129], v[134:137], v[182:185], v[126:129]
	v_mfma_f32_16x16x32_bf16 v[122:125], v[142:145], v[182:185], v[122:125]
	v_mfma_f32_16x16x32_bf16 v[110:113], v[134:137], v[198:201], v[110:113]
	v_mfma_f32_16x16x32_bf16 v[106:109], v[142:145], v[198:201], v[106:109]
	v_mfma_f32_16x16x32_bf16 v[94:97], v[134:137], v[206:209], v[94:97]
	v_mfma_f32_16x16x32_bf16 v[90:93], v[142:145], v[206:209], v[90:93]
	v_mfma_f32_16x16x32_bf16 v[78:81], v[134:137], v[214:217], v[78:81]
	v_mfma_f32_16x16x32_bf16 v[74:77], v[142:145], v[214:217], v[74:77]
	v_mfma_f32_16x16x32_bf16 v[118:121], v[146:149], v[178:181], v[118:121]
	v_mfma_f32_16x16x32_bf16 v[114:117], v[170:173], v[178:181], v[114:117]
	v_mfma_f32_16x16x32_bf16 v[102:105], v[146:149], v[194:197], v[102:105]
	v_mfma_f32_16x16x32_bf16 v[98:101], v[170:173], v[194:197], v[98:101]
	v_mfma_f32_16x16x32_bf16 v[86:89], v[146:149], v[202:205], v[86:89]
	v_mfma_f32_16x16x32_bf16 v[82:85], v[170:173], v[202:205], v[82:85]
	v_mfma_f32_16x16x32_bf16 v[70:73], v[146:149], v[210:213], v[70:73]
	v_mfma_f32_16x16x32_bf16 v[66:69], v[170:173], v[210:213], v[66:69]
	v_mfma_f32_16x16x32_bf16 v[118:121], v[150:153], v[182:185], v[118:121]
	v_mfma_f32_16x16x32_bf16 v[114:117], v[174:177], v[182:185], v[114:117]
	v_mfma_f32_16x16x32_bf16 v[102:105], v[150:153], v[198:201], v[102:105]
	v_mfma_f32_16x16x32_bf16 v[98:101], v[174:177], v[198:201], v[98:101]
	v_mfma_f32_16x16x32_bf16 v[86:89], v[150:153], v[206:209], v[86:89]
	v_mfma_f32_16x16x32_bf16 v[82:85], v[174:177], v[206:209], v[82:85]
	v_mfma_f32_16x16x32_bf16 v[70:73], v[150:153], v[214:217], v[70:73]
	v_mfma_f32_16x16x32_bf16 v[66:69], v[174:177], v[214:217], v[66:69]
	s_setprio 0
	s_barrier
; #define PG8_STAGE(bufoff, gbase, voff) do { _Pragma("unroll") for (int _i = 0; _i < 2; ++_i) \
;         __builtin_amdgcn_global_load_lds((const unsigned*)((const char*)(gbase) + (voff)[_i]), (PG8_LAS unsigned*)(lds + (bufoff) + ldsw + _i * 8192), 16, 0, 0); } while (0)
; #define PG8_LDA(dst, b, h) do { _Pragma("unroll") for (int m = 0; m < 4; ++m) _Pragma("unroll") for (int k = 0; k < 2; ++k) dst[m][k] = *(const PG8_LAS bf16x8*)(lds + PG8_SA(b, h) + aoff + m * 2048 + k * 1024); } while (0)
; #define PG8_MMA(ai, bj, At, Bt) do { __builtin_amdgcn_s_setprio(1); _Pragma("unroll") for (int m = 0; m < 4; ++m) _Pragma("unroll") for (int n = 0; n < 2; ++n) _Pragma("unroll") for (int k = 0; k < 2; ++k) \
;         acc[ai][bj][m][n] = __builtin_amdgcn_mfma_f32_16x16x32_bf16(Bt[n][k], At[m][k], acc[ai][bj][m][n], 0, 0, 0); __builtin_amdgcn_s_setprio(0); } while (0)
; #define PG8_WAIT_V(n) asm volatile("s_waitcnt vmcnt(" #n ")" ::: "memory")
; #define PG8_WAIT_L(n) asm volatile("s_waitcnt lgkmcnt(" #n ")" ::: "memory")
; #define PG8_BAR __builtin_amdgcn_s_barrier()
; #define PG8_SCHED __builtin_amdgcn_sched_barrier(0)
; template <class Epi, class Sched, bool ALIGN_EPI = false, bool SP2 = false>
; __device__ __forceinline__ void gemm_phase(PG8_LAS unsigned char* lds, const Gemm g, const Sched& S, const Epi& E) {
;     ...
;             PG8_LDA(At, 1, 1); PG8_STAGE(PG8_SB(1, 0), b3, voffB); PG8_STAGE(PG8_SB(1, 1), b3 + hstep, voffB); PG8_STAGE(PG8_SA(1, 0), a3, voffA);
;             PG8_WAIT_V(8); PG8_WAIT_L(0); PG8_BAR; PG8_MMA(1, 0, At, B0); PG8_MMA(1, 1, At, B1); PG8_BAR; PG8_SCHED;
	s_add_i32 s34, s58, s39
	v_lshl_add_u64 v[186:187], v[186:187], 0, s[14:15]
	s_mov_b32 m0, s34
	ds_read_b128 v[178:181], v192 offset:49152
	ds_read_b128 v[182:185], v192 offset:50176
	ds_read_b128 v[194:197], v192 offset:51200
	ds_read_b128 v[198:201], v192 offset:52224
	ds_read_b128 v[202:205], v192 offset:53248
	ds_read_b128 v[206:209], v192 offset:54272
	ds_read_b128 v[210:213], v192 offset:55296
	ds_read_b128 v[214:217], v192 offset:56320
	global_load_lds_dwordx4 v[186:187], off
	s_add_i32 m0, s34, 0x2000
	s_add_u32 s30, s30, 0x40080
	v_lshl_add_u64 v[186:187], v[218:219], 0, s[14:15]
	s_addc_u32 s31, s31, 0
	s_add_i32 s34, s59, s39
	global_load_lds_dwordx4 v[186:187], off
	v_lshl_add_u64 v[186:187], s[30:31], 0, v[156:157]
	s_mov_b32 m0, s34
	s_nop 0
	global_load_lds_dwordx4 v[186:187], off
	v_lshl_add_u64 v[186:187], s[30:31], 0, v[160:161]
	s_add_i32 m0, s34, 0x2000
	s_nop 0
	global_load_lds_dwordx4 v[186:187], off
	v_lshl_add_u64 v[186:187], v[220:221], 0, s[14:15]
	s_mov_b32 m0, s47
	s_nop 0
	global_load_lds_dwordx4 v[186:187], off
	v_lshl_add_u64 v[186:187], v[222:223], 0, s[14:15]
	s_mov_b32 m0, s48
	s_nop 0
	global_load_lds_dwordx4 v[186:187], off
	s_waitcnt vmcnt(8)
	s_waitcnt lgkmcnt(0)
	s_barrier
	s_setprio 1
	s_waitcnt lgkmcnt(0)
	v_mfma_f32_16x16x32_bf16 v[62:65], v[130:133], v[178:181], v[62:65]
	v_mfma_f32_16x16x32_bf16 v[58:61], v[138:141], v[178:181], v[58:61]
	v_mfma_f32_16x16x32_bf16 v[46:49], v[130:133], v[194:197], v[46:49]
	v_mfma_f32_16x16x32_bf16 v[42:45], v[138:141], v[194:197], v[42:45]
	v_mfma_f32_16x16x32_bf16 v[30:33], v[130:133], v[202:205], v[30:33]
	v_mfma_f32_16x16x32_bf16 v[26:29], v[138:141], v[202:205], v[26:29]
	v_mfma_f32_16x16x32_bf16 v[14:17], v[130:133], v[210:213], v[14:17]
	v_mfma_f32_16x16x32_bf16 v[10:13], v[138:141], v[210:213], v[10:13]
	v_mfma_f32_16x16x32_bf16 v[62:65], v[134:137], v[182:185], v[62:65]
	v_mfma_f32_16x16x32_bf16 v[58:61], v[142:145], v[182:185], v[58:61]
	v_mfma_f32_16x16x32_bf16 v[46:49], v[134:137], v[198:201], v[46:49]
	v_mfma_f32_16x16x32_bf16 v[42:45], v[142:145], v[198:201], v[42:45]
	v_mfma_f32_16x16x32_bf16 v[30:33], v[134:137], v[206:209], v[30:33]
	v_mfma_f32_16x16x32_bf16 v[26:29], v[142:145], v[206:209], v[26:29]
	v_mfma_f32_16x16x32_bf16 v[14:17], v[134:137], v[214:217], v[14:17]
	v_mfma_f32_16x16x32_bf16 v[10:13], v[142:145], v[214:217], v[10:13]
	v_mfma_f32_16x16x32_bf16 v[54:57], v[146:149], v[178:181], v[54:57]
	v_mfma_f32_16x16x32_bf16 v[50:53], v[170:173], v[178:181], v[50:53]
	v_mfma_f32_16x16x32_bf16 v[38:41], v[146:149], v[194:197], v[38:41]
	v_mfma_f32_16x16x32_bf16 v[34:37], v[170:173], v[194:197], v[34:37]
	v_mfma_f32_16x16x32_bf16 v[22:25], v[146:149], v[202:205], v[22:25]
	v_mfma_f32_16x16x32_bf16 v[18:21], v[170:173], v[202:205], v[18:21]
	v_mfma_f32_16x16x32_bf16 v[6:9], v[146:149], v[210:213], v[6:9]
	v_mfma_f32_16x16x32_bf16 v[2:5], v[170:173], v[210:213], v[2:5]
	v_mfma_f32_16x16x32_bf16 v[54:57], v[150:153], v[182:185], v[54:57]
	v_mfma_f32_16x16x32_bf16 v[50:53], v[174:177], v[182:185], v[50:53]
	v_mfma_f32_16x16x32_bf16 v[38:41], v[150:153], v[198:201], v[38:41]
	v_mfma_f32_16x16x32_bf16 v[34:37], v[174:177], v[198:201], v[34:37]
	v_mfma_f32_16x16x32_bf16 v[22:25], v[150:153], v[206:209], v[22:25]
	v_mfma_f32_16x16x32_bf16 v[18:21], v[174:177], v[206:209], v[18:21]
	v_mfma_f32_16x16x32_bf16 v[6:9], v[150:153], v[214:217], v[6:9]
	v_mfma_f32_16x16x32_bf16 v[2:5], v[174:177], v[214:217], v[2:5]
	s_setprio 0
	s_barrier
	s_add_i32 s57, s57, 2
	s_add_u32 s28, s28, 0x100
	s_addc_u32 s29, s29, 0
	s_add_u32 s55, s55, 0x100
	s_addc_u32 s56, s56, 0
	s_cmp_gt_u32 s57, 13
	s_cbranch_scc0 .LBB0_976
	s_and_b64 vcc, exec, s[16:17]
	s_cbranch_vccz .LBB0_979
	s_barrier

; #define PG8_STAGE(bufoff, gbase, voff) do { _Pragma("unroll") for (int _i = 0; _i < 2; ++_i) \
;         __builtin_amdgcn_global_load_lds((const unsigned*)((const char*)(gbase) + (voff)[_i]), (PG8_LAS unsigned*)(lds + (bufoff) + ldsw + _i * 8192), 16, 0, 0); } while (0)
; #define PG8_LDA(dst, b, h) do { _Pragma("unroll") for (int m = 0; m < 4; ++m) _Pragma("unroll") for (int k = 0; k < 2; ++k) dst[m][k] = *(const PG8_LAS bf16x8*)(lds + PG8_SA(b, h) + aoff + m * 2048 + k * 1024); } while (0)
; #define PG8_LDB(dst, b, h) do { _Pragma("unroll") for (int n = 0; n < 2; ++n) _Pragma("unroll") for (int k = 0; k < 2; ++k) dst[n][k] = *(const PG8_LAS bf16x8*)(lds + PG8_SB(b, h) + boff + n * 2048 + k * 1024); } while (0)
; #define PG8_MMA(ai, bj, At, Bt) do { __builtin_amdgcn_s_setprio(1); _Pragma("unroll") for (int m = 0; m < 4; ++m) _Pragma("unroll") for (int n = 0; n < 2; ++n) _Pragma("unroll") for (int k = 0; k < 2; ++k) \
;         acc[ai][bj][m][n] = __builtin_amdgcn_mfma_f32_16x16x32_bf16(Bt[n][k], At[m][k], acc[ai][bj][m][n], 0, 0, 0); __builtin_amdgcn_s_setprio(0); } while (0)
; #define PG8_WAIT_V(n) asm volatile("s_waitcnt vmcnt(" #n ")" ::: "memory")
; #define PG8_WAIT_L(n) asm volatile("s_waitcnt lgkmcnt(" #n ")" ::: "memory")
; #define PG8_BAR __builtin_amdgcn_s_barrier()
; #define PG8_SCHED __builtin_amdgcn_sched_barrier(0)
; template <class Epi, class Sched, bool ALIGN_EPI = false, bool SP2 = false>
; __device__ __forceinline__ void gemm_phase(PG8_LAS unsigned char* lds, const Gemm g, const Sched& S, const Epi& E) {
;     ...
;             PG8_LDB(B0, 0, 0); PG8_LDB(B1, 0, 1); PG8_SCHED; PG8_LDA(At, 0, 0); PG8_STAGE(PG8_SA(1, 1), a1 + ahstep, voffA);
;             PG8_WAIT_V(8); PG8_WAIT_L(0); PG8_BAR; PG8_MMA(0, 0, At, B0); PG8_MMA(0, 1, At, B1); PG8_BAR; PG8_SCHED;
;             PG8_LDA(At, 0, 1); PG8_STAGE(PG8_SB(0, 0), b2, voffB); PG8_STAGE(PG8_SB(0, 1), b2 + hstep, voffB); PG8_STAGE(PG8_SA(0, 0), a2, voffA);
.LBB0_1075:
	s_add_u32 s30, s0, 0xfffc0080
	s_addc_u32 s31, s1, -1
	s_add_i32 s79, 0, 0x10000
	s_cmp_eq_u32 s61, 12
	s_cselect_b32 s35, s33, s31
	s_cselect_b32 s34, s60, s30
	s_cselect_b32 s31, s39, s29
	s_cselect_b32 s30, s38, s28
	s_add_i32 s82, 0, 0x14000
	v_add_u32_e32 v170, s79, v213
	v_add_u32_e32 v186, s82, v213
	ds_read_b128 v[66:69], v170
	ds_read_b128 v[70:73], v170 offset:1024
	ds_read_b128 v[166:169], v170 offset:2048
	ds_read_b128 v[170:173], v170 offset:3072
	ds_read_b128 v[174:177], v186
	ds_read_b128 v[178:181], v186 offset:1024
	ds_read_b128 v[182:185], v186 offset:2048
	ds_read_b128 v[186:189], v186 offset:3072
	v_lshl_add_u64 v[194:195], s[0:1], 0, v[150:151]
	s_add_i32 m0, s27, 0xc000
	ds_read_b128 v[190:193], v216
	ds_read_b128 v[218:221], v216 offset:1024
	ds_read_b128 v[222:225], v216 offset:2048
	ds_read_b128 v[226:229], v216 offset:3072
	ds_read_b128 v[230:233], v216 offset:4096
	ds_read_b128 v[234:237], v216 offset:5120
	ds_read_b128 v[238:241], v216 offset:6144
	ds_read_b128 v[242:245], v216 offset:7168
	global_load_lds_dwordx4 v[194:195], off
	v_lshl_add_u64 v[194:195], s[0:1], 0, v[152:153]
	s_add_i32 m0, s27, 0xe000
	s_nop 0
	global_load_lds_dwordx4 v[194:195], off
	s_waitcnt vmcnt(8)
	s_waitcnt lgkmcnt(0)
	s_barrier
	s_setprio 1
	s_waitcnt lgkmcnt(0)
	v_mfma_f32_16x16x32_bf16 v[134:137], v[66:69], v[190:193], v[134:137]
	v_mfma_f32_16x16x32_bf16 v[130:133], v[166:169], v[190:193], v[130:133]
	v_mfma_f32_16x16x32_bf16 v[118:121], v[66:69], v[222:225], v[118:121]
	v_mfma_f32_16x16x32_bf16 v[114:117], v[166:169], v[222:225], v[114:117]
	v_mfma_f32_16x16x32_bf16 v[126:129], v[66:69], v[230:233], v[126:129]
	v_mfma_f32_16x16x32_bf16 v[122:125], v[166:169], v[230:233], v[122:125]
	v_mfma_f32_16x16x32_bf16 v[62:65], v[66:69], v[238:241], v[62:65]
	v_mfma_f32_16x16x32_bf16 v[58:61], v[166:169], v[238:241], v[58:61]
	v_mfma_f32_16x16x32_bf16 v[134:137], v[70:73], v[218:221], v[134:137]
	v_mfma_f32_16x16x32_bf16 v[130:133], v[170:173], v[218:221], v[130:133]
	v_mfma_f32_16x16x32_bf16 v[118:121], v[70:73], v[226:229], v[118:121]
	v_mfma_f32_16x16x32_bf16 v[114:117], v[170:173], v[226:229], v[114:117]
	v_mfma_f32_16x16x32_bf16 v[126:129], v[70:73], v[234:237], v[126:129]
	v_mfma_f32_16x16x32_bf16 v[122:125], v[170:173], v[234:237], v[122:125]
	v_mfma_f32_16x16x32_bf16 v[62:65], v[70:73], v[242:245], v[62:65]
	v_mfma_f32_16x16x32_bf16 v[58:61], v[170:173], v[242:245], v[58:61]
	v_mfma_f32_16x16x32_bf16 v[102:105], v[174:177], v[190:193], v[102:105]
	v_mfma_f32_16x16x32_bf16 v[98:101], v[182:185], v[190:193], v[98:101]
	v_mfma_f32_16x16x32_bf16 v[94:97], v[174:177], v[222:225], v[94:97]
	v_mfma_f32_16x16x32_bf16 v[90:93], v[182:185], v[222:225], v[90:93]
	v_mfma_f32_16x16x32_bf16 v[86:89], v[174:177], v[230:233], v[86:89]
	v_mfma_f32_16x16x32_bf16 v[82:85], v[182:185], v[230:233], v[82:85]
	v_mfma_f32_16x16x32_bf16 v[78:81], v[174:177], v[238:241], v[78:81]
	v_mfma_f32_16x16x32_bf16 v[74:77], v[182:185], v[238:241], v[74:77]
	v_mfma_f32_16x16x32_bf16 v[102:105], v[178:181], v[218:221], v[102:105]
	v_mfma_f32_16x16x32_bf16 v[98:101], v[186:189], v[218:221], v[98:101]
	v_mfma_f32_16x16x32_bf16 v[94:97], v[178:181], v[226:229], v[94:97]
	v_mfma_f32_16x16x32_bf16 v[90:93], v[186:189], v[226:229], v[90:93]
	v_mfma_f32_16x16x32_bf16 v[86:89], v[178:181], v[234:237], v[86:89]
	v_mfma_f32_16x16x32_bf16 v[82:85], v[186:189], v[234:237], v[82:85]
	v_mfma_f32_16x16x32_bf16 v[78:81], v[178:181], v[242:245], v[78:81]
	v_mfma_f32_16x16x32_bf16 v[74:77], v[186:189], v[242:245], v[74:77]
	s_setprio 0
	s_barrier
	s_add_i32 s79, s79, s65
	v_lshl_add_u64 v[194:195], s[30:31], 0, v[142:143]
	s_mov_b32 m0, s79
	ds_read_b128 v[190:193], v216 offset:16384
	ds_read_b128 v[218:221], v216 offset:17408
	ds_read_b128 v[222:225], v216 offset:18432
	ds_read_b128 v[226:229], v216 offset:19456
	ds_read_b128 v[230:233], v216 offset:20480
	ds_read_b128 v[234:237], v216 offset:21504
	ds_read_b128 v[238:241], v216 offset:22528
	ds_read_b128 v[242:245], v216 offset:23552
	global_load_lds_dwordx4 v[194:195], off
	s_add_i32 m0, s79, 0x2000
	s_add_u32 s80, s30, 0x40000
	v_lshl_add_u64 v[246:247], s[30:31], 0, v[138:139]
	s_addc_u32 s81, s31, 0
	s_add_i32 s79, s82, s65
	global_load_lds_dwordx4 v[246:247], off
	v_lshl_add_u64 v[248:249], s[80:81], 0, v[142:143]
	s_mov_b32 m0, s79
	v_lshl_add_u64 v[250:251], s[34:35], 0, v[140:141]
	global_load_lds_dwordx4 v[248:249], off
	v_lshl_add_u64 v[248:249], s[80:81], 0, v[138:139]
	s_add_i32 m0, s79, 0x2000
	s_nop 0
	global_load_lds_dwordx4 v[248:249], off
	v_lshl_add_u64 v[248:249], s[34:35], 0, v[144:145]
	s_mov_b32 m0, s27
	s_nop 0
	global_load_lds_dwordx4 v[248:249], off
	s_mov_b32 m0, s66
	s_nop 0
	global_load_lds_dwordx4 v[250:251], off
	s_waitcnt vmcnt(8)
	s_waitcnt lgkmcnt(0)
	s_barrier
; #define PG8_STAGE(bufoff, gbase, voff) do { _Pragma("unroll") for (int _i = 0; _i < 2; ++_i) \
;         __builtin_amdgcn_global_load_lds((const unsigned*)((const char*)(gbase) + (voff)[_i]), (PG8_LAS unsigned*)(lds + (bufoff) + ldsw + _i * 8192), 16, 0, 0); } while (0)
; #define PG8_LDA(dst, b, h) do { _Pragma("unroll") for (int m = 0; m < 4; ++m) _Pragma("unroll") for (int k = 0; k < 2; ++k) dst[m][k] = *(const PG8_LAS bf16x8*)(lds + PG8_SA(b, h) + aoff + m * 2048 + k * 1024); } while (0)
; #define PG8_LDB(dst, b, h) do { _Pragma("unroll") for (int n = 0; n < 2; ++n) _Pragma("unroll") for (int k = 0; k < 2; ++k) dst[n][k] = *(const PG8_LAS bf16x8*)(lds + PG8_SB(b, h) + boff + n * 2048 + k * 1024); } while (0)
; #define PG8_MMA(ai, bj, At, Bt) do { __builtin_amdgcn_s_setprio(1); _Pragma("unroll") for (int m = 0; m < 4; ++m) _Pragma("unroll") for (int n = 0; n < 2; ++n) _Pragma("unroll") for (int k = 0; k < 2; ++k) \
;         acc[ai][bj][m][n] = __builtin_amdgcn_mfma_f32_16x16x32_bf16(Bt[n][k], At[m][k], acc[ai][bj][m][n], 0, 0, 0); __builtin_amdgcn_s_setprio(0); } while (0)
; #define PG8_WAIT_V(n) asm volatile("s_waitcnt vmcnt(" #n ")" ::: "memory")
; #define PG8_WAIT_L(n) asm volatile("s_waitcnt lgkmcnt(" #n ")" ::: "memory")
; #define PG8_BAR __builtin_amdgcn_s_barrier()
; #define PG8_SCHED __builtin_amdgcn_sched_barrier(0)
; template <class Epi, class Sched, bool ALIGN_EPI = false, bool SP2 = false>
; __device__ __forceinline__ void gemm_phase(PG8_LAS unsigned char* lds, const Gemm g, const Sched& S, const Epi& E) {
;     ...
;             PG8_WAIT_V(8); PG8_WAIT_L(0); PG8_BAR; PG8_MMA(1, 0, At, B0); PG8_MMA(1, 1, At, B1); PG8_BAR; PG8_SCHED;
;             PG8_LDB(B0, 1, 0); PG8_LDB(B1, 1, 1); PG8_SCHED; PG8_LDA(At, 1, 0); PG8_STAGE(PG8_SA(0, 1), a2 + ahstep, voffA);
;             PG8_WAIT_V(8); PG8_WAIT_L(0); PG8_BAR; PG8_MMA(0, 0, At, B0); PG8_MMA(0, 1, At, B1); PG8_BAR; PG8_SCHED;
	s_setprio 1
	s_waitcnt lgkmcnt(0)
	v_mfma_f32_16x16x32_bf16 v[54:57], v[66:69], v[190:193], v[54:57]
	v_mfma_f32_16x16x32_bf16 v[50:53], v[166:169], v[190:193], v[50:53]
	v_mfma_f32_16x16x32_bf16 v[110:113], v[66:69], v[222:225], v[110:113]
	v_mfma_f32_16x16x32_bf16 v[106:109], v[166:169], v[222:225], v[106:109]
	v_mfma_f32_16x16x32_bf16 v[46:49], v[66:69], v[230:233], v[46:49]
	v_mfma_f32_16x16x32_bf16 v[42:45], v[166:169], v[230:233], v[42:45]
	v_mfma_f32_16x16x32_bf16 v[38:41], v[66:69], v[238:241], v[38:41]
	v_mfma_f32_16x16x32_bf16 v[34:37], v[166:169], v[238:241], v[34:37]
	v_mfma_f32_16x16x32_bf16 v[54:57], v[70:73], v[218:221], v[54:57]
	v_mfma_f32_16x16x32_bf16 v[50:53], v[170:173], v[218:221], v[50:53]
	v_mfma_f32_16x16x32_bf16 v[110:113], v[70:73], v[226:229], v[110:113]
	v_mfma_f32_16x16x32_bf16 v[106:109], v[170:173], v[226:229], v[106:109]
	v_mfma_f32_16x16x32_bf16 v[46:49], v[70:73], v[234:237], v[46:49]
	v_mfma_f32_16x16x32_bf16 v[42:45], v[170:173], v[234:237], v[42:45]
	v_mfma_f32_16x16x32_bf16 v[38:41], v[70:73], v[242:245], v[38:41]
	v_mfma_f32_16x16x32_bf16 v[34:37], v[170:173], v[242:245], v[34:37]
	v_mfma_f32_16x16x32_bf16 v[30:33], v[174:177], v[190:193], v[30:33]
	v_mfma_f32_16x16x32_bf16 v[26:29], v[182:185], v[190:193], v[26:29]
	v_mfma_f32_16x16x32_bf16 v[22:25], v[174:177], v[222:225], v[22:25]
	v_mfma_f32_16x16x32_bf16 v[18:21], v[182:185], v[222:225], v[18:21]
	v_mfma_f32_16x16x32_bf16 v[14:17], v[174:177], v[230:233], v[14:17]
	v_mfma_f32_16x16x32_bf16 v[10:13], v[182:185], v[230:233], v[10:13]
	v_mfma_f32_16x16x32_bf16 v[6:9], v[174:177], v[238:241], v[6:9]
	v_mfma_f32_16x16x32_bf16 v[2:5], v[182:185], v[238:241], v[2:5]
	v_mfma_f32_16x16x32_bf16 v[30:33], v[178:181], v[218:221], v[30:33]
	v_mfma_f32_16x16x32_bf16 v[26:29], v[186:189], v[218:221], v[26:29]
	v_mfma_f32_16x16x32_bf16 v[22:25], v[178:181], v[226:229], v[22:25]
	v_mfma_f32_16x16x32_bf16 v[18:21], v[186:189], v[226:229], v[18:21]
	v_mfma_f32_16x16x32_bf16 v[14:17], v[178:181], v[234:237], v[14:17]
	v_mfma_f32_16x16x32_bf16 v[10:13], v[186:189], v[234:237], v[10:13]
	v_mfma_f32_16x16x32_bf16 v[6:9], v[178:181], v[242:245], v[6:9]
	v_mfma_f32_16x16x32_bf16 v[2:5], v[186:189], v[242:245], v[2:5]
	s_setprio 0
	s_barrier
	s_add_i32 s79, 0, 0x18000
	s_add_i32 s80, 0, 0x1c000
	v_add_u32_e32 v170, s79, v213
	v_add_u32_e32 v186, s80, v213
	ds_read_b128 v[66:69], v170
	ds_read_b128 v[70:73], v170 offset:1024
	ds_read_b128 v[166:169], v170 offset:2048
	ds_read_b128 v[170:173], v170 offset:3072
	ds_read_b128 v[174:177], v186
	ds_read_b128 v[178:181], v186 offset:1024
	ds_read_b128 v[182:185], v186 offset:2048
	ds_read_b128 v[186:189], v186 offset:3072
	s_add_u32 s34, s34, 0x40000
	s_addc_u32 s35, s35, 0
	s_mov_b32 m0, s67
	v_lshl_add_u64 v[252:253], s[34:35], 0, v[144:145]
	ds_read_b128 v[190:193], v216 offset:32768
	ds_read_b128 v[218:221], v216 offset:33792
	ds_read_b128 v[222:225], v216 offset:34816
	ds_read_b128 v[226:229], v216 offset:35840
	ds_read_b128 v[230:233], v216 offset:36864
	ds_read_b128 v[234:237], v216 offset:37888
	ds_read_b128 v[238:241], v216 offset:38912
	ds_read_b128 v[242:245], v216 offset:39936
	global_load_lds_dwordx4 v[252:253], off
	v_lshl_add_u64 v[252:253], s[34:35], 0, v[140:141]
	s_mov_b32 m0, s68
	s_nop 0
	global_load_lds_dwordx4 v[252:253], off
	s_waitcnt vmcnt(8)
	s_waitcnt lgkmcnt(0)
	s_barrier
	s_setprio 1
	s_waitcnt lgkmcnt(0)
	v_mfma_f32_16x16x32_bf16 v[134:137], v[66:69], v[190:193], v[134:137]
	v_mfma_f32_16x16x32_bf16 v[130:133], v[166:169], v[190:193], v[130:133]
	v_mfma_f32_16x16x32_bf16 v[118:121], v[66:69], v[222:225], v[118:121]
	v_mfma_f32_16x16x32_bf16 v[114:117], v[166:169], v[222:225], v[114:117]
	v_mfma_f32_16x16x32_bf16 v[126:129], v[66:69], v[230:233], v[126:129]
	v_mfma_f32_16x16x32_bf16 v[122:125], v[166:169], v[230:233], v[122:125]
	v_mfma_f32_16x16x32_bf16 v[62:65], v[66:69], v[238:241], v[62:65]
	v_mfma_f32_16x16x32_bf16 v[58:61], v[166:169], v[238:241], v[58:61]
	v_mfma_f32_16x16x32_bf16 v[134:137], v[70:73], v[218:221], v[134:137]
	v_mfma_f32_16x16x32_bf16 v[130:133], v[170:173], v[218:221], v[130:133]
	v_mfma_f32_16x16x32_bf16 v[118:121], v[70:73], v[226:229], v[118:121]
	v_mfma_f32_16x16x32_bf16 v[114:117], v[170:173], v[226:229], v[114:117]
	v_mfma_f32_16x16x32_bf16 v[126:129], v[70:73], v[234:237], v[126:129]
	v_mfma_f32_16x16x32_bf16 v[122:125], v[170:173], v[234:237], v[122:125]
	v_mfma_f32_16x16x32_bf16 v[62:65], v[70:73], v[242:245], v[62:65]
	v_mfma_f32_16x16x32_bf16 v[58:61], v[170:173], v[242:245], v[58:61]
	v_mfma_f32_16x16x32_bf16 v[102:105], v[174:177], v[190:193], v[102:105]
	v_mfma_f32_16x16x32_bf16 v[98:101], v[182:185], v[190:193], v[98:101]
	v_mfma_f32_16x16x32_bf16 v[94:97], v[174:177], v[222:225], v[94:97]
	v_mfma_f32_16x16x32_bf16 v[90:93], v[182:185], v[222:225], v[90:93]
	v_mfma_f32_16x16x32_bf16 v[86:89], v[174:177], v[230:233], v[86:89]
	v_mfma_f32_16x16x32_bf16 v[82:85], v[182:185], v[230:233], v[82:85]
	v_mfma_f32_16x16x32_bf16 v[78:81], v[174:177], v[238:241], v[78:81]
	v_mfma_f32_16x16x32_bf16 v[74:77], v[182:185], v[238:241], v[74:77]
	v_mfma_f32_16x16x32_bf16 v[102:105], v[178:181], v[218:221], v[102:105]
	v_mfma_f32_16x16x32_bf16 v[98:101], v[186:189], v[218:221], v[98:101]
	v_mfma_f32_16x16x32_bf16 v[94:97], v[178:181], v[226:229], v[94:97]
	v_mfma_f32_16x16x32_bf16 v[90:93], v[186:189], v[226:229], v[90:93]
	v_mfma_f32_16x16x32_bf16 v[86:89], v[178:181], v[234:237], v[86:89]
	v_mfma_f32_16x16x32_bf16 v[82:85], v[186:189], v[234:237], v[82:85]
	v_mfma_f32_16x16x32_bf16 v[78:81], v[178:181], v[242:245], v[78:81]
	v_mfma_f32_16x16x32_bf16 v[74:77], v[186:189], v[242:245], v[74:77]
	s_setprio 0
	s_barrier
; #define PG8_STAGE(bufoff, gbase, voff) do { _Pragma("unroll") for (int _i = 0; _i < 2; ++_i) \
;         __builtin_amdgcn_global_load_lds((const unsigned*)((const char*)(gbase) + (voff)[_i]), (PG8_LAS unsigned*)(lds + (bufoff) + ldsw + _i * 8192), 16, 0, 0); } while (0)
; #define PG8_LDA(dst, b, h) do { _Pragma("unroll") for (int m = 0; m < 4; ++m) _Pragma("unroll") for (int k = 0; k < 2; ++k) dst[m][k] = *(const PG8_LAS bf16x8*)(lds + PG8_SA(b, h) + aoff + m * 2048 + k * 1024); } while (0)
; #define PG8_MMA(ai, bj, At, Bt) do { __builtin_amdgcn_s_setprio(1); _Pragma("unroll") for (int m = 0; m < 4; ++m) _Pragma("unroll") for (int n = 0; n < 2; ++n) _Pragma("unroll") for (int k = 0; k < 2; ++k) \
;         acc[ai][bj][m][n] = __builtin_amdgcn_mfma_f32_16x16x32_bf16(Bt[n][k], At[m][k], acc[ai][bj][m][n], 0, 0, 0); __builtin_amdgcn_s_setprio(0); } while (0)
; #define PG8_WAIT_V(n) asm volatile("s_waitcnt vmcnt(" #n ")" ::: "memory")
; #define PG8_WAIT_L(n) asm volatile("s_waitcnt lgkmcnt(" #n ")" ::: "memory")
; #define PG8_BAR __builtin_amdgcn_s_barrier()
; #define PG8_SCHED __builtin_amdgcn_sched_barrier(0)
; template <class Epi, class Sched, bool ALIGN_EPI = false, bool SP2 = false>
; __device__ __forceinline__ void gemm_phase(PG8_LAS unsigned char* lds, const Gemm g, const Sched& S, const Epi& E) {
;     ...
;             PG8_LDA(At, 1, 1); PG8_STAGE(PG8_SB(1, 0), b3, voffB); PG8_STAGE(PG8_SB(1, 1), b3 + hstep, voffB); PG8_STAGE(PG8_SA(1, 0), a3, voffA);
;             PG8_WAIT_V(8); PG8_WAIT_L(0); PG8_BAR; PG8_MMA(1, 0, At, B0); PG8_MMA(1, 1, At, B1); PG8_BAR; PG8_SCHED;
	s_add_i32 s34, s79, s65
	v_lshl_add_u64 v[194:195], v[194:195], 0, s[24:25]
	s_mov_b32 m0, s34
	ds_read_b128 v[190:193], v216 offset:49152
	ds_read_b128 v[218:221], v216 offset:50176
	ds_read_b128 v[222:225], v216 offset:51200
	ds_read_b128 v[226:229], v216 offset:52224
	ds_read_b128 v[230:233], v216 offset:53248
	ds_read_b128 v[234:237], v216 offset:54272
	ds_read_b128 v[238:241], v216 offset:55296
	ds_read_b128 v[242:245], v216 offset:56320
	global_load_lds_dwordx4 v[194:195], off
	s_add_i32 m0, s34, 0x2000
	s_add_u32 s30, s30, 0x40080
	v_lshl_add_u64 v[194:195], v[246:247], 0, s[24:25]
	s_addc_u32 s31, s31, 0
	s_add_i32 s34, s80, s65
	global_load_lds_dwordx4 v[194:195], off
	v_lshl_add_u64 v[194:195], s[30:31], 0, v[142:143]
	s_mov_b32 m0, s34
	s_nop 0
	global_load_lds_dwordx4 v[194:195], off
	v_lshl_add_u64 v[194:195], s[30:31], 0, v[138:139]
	s_add_i32 m0, s34, 0x2000
	s_nop 0
	global_load_lds_dwordx4 v[194:195], off
	v_lshl_add_u64 v[194:195], v[248:249], 0, s[24:25]
	s_mov_b32 m0, s70
	s_nop 0
	global_load_lds_dwordx4 v[194:195], off
	v_lshl_add_u64 v[194:195], v[250:251], 0, s[24:25]
	s_mov_b32 m0, s71
	s_nop 0
	global_load_lds_dwordx4 v[194:195], off
	s_waitcnt vmcnt(8)
	s_waitcnt lgkmcnt(0)
	s_barrier
	s_setprio 1
	s_waitcnt lgkmcnt(0)
	v_mfma_f32_16x16x32_bf16 v[54:57], v[66:69], v[190:193], v[54:57]
	v_mfma_f32_16x16x32_bf16 v[50:53], v[166:169], v[190:193], v[50:53]
	v_mfma_f32_16x16x32_bf16 v[110:113], v[66:69], v[222:225], v[110:113]
	v_mfma_f32_16x16x32_bf16 v[106:109], v[166:169], v[222:225], v[106:109]
	v_mfma_f32_16x16x32_bf16 v[46:49], v[66:69], v[230:233], v[46:49]
	v_mfma_f32_16x16x32_bf16 v[42:45], v[166:169], v[230:233], v[42:45]
	v_mfma_f32_16x16x32_bf16 v[38:41], v[66:69], v[238:241], v[38:41]
	v_mfma_f32_16x16x32_bf16 v[34:37], v[166:169], v[238:241], v[34:37]
	v_mfma_f32_16x16x32_bf16 v[54:57], v[70:73], v[218:221], v[54:57]
	v_mfma_f32_16x16x32_bf16 v[50:53], v[170:173], v[218:221], v[50:53]
	v_mfma_f32_16x16x32_bf16 v[110:113], v[70:73], v[226:229], v[110:113]
	v_mfma_f32_16x16x32_bf16 v[106:109], v[170:173], v[226:229], v[106:109]
	v_mfma_f32_16x16x32_bf16 v[46:49], v[70:73], v[234:237], v[46:49]
	v_mfma_f32_16x16x32_bf16 v[42:45], v[170:173], v[234:237], v[42:45]
	v_mfma_f32_16x16x32_bf16 v[38:41], v[70:73], v[242:245], v[38:41]
	v_mfma_f32_16x16x32_bf16 v[34:37], v[170:173], v[242:245], v[34:37]
	v_mfma_f32_16x16x32_bf16 v[30:33], v[174:177], v[190:193], v[30:33]
	v_mfma_f32_16x16x32_bf16 v[26:29], v[182:185], v[190:193], v[26:29]
	v_mfma_f32_16x16x32_bf16 v[22:25], v[174:177], v[222:225], v[22:25]
	v_mfma_f32_16x16x32_bf16 v[18:21], v[182:185], v[222:225], v[18:21]
	v_mfma_f32_16x16x32_bf16 v[14:17], v[174:177], v[230:233], v[14:17]
	v_mfma_f32_16x16x32_bf16 v[10:13], v[182:185], v[230:233], v[10:13]
	v_mfma_f32_16x16x32_bf16 v[6:9], v[174:177], v[238:241], v[6:9]
	v_mfma_f32_16x16x32_bf16 v[2:5], v[182:185], v[238:241], v[2:5]
	v_mfma_f32_16x16x32_bf16 v[30:33], v[178:181], v[218:221], v[30:33]
	v_mfma_f32_16x16x32_bf16 v[26:29], v[186:189], v[218:221], v[26:29]
	v_mfma_f32_16x16x32_bf16 v[22:25], v[178:181], v[226:229], v[22:25]
	v_mfma_f32_16x16x32_bf16 v[18:21], v[186:189], v[226:229], v[18:21]
	v_mfma_f32_16x16x32_bf16 v[14:17], v[178:181], v[234:237], v[14:17]
	v_mfma_f32_16x16x32_bf16 v[10:13], v[186:189], v[234:237], v[10:13]
	v_mfma_f32_16x16x32_bf16 v[6:9], v[178:181], v[242:245], v[6:9]
	v_mfma_f32_16x16x32_bf16 v[2:5], v[186:189], v[242:245], v[2:5]
	s_setprio 0
	s_barrier
	s_add_i32 s61, s61, 2
	s_add_u32 s0, s0, 0x100
	s_addc_u32 s1, s1, 0
	s_add_u32 s28, s28, 0x100
	s_addc_u32 s29, s29, 0
	s_cmp_gt_u32 s61, 13
	s_cbranch_scc0 .LBB0_1075
	s_and_b64 vcc, exec, s[12:13]
	s_cbranch_vccz .LBB0_1078
	s_barrier

; #define PG8_STAGE(bufoff, gbase, voff) do { _Pragma("unroll") for (int _i = 0; _i < 2; ++_i) \
;         __builtin_amdgcn_global_load_lds((const unsigned*)((const char*)(gbase) + (voff)[_i]), (PG8_LAS unsigned*)(lds + (bufoff) + ldsw + _i * 8192), 16, 0, 0); } while (0)
; #define PG8_LDA(dst, b, h) do { _Pragma("unroll") for (int m = 0; m < 4; ++m) _Pragma("unroll") for (int k = 0; k < 2; ++k) dst[m][k] = *(const PG8_LAS bf16x8*)(lds + PG8_SA(b, h) + aoff + m * 2048 + k * 1024); } while (0)
; #define PG8_LDB(dst, b, h) do { _Pragma("unroll") for (int n = 0; n < 2; ++n) _Pragma("unroll") for (int k = 0; k < 2; ++k) dst[n][k] = *(const PG8_LAS bf16x8*)(lds + PG8_SB(b, h) + boff + n * 2048 + k * 1024); } while (0)
; #define PG8_MMA(ai, bj, At, Bt) do { __builtin_amdgcn_s_setprio(1); _Pragma("unroll") for (int m = 0; m < 4; ++m) _Pragma("unroll") for (int n = 0; n < 2; ++n) _Pragma("unroll") for (int k = 0; k < 2; ++k) \
;         acc[ai][bj][m][n] = __builtin_amdgcn_mfma_f32_16x16x32_bf16(Bt[n][k], At[m][k], acc[ai][bj][m][n], 0, 0, 0); __builtin_amdgcn_s_setprio(0); } while (0)
; #define PG8_WAIT_V(n) asm volatile("s_waitcnt vmcnt(" #n ")" ::: "memory")
; #define PG8_WAIT_L(n) asm volatile("s_waitcnt lgkmcnt(" #n ")" ::: "memory")
; #define PG8_BAR __builtin_amdgcn_s_barrier()
; #define PG8_SCHED __builtin_amdgcn_sched_barrier(0)
; template <class Epi, class Sched, bool ALIGN_EPI = false, bool SP2 = false>
; __device__ __forceinline__ void gemm_phase(PG8_LAS unsigned char* lds, const Gemm g, const Sched& S, const Epi& E) {
;     ...
;             PG8_LDB(B0, 0, 0); PG8_LDB(B1, 0, 1); PG8_SCHED; PG8_LDA(At, 0, 0); PG8_STAGE(PG8_SA(1, 1), a1 + ahstep, voffA);
;             PG8_WAIT_V(8); PG8_WAIT_L(0); PG8_BAR; PG8_MMA(0, 0, At, B0); PG8_MMA(0, 1, At, B1); PG8_BAR; PG8_SCHED;
;             PG8_LDA(At, 0, 1); PG8_STAGE(PG8_SB(0, 0), b2, voffB); PG8_STAGE(PG8_SB(0, 1), b2 + hstep, voffB); PG8_STAGE(PG8_SA(0, 0), a2, voffA);
.LBB0_1199:
	ds_read_b128 v[144:147], v155
	ds_read_b128 v[148:151], v155 offset:1024
	ds_read_b128 v[158:161], v155 offset:2048
	ds_read_b128 v[162:165], v155 offset:3072
	ds_read_b128 v[166:169], v156
	ds_read_b128 v[170:173], v156 offset:1024
	ds_read_b128 v[174:177], v156 offset:2048
	ds_read_b128 v[178:181], v156 offset:3072
	s_add_u32 s22, s2, 0x20c000
	s_addc_u32 s23, s3, 0
	s_cmp_eq_u32 s47, 40
	s_cselect_b32 s26, s44, s22
	s_cselect_b32 s27, s15, s23
	s_cselect_b32 s24, s16, s45
	s_cselect_b32 s25, s17, s46
	s_add_u32 s22, s26, 0x210000
	s_addc_u32 s23, s27, 0
	v_lshl_add_u64 v[214:215], s[2:3], 0, v[136:137]
	s_add_i32 m0, s21, 0xc000
	ds_read_b128 v[182:185], v157
	ds_read_b128 v[186:189], v157 offset:1024
	ds_read_b128 v[190:193], v157 offset:2048
	ds_read_b128 v[194:197], v157 offset:3072
	ds_read_b128 v[198:201], v157 offset:4096
	ds_read_b128 v[202:205], v157 offset:5120
	ds_read_b128 v[206:209], v157 offset:6144
	ds_read_b128 v[210:213], v157 offset:7168
	global_load_lds_dwordx4 v[214:215], off
	v_lshl_add_u64 v[214:215], s[2:3], 0, v[138:139]
	s_add_i32 m0, s21, 0xe000
	s_nop 0
	global_load_lds_dwordx4 v[214:215], off
	s_waitcnt vmcnt(8)
	s_waitcnt lgkmcnt(0)
	s_barrier
	s_setprio 1
	s_waitcnt lgkmcnt(0)
	v_mfma_f32_16x16x32_bf16 v[124:127], v[144:147], v[182:185], v[124:127]
	v_mfma_f32_16x16x32_bf16 v[120:123], v[158:161], v[182:185], v[120:123]
	v_mfma_f32_16x16x32_bf16 v[108:111], v[144:147], v[190:193], v[108:111]
	v_mfma_f32_16x16x32_bf16 v[104:107], v[158:161], v[190:193], v[104:107]
	v_mfma_f32_16x16x32_bf16 v[96:99], v[144:147], v[198:201], v[96:99]
	v_mfma_f32_16x16x32_bf16 v[88:91], v[158:161], v[198:201], v[88:91]
	v_mfma_f32_16x16x32_bf16 v[80:83], v[144:147], v[206:209], v[80:83]
	v_mfma_f32_16x16x32_bf16 v[72:75], v[158:161], v[206:209], v[72:75]
	v_mfma_f32_16x16x32_bf16 v[124:127], v[148:151], v[186:189], v[124:127]
	v_mfma_f32_16x16x32_bf16 v[120:123], v[162:165], v[186:189], v[120:123]
	v_mfma_f32_16x16x32_bf16 v[108:111], v[148:151], v[194:197], v[108:111]
	v_mfma_f32_16x16x32_bf16 v[104:107], v[162:165], v[194:197], v[104:107]
	v_mfma_f32_16x16x32_bf16 v[96:99], v[148:151], v[202:205], v[96:99]
	v_mfma_f32_16x16x32_bf16 v[88:91], v[162:165], v[202:205], v[88:91]
	v_mfma_f32_16x16x32_bf16 v[80:83], v[148:151], v[210:213], v[80:83]
	v_mfma_f32_16x16x32_bf16 v[72:75], v[162:165], v[210:213], v[72:75]
	v_mfma_f32_16x16x32_bf16 v[116:119], v[166:169], v[182:185], v[116:119]
	v_mfma_f32_16x16x32_bf16 v[112:115], v[174:177], v[182:185], v[112:115]
	v_mfma_f32_16x16x32_bf16 v[100:103], v[166:169], v[190:193], v[100:103]
	v_mfma_f32_16x16x32_bf16 v[92:95], v[174:177], v[190:193], v[92:95]
	v_mfma_f32_16x16x32_bf16 v[84:87], v[166:169], v[198:201], v[84:87]
	v_mfma_f32_16x16x32_bf16 v[76:79], v[174:177], v[198:201], v[76:79]
	v_mfma_f32_16x16x32_bf16 v[68:71], v[166:169], v[206:209], v[68:71]
	v_mfma_f32_16x16x32_bf16 v[64:67], v[174:177], v[206:209], v[64:67]
	v_mfma_f32_16x16x32_bf16 v[116:119], v[170:173], v[186:189], v[116:119]
	v_mfma_f32_16x16x32_bf16 v[112:115], v[178:181], v[186:189], v[112:115]
	v_mfma_f32_16x16x32_bf16 v[100:103], v[170:173], v[194:197], v[100:103]
	v_mfma_f32_16x16x32_bf16 v[92:95], v[178:181], v[194:197], v[92:95]
	v_mfma_f32_16x16x32_bf16 v[84:87], v[170:173], v[202:205], v[84:87]
	v_mfma_f32_16x16x32_bf16 v[76:79], v[178:181], v[202:205], v[76:79]
	v_mfma_f32_16x16x32_bf16 v[68:71], v[170:173], v[210:213], v[68:71]
	v_mfma_f32_16x16x32_bf16 v[64:67], v[178:181], v[210:213], v[64:67]
	s_setprio 0
	s_barrier
	s_add_i32 s48, s40, s29
	v_lshl_add_u64 v[214:215], s[24:25], 0, v[130:131]
	s_mov_b32 m0, s48
	ds_read_b128 v[182:185], v157 offset:16384
	ds_read_b128 v[186:189], v157 offset:17408
	ds_read_b128 v[190:193], v157 offset:18432
	ds_read_b128 v[194:197], v157 offset:19456
	ds_read_b128 v[198:201], v157 offset:20480
	ds_read_b128 v[202:205], v157 offset:21504
	ds_read_b128 v[206:209], v157 offset:22528
	ds_read_b128 v[210:213], v157 offset:23552
	global_load_lds_dwordx4 v[214:215], off
	s_add_i32 m0, s48, 0x2000
	s_add_u32 s48, s24, 0xb0000
	v_lshl_add_u64 v[216:217], s[24:25], 0, v[134:135]
	s_addc_u32 s49, s25, 0
	s_add_i32 s50, s41, s29
	global_load_lds_dwordx4 v[216:217], off
	v_lshl_add_u64 v[218:219], s[48:49], 0, v[130:131]
	s_mov_b32 m0, s50
	s_nop 0
	global_load_lds_dwordx4 v[218:219], off
	v_lshl_add_u64 v[218:219], s[48:49], 0, v[134:135]
	s_add_i32 m0, s50, 0x2000
	s_nop 0
	global_load_lds_dwordx4 v[218:219], off
	v_lshl_add_u64 v[218:219], s[26:27], 0, v[128:129]
	s_mov_b32 m0, s21
	s_nop 0
	global_load_lds_dwordx4 v[218:219], off
	v_lshl_add_u64 v[218:219], s[26:27], 0, v[132:133]
	s_mov_b32 m0, s33
	s_nop 0
	global_load_lds_dwordx4 v[218:219], off
	s_waitcnt vmcnt(8)
	s_waitcnt lgkmcnt(0)
	s_barrier
; #define PG8_STAGE(bufoff, gbase, voff) do { _Pragma("unroll") for (int _i = 0; _i < 2; ++_i) \
;         __builtin_amdgcn_global_load_lds((const unsigned*)((const char*)(gbase) + (voff)[_i]), (PG8_LAS unsigned*)(lds + (bufoff) + ldsw + _i * 8192), 16, 0, 0); } while (0)
; #define PG8_LDA(dst, b, h) do { _Pragma("unroll") for (int m = 0; m < 4; ++m) _Pragma("unroll") for (int k = 0; k < 2; ++k) dst[m][k] = *(const PG8_LAS bf16x8*)(lds + PG8_SA(b, h) + aoff + m * 2048 + k * 1024); } while (0)
; #define PG8_LDB(dst, b, h) do { _Pragma("unroll") for (int n = 0; n < 2; ++n) _Pragma("unroll") for (int k = 0; k < 2; ++k) dst[n][k] = *(const PG8_LAS bf16x8*)(lds + PG8_SB(b, h) + boff + n * 2048 + k * 1024); } while (0)
; #define PG8_MMA(ai, bj, At, Bt) do { __builtin_amdgcn_s_setprio(1); _Pragma("unroll") for (int m = 0; m < 4; ++m) _Pragma("unroll") for (int n = 0; n < 2; ++n) _Pragma("unroll") for (int k = 0; k < 2; ++k) \
;         acc[ai][bj][m][n] = __builtin_amdgcn_mfma_f32_16x16x32_bf16(Bt[n][k], At[m][k], acc[ai][bj][m][n], 0, 0, 0); __builtin_amdgcn_s_setprio(0); } while (0)
; #define PG8_WAIT_V(n) asm volatile("s_waitcnt vmcnt(" #n ")" ::: "memory")
; #define PG8_WAIT_L(n) asm volatile("s_waitcnt lgkmcnt(" #n ")" ::: "memory")
; #define PG8_BAR __builtin_amdgcn_s_barrier()
; #define PG8_SCHED __builtin_amdgcn_sched_barrier(0)
; template <class Epi, class Sched, bool ALIGN_EPI = false, bool SP2 = false>
; __device__ __forceinline__ void gemm_phase(PG8_LAS unsigned char* lds, const Gemm g, const Sched& S, const Epi& E) {
;     ...
;             PG8_WAIT_V(8); PG8_WAIT_L(0); PG8_BAR; PG8_MMA(1, 0, At, B0); PG8_MMA(1, 1, At, B1); PG8_BAR; PG8_SCHED;
;             PG8_LDB(B0, 1, 0); PG8_LDB(B1, 1, 1); PG8_SCHED; PG8_LDA(At, 1, 0); PG8_STAGE(PG8_SA(0, 1), a2 + ahstep, voffA);
;             PG8_WAIT_V(8); PG8_WAIT_L(0); PG8_BAR; PG8_MMA(0, 0, At, B0); PG8_MMA(0, 1, At, B1); PG8_BAR; PG8_SCHED;
	s_setprio 1
	s_waitcnt lgkmcnt(0)
	v_mfma_f32_16x16x32_bf16 v[60:63], v[144:147], v[182:185], v[60:63]
	v_mfma_f32_16x16x32_bf16 v[56:59], v[158:161], v[182:185], v[56:59]
	v_mfma_f32_16x16x32_bf16 v[48:51], v[144:147], v[190:193], v[48:51]
	v_mfma_f32_16x16x32_bf16 v[40:43], v[158:161], v[190:193], v[40:43]
	v_mfma_f32_16x16x32_bf16 v[32:35], v[144:147], v[198:201], v[32:35]
	v_mfma_f32_16x16x32_bf16 v[24:27], v[158:161], v[198:201], v[24:27]
	v_mfma_f32_16x16x32_bf16 v[16:19], v[144:147], v[206:209], v[16:19]
	v_mfma_f32_16x16x32_bf16 v[8:11], v[158:161], v[206:209], v[8:11]
	v_mfma_f32_16x16x32_bf16 v[60:63], v[148:151], v[186:189], v[60:63]
	v_mfma_f32_16x16x32_bf16 v[56:59], v[162:165], v[186:189], v[56:59]
	v_mfma_f32_16x16x32_bf16 v[48:51], v[148:151], v[194:197], v[48:51]
	v_mfma_f32_16x16x32_bf16 v[40:43], v[162:165], v[194:197], v[40:43]
	v_mfma_f32_16x16x32_bf16 v[32:35], v[148:151], v[202:205], v[32:35]
	v_mfma_f32_16x16x32_bf16 v[24:27], v[162:165], v[202:205], v[24:27]
	v_mfma_f32_16x16x32_bf16 v[16:19], v[148:151], v[210:213], v[16:19]
	v_mfma_f32_16x16x32_bf16 v[8:11], v[162:165], v[210:213], v[8:11]
	v_mfma_f32_16x16x32_bf16 v[52:55], v[166:169], v[182:185], v[52:55]
	v_mfma_f32_16x16x32_bf16 v[44:47], v[174:177], v[182:185], v[44:47]
	v_mfma_f32_16x16x32_bf16 v[36:39], v[166:169], v[190:193], v[36:39]
	v_mfma_f32_16x16x32_bf16 v[28:31], v[174:177], v[190:193], v[28:31]
	v_mfma_f32_16x16x32_bf16 v[20:23], v[166:169], v[198:201], v[20:23]
	v_mfma_f32_16x16x32_bf16 v[12:15], v[174:177], v[198:201], v[12:15]
	v_mfma_f32_16x16x32_bf16 v[4:7], v[166:169], v[206:209], v[4:7]
	v_mfma_f32_16x16x32_bf16 v[0:3], v[174:177], v[206:209], v[0:3]
	v_mfma_f32_16x16x32_bf16 v[52:55], v[170:173], v[186:189], v[52:55]
	v_mfma_f32_16x16x32_bf16 v[44:47], v[178:181], v[186:189], v[44:47]
	v_mfma_f32_16x16x32_bf16 v[36:39], v[170:173], v[194:197], v[36:39]
	v_mfma_f32_16x16x32_bf16 v[28:31], v[178:181], v[194:197], v[28:31]
	v_mfma_f32_16x16x32_bf16 v[20:23], v[170:173], v[202:205], v[20:23]
	v_mfma_f32_16x16x32_bf16 v[12:15], v[178:181], v[202:205], v[12:15]
	v_mfma_f32_16x16x32_bf16 v[4:7], v[170:173], v[210:213], v[4:7]
	v_mfma_f32_16x16x32_bf16 v[0:3], v[178:181], v[210:213], v[0:3]
	s_setprio 0
	s_barrier
	s_add_i32 s48, 0, 0x18000
	s_add_i32 s49, 0, 0x1c000
	v_add_u32_e32 v162, s48, v153
	v_add_u32_e32 v178, s49, v153
	ds_read_b128 v[144:147], v162
	ds_read_b128 v[148:151], v162 offset:1024
	ds_read_b128 v[158:161], v162 offset:2048
	ds_read_b128 v[162:165], v162 offset:3072
	ds_read_b128 v[166:169], v178
	ds_read_b128 v[170:173], v178 offset:1024
	ds_read_b128 v[174:177], v178 offset:2048
	ds_read_b128 v[178:181], v178 offset:3072
	s_add_u32 s26, s26, 0x4000
	s_addc_u32 s27, s27, 0
	s_mov_b32 m0, s34
	v_lshl_add_u64 v[218:219], s[26:27], 0, v[128:129]
	ds_read_b128 v[182:185], v157 offset:32768
	ds_read_b128 v[186:189], v157 offset:33792
	ds_read_b128 v[190:193], v157 offset:34816
	ds_read_b128 v[194:197], v157 offset:35840
	ds_read_b128 v[198:201], v157 offset:36864
	ds_read_b128 v[202:205], v157 offset:37888
	ds_read_b128 v[206:209], v157 offset:38912
	ds_read_b128 v[210:213], v157 offset:39936
	global_load_lds_dwordx4 v[218:219], off
	v_lshl_add_u64 v[218:219], s[26:27], 0, v[132:133]
	s_mov_b32 m0, s35
	s_nop 0
	global_load_lds_dwordx4 v[218:219], off
	s_waitcnt vmcnt(8)
	s_waitcnt lgkmcnt(0)
	s_barrier
	s_setprio 1
	s_waitcnt lgkmcnt(0)
	v_mfma_f32_16x16x32_bf16 v[124:127], v[144:147], v[182:185], v[124:127]
	v_mfma_f32_16x16x32_bf16 v[120:123], v[158:161], v[182:185], v[120:123]
	v_mfma_f32_16x16x32_bf16 v[108:111], v[144:147], v[190:193], v[108:111]
	v_mfma_f32_16x16x32_bf16 v[104:107], v[158:161], v[190:193], v[104:107]
	v_mfma_f32_16x16x32_bf16 v[96:99], v[144:147], v[198:201], v[96:99]
	v_mfma_f32_16x16x32_bf16 v[88:91], v[158:161], v[198:201], v[88:91]
	v_mfma_f32_16x16x32_bf16 v[80:83], v[144:147], v[206:209], v[80:83]
	v_mfma_f32_16x16x32_bf16 v[72:75], v[158:161], v[206:209], v[72:75]
	v_mfma_f32_16x16x32_bf16 v[124:127], v[148:151], v[186:189], v[124:127]
	v_mfma_f32_16x16x32_bf16 v[120:123], v[162:165], v[186:189], v[120:123]
	v_mfma_f32_16x16x32_bf16 v[108:111], v[148:151], v[194:197], v[108:111]
	v_mfma_f32_16x16x32_bf16 v[104:107], v[162:165], v[194:197], v[104:107]
	v_mfma_f32_16x16x32_bf16 v[96:99], v[148:151], v[202:205], v[96:99]
	v_mfma_f32_16x16x32_bf16 v[88:91], v[162:165], v[202:205], v[88:91]
	v_mfma_f32_16x16x32_bf16 v[80:83], v[148:151], v[210:213], v[80:83]
	v_mfma_f32_16x16x32_bf16 v[72:75], v[162:165], v[210:213], v[72:75]
	v_mfma_f32_16x16x32_bf16 v[116:119], v[166:169], v[182:185], v[116:119]
	v_mfma_f32_16x16x32_bf16 v[112:115], v[174:177], v[182:185], v[112:115]
	v_mfma_f32_16x16x32_bf16 v[100:103], v[166:169], v[190:193], v[100:103]
	v_mfma_f32_16x16x32_bf16 v[92:95], v[174:177], v[190:193], v[92:95]
	v_mfma_f32_16x16x32_bf16 v[84:87], v[166:169], v[198:201], v[84:87]
	v_mfma_f32_16x16x32_bf16 v[76:79], v[174:177], v[198:201], v[76:79]
	v_mfma_f32_16x16x32_bf16 v[68:71], v[166:169], v[206:209], v[68:71]
	v_mfma_f32_16x16x32_bf16 v[64:67], v[174:177], v[206:209], v[64:67]
	v_mfma_f32_16x16x32_bf16 v[116:119], v[170:173], v[186:189], v[116:119]
	v_mfma_f32_16x16x32_bf16 v[112:115], v[178:181], v[186:189], v[112:115]
	v_mfma_f32_16x16x32_bf16 v[100:103], v[170:173], v[194:197], v[100:103]
	v_mfma_f32_16x16x32_bf16 v[92:95], v[178:181], v[194:197], v[92:95]
	v_mfma_f32_16x16x32_bf16 v[84:87], v[170:173], v[202:205], v[84:87]
	v_mfma_f32_16x16x32_bf16 v[76:79], v[178:181], v[202:205], v[76:79]
	v_mfma_f32_16x16x32_bf16 v[68:71], v[170:173], v[210:213], v[68:71]
	v_mfma_f32_16x16x32_bf16 v[64:67], v[178:181], v[210:213], v[64:67]
	s_setprio 0
	s_barrier
; #define PG8_STAGE(bufoff, gbase, voff) do { _Pragma("unroll") for (int _i = 0; _i < 2; ++_i) \
;         __builtin_amdgcn_global_load_lds((const unsigned*)((const char*)(gbase) + (voff)[_i]), (PG8_LAS unsigned*)(lds + (bufoff) + ldsw + _i * 8192), 16, 0, 0); } while (0)
; #define PG8_LDA(dst, b, h) do { _Pragma("unroll") for (int m = 0; m < 4; ++m) _Pragma("unroll") for (int k = 0; k < 2; ++k) dst[m][k] = *(const PG8_LAS bf16x8*)(lds + PG8_SA(b, h) + aoff + m * 2048 + k * 1024); } while (0)
; #define PG8_MMA(ai, bj, At, Bt) do { __builtin_amdgcn_s_setprio(1); _Pragma("unroll") for (int m = 0; m < 4; ++m) _Pragma("unroll") for (int n = 0; n < 2; ++n) _Pragma("unroll") for (int k = 0; k < 2; ++k) \
;         acc[ai][bj][m][n] = __builtin_amdgcn_mfma_f32_16x16x32_bf16(Bt[n][k], At[m][k], acc[ai][bj][m][n], 0, 0, 0); __builtin_amdgcn_s_setprio(0); } while (0)
; #define PG8_WAIT_V(n) asm volatile("s_waitcnt vmcnt(" #n ")" ::: "memory")
; #define PG8_WAIT_L(n) asm volatile("s_waitcnt lgkmcnt(" #n ")" ::: "memory")
; #define PG8_BAR __builtin_amdgcn_s_barrier()
; #define PG8_SCHED __builtin_amdgcn_sched_barrier(0)
; template <class Epi, class Sched, bool ALIGN_EPI = false, bool SP2 = false>
; __device__ __forceinline__ void gemm_phase(PG8_LAS unsigned char* lds, const Gemm g, const Sched& S, const Epi& E) {
;     ...
;             PG8_LDA(At, 1, 1); PG8_STAGE(PG8_SB(1, 0), b3, voffB); PG8_STAGE(PG8_SB(1, 1), b3 + hstep, voffB); PG8_STAGE(PG8_SA(1, 0), a3, voffA);
;             PG8_WAIT_V(8); PG8_WAIT_L(0); PG8_BAR; PG8_MMA(1, 0, At, B0); PG8_MMA(1, 1, At, B1); PG8_BAR; PG8_SCHED;
	s_add_i32 s26, s48, s29
	v_lshl_add_u64 v[214:215], v[214:215], 0, s[10:11]
	s_mov_b32 m0, s26
	ds_read_b128 v[182:185], v157 offset:49152
	ds_read_b128 v[186:189], v157 offset:50176
	ds_read_b128 v[190:193], v157 offset:51200
	ds_read_b128 v[194:197], v157 offset:52224
	ds_read_b128 v[198:201], v157 offset:53248
	ds_read_b128 v[202:205], v157 offset:54272
	ds_read_b128 v[206:209], v157 offset:55296
	ds_read_b128 v[210:213], v157 offset:56320
	global_load_lds_dwordx4 v[214:215], off
	s_add_i32 m0, s26, 0x2000
	s_add_u32 s24, s24, 0xb0080
	v_lshl_add_u64 v[214:215], v[216:217], 0, s[10:11]
	s_addc_u32 s25, s25, 0
	s_add_i32 s26, s49, s29
	global_load_lds_dwordx4 v[214:215], off
	v_lshl_add_u64 v[214:215], s[24:25], 0, v[130:131]
	s_mov_b32 m0, s26
	s_nop 0
	global_load_lds_dwordx4 v[214:215], off
	v_lshl_add_u64 v[214:215], s[24:25], 0, v[134:135]
	s_add_i32 m0, s26, 0x2000
	s_nop 0
	global_load_lds_dwordx4 v[214:215], off
	v_lshl_add_u64 v[214:215], s[22:23], 0, v[128:129]
	s_mov_b32 m0, s37
	s_nop 0
	global_load_lds_dwordx4 v[214:215], off
	v_lshl_add_u64 v[214:215], s[22:23], 0, v[132:133]
	s_mov_b32 m0, s38
	s_nop 0
	global_load_lds_dwordx4 v[214:215], off
	s_waitcnt vmcnt(8)
	s_waitcnt lgkmcnt(0)
	s_barrier
	s_setprio 1
	s_waitcnt lgkmcnt(0)
	v_mfma_f32_16x16x32_bf16 v[60:63], v[144:147], v[182:185], v[60:63]
	v_mfma_f32_16x16x32_bf16 v[56:59], v[158:161], v[182:185], v[56:59]
	v_mfma_f32_16x16x32_bf16 v[48:51], v[144:147], v[190:193], v[48:51]
	v_mfma_f32_16x16x32_bf16 v[40:43], v[158:161], v[190:193], v[40:43]
	v_mfma_f32_16x16x32_bf16 v[32:35], v[144:147], v[198:201], v[32:35]
	v_mfma_f32_16x16x32_bf16 v[24:27], v[158:161], v[198:201], v[24:27]
	v_mfma_f32_16x16x32_bf16 v[16:19], v[144:147], v[206:209], v[16:19]
	v_mfma_f32_16x16x32_bf16 v[8:11], v[158:161], v[206:209], v[8:11]
	v_mfma_f32_16x16x32_bf16 v[60:63], v[148:151], v[186:189], v[60:63]
	v_mfma_f32_16x16x32_bf16 v[56:59], v[162:165], v[186:189], v[56:59]
	v_mfma_f32_16x16x32_bf16 v[48:51], v[148:151], v[194:197], v[48:51]
	v_mfma_f32_16x16x32_bf16 v[40:43], v[162:165], v[194:197], v[40:43]
	v_mfma_f32_16x16x32_bf16 v[32:35], v[148:151], v[202:205], v[32:35]
	v_mfma_f32_16x16x32_bf16 v[24:27], v[162:165], v[202:205], v[24:27]
	v_mfma_f32_16x16x32_bf16 v[16:19], v[148:151], v[210:213], v[16:19]
	v_mfma_f32_16x16x32_bf16 v[8:11], v[162:165], v[210:213], v[8:11]
	v_mfma_f32_16x16x32_bf16 v[52:55], v[166:169], v[182:185], v[52:55]
	v_mfma_f32_16x16x32_bf16 v[44:47], v[174:177], v[182:185], v[44:47]
	v_mfma_f32_16x16x32_bf16 v[36:39], v[166:169], v[190:193], v[36:39]
	v_mfma_f32_16x16x32_bf16 v[28:31], v[174:177], v[190:193], v[28:31]
	v_mfma_f32_16x16x32_bf16 v[20:23], v[166:169], v[198:201], v[20:23]
	v_mfma_f32_16x16x32_bf16 v[12:15], v[174:177], v[198:201], v[12:15]
	v_mfma_f32_16x16x32_bf16 v[4:7], v[166:169], v[206:209], v[4:7]
	v_mfma_f32_16x16x32_bf16 v[0:3], v[174:177], v[206:209], v[0:3]
	v_mfma_f32_16x16x32_bf16 v[52:55], v[170:173], v[186:189], v[52:55]
	v_mfma_f32_16x16x32_bf16 v[44:47], v[178:181], v[186:189], v[44:47]
	v_mfma_f32_16x16x32_bf16 v[36:39], v[170:173], v[194:197], v[36:39]
	v_mfma_f32_16x16x32_bf16 v[28:31], v[178:181], v[194:197], v[28:31]
	v_mfma_f32_16x16x32_bf16 v[20:23], v[170:173], v[202:205], v[20:23]
	v_mfma_f32_16x16x32_bf16 v[12:15], v[178:181], v[202:205], v[12:15]
	v_mfma_f32_16x16x32_bf16 v[4:7], v[170:173], v[210:213], v[4:7]
	v_mfma_f32_16x16x32_bf16 v[0:3], v[178:181], v[210:213], v[0:3]
	s_setprio 0
	s_barrier
	s_add_i32 s47, s47, 2
	s_add_u32 s45, s45, 0x100
	s_addc_u32 s46, s46, 0
	s_add_u32 s2, s2, 0x420000
	s_addc_u32 s3, s3, 0
	s_cmp_gt_u32 s47, 41
	s_cbranch_scc0 .LBB0_1199
	s_and_b64 vcc, exec, s[12:13]
	s_cbranch_vccz .LBB0_1202
	s_barrier
